# inproj1 also with 256x128 pair tiles + hand-written hdn1 (fragment-major layout)
# speedup vs baseline: 1.0481x; 1.0136x over previous
.LBB0_370:
	s_or_b64 exec, exec, s[0:1]
	s_andn2_b64 vcc, exec, s[26:27]
	s_waitcnt lgkmcnt(0)
	s_barrier
	s_cbranch_vccnz .LBB0_375
	s_mov_b32 s4, s2
.Lmy_hdn1_loop:
	s_lshr_b32 s5, s4, 7
	s_mul_i32 s5, s5, 0x3000
	s_add_u32 s6, s50, s5
	s_addc_u32 s7, s51, 0
	s_add_u32 s6, s6, 0x1120000
	s_addc_u32 s7, s7, 0
	v_add_u32_e32 v210, 0x1000, v129
	s_barrier
	global_load_dwordx4 v[0:3], v129, s[6:7]
	global_load_dwordx4 v[32:35], v210, s[6:7]
	s_add_u32 s6, s6, 0xc000
	s_addc_u32 s7, s7, 0
	global_load_dwordx4 v[4:7], v129, s[6:7]
	global_load_dwordx4 v[36:39], v210, s[6:7]
	s_add_u32 s6, s6, 0xc000
	s_addc_u32 s7, s7, 0
	global_load_dwordx4 v[8:11], v129, s[6:7]
	global_load_dwordx4 v[40:43], v210, s[6:7]
	s_add_u32 s6, s6, 0xc000
	s_addc_u32 s7, s7, 0
	global_load_dwordx4 v[12:15], v129, s[6:7]
	global_load_dwordx4 v[44:47], v210, s[6:7]
	s_add_u32 s6, s6, 0xc000
	s_addc_u32 s7, s7, 0
	global_load_dwordx4 v[16:19], v129, s[6:7]
	global_load_dwordx4 v[48:51], v210, s[6:7]
	s_add_u32 s6, s6, 0xc000
	s_addc_u32 s7, s7, 0
	global_load_dwordx4 v[20:23], v129, s[6:7]
	global_load_dwordx4 v[52:55], v210, s[6:7]
	s_add_u32 s6, s6, 0xc000
	s_addc_u32 s7, s7, 0
	global_load_dwordx4 v[24:27], v129, s[6:7]
	global_load_dwordx4 v[56:59], v210, s[6:7]
	s_add_u32 s6, s6, 0xc000
	s_addc_u32 s7, s7, 0
	global_load_dwordx4 v[28:31], v129, s[6:7]
	global_load_dwordx4 v[60:63], v210, s[6:7]
	global_load_dwordx4 v[64:67], v129, s[62:63]
	v_and_b32_e32 v173, 63, v131
	v_lshrrev_b32_e32 v172, 6, v131
	v_lshlrev_b32_e32 v168, 4, v173
	v_lshl_add_u32 v168, v172, 15, v168
	v_lshrrev_b32_e32 v169, 3, v173
	v_lshlrev_b32_e32 v169, 10, v169
	v_bfe_u32 v170, v173, 1, 2
	v_lshl_or_b32 v169, v170, 8, v169
	v_and_b32_e32 v170, 1, v173
	v_lshl_or_b32 v169, v170, 3, v169
	v_lshrrev_b32_e32 v170, 1, v172
	v_lshl_or_b32 v169, v170, 15, v169
	v_and_b32_e32 v170, 1, v172
	v_lshl_or_b32 v169, v170, 7, v169
	v_add_u32_e32 v170, 0x2000, v169
	v_add_u32_e32 v171, 0x4000, v169
	v_add_u32_e32 v172, 0x6000, v169
	v_lshlrev_b32_e32 v173, 4, v173
	v_mov_b32_e32 v174, 0x3a800000
	s_lshl_b32 s5, s4, 17
	s_add_u32 s8, s48, s5
	s_addc_u32 s9, s49, 0
	s_lshl_b32 s5, s4, 16
	s_add_u32 s10, s50, s5
	s_addc_u32 s11, s51, 0
	s_add_u32 s10, s10, 0x3a00000
	s_addc_u32 s11, s11, 0
	s_waitcnt vmcnt(0)
	v_add_f32_e32 v0, v0, v4
	v_add_f32_e32 v0, v0, v8
	v_add_f32_e32 v0, v0, v12
	v_add_f32_e32 v0, v0, v16
	v_add_f32_e32 v0, v0, v20
	v_add_f32_e32 v0, v0, v24
	v_add_f32_e32 v0, v0, v28
	v_add_f32_e32 v1, v1, v5
	v_add_f32_e32 v1, v1, v9
	v_add_f32_e32 v1, v1, v13
	v_add_f32_e32 v1, v1, v17
	v_add_f32_e32 v1, v1, v21
	v_add_f32_e32 v1, v1, v25
	v_add_f32_e32 v1, v1, v29
	v_add_f32_e32 v2, v2, v6
	v_add_f32_e32 v2, v2, v10
	v_add_f32_e32 v2, v2, v14
	v_add_f32_e32 v2, v2, v18
	v_add_f32_e32 v2, v2, v22
	v_add_f32_e32 v2, v2, v26
	v_add_f32_e32 v2, v2, v30
	v_add_f32_e32 v3, v3, v7
	v_add_f32_e32 v3, v3, v11
	v_add_f32_e32 v3, v3, v15
	v_add_f32_e32 v3, v3, v19
	v_add_f32_e32 v3, v3, v23
	v_add_f32_e32 v3, v3, v27
	v_add_f32_e32 v3, v3, v31
	v_add_f32_e32 v32, v32, v36
	v_add_f32_e32 v32, v32, v40
	v_add_f32_e32 v32, v32, v44
	v_add_f32_e32 v32, v32, v48
	v_add_f32_e32 v32, v32, v52
	v_add_f32_e32 v32, v32, v56
	v_add_f32_e32 v32, v32, v60
	v_add_f32_e32 v33, v33, v37
	v_add_f32_e32 v33, v33, v41
	v_add_f32_e32 v33, v33, v45
	v_add_f32_e32 v33, v33, v49
	v_add_f32_e32 v33, v33, v53
	v_add_f32_e32 v33, v33, v57
	v_add_f32_e32 v33, v33, v61
	v_add_f32_e32 v34, v34, v38
	v_add_f32_e32 v34, v34, v42
	v_add_f32_e32 v34, v34, v46
	v_add_f32_e32 v34, v34, v50
	v_add_f32_e32 v34, v34, v54
	v_add_f32_e32 v34, v34, v58
	v_add_f32_e32 v34, v34, v62
	v_add_f32_e32 v35, v35, v39
	v_add_f32_e32 v35, v35, v43
	v_add_f32_e32 v35, v35, v47
	v_add_f32_e32 v35, v35, v51
	v_add_f32_e32 v35, v35, v55
	v_add_f32_e32 v35, v35, v59
	v_add_f32_e32 v35, v35, v63
	v_add_f32_e32 v32, 1.0, v32
	v_add_f32_e32 v33, 1.0, v33
	v_add_f32_e32 v34, 1.0, v34
	v_add_f32_e32 v35, 1.0, v35
	v_mul_f32_e32 v200, v64, v32
	v_mul_f32_e32 v201, v65, v33
	v_mul_f32_e32 v202, v66, v34
	v_mul_f32_e32 v203, v67, v35
	v_mov_b32_e32 v204, v0
	v_mov_b32_e32 v205, v1
	v_mov_b32_e32 v206, v2
	v_mov_b32_e32 v207, v3
	ds_write_b128 v129, v[200:203]
	ds_write_b128 v129, v[204:207] offset:4096
	global_load_dwordx4 v[0:3], v168, s[8:9] offset:0 nt
	global_load_dwordx4 v[4:7], v168, s[8:9] offset:1024 nt
	global_load_dwordx4 v[8:11], v168, s[8:9] offset:2048 nt
	global_load_dwordx4 v[12:15], v168, s[8:9] offset:3072 nt
	s_add_u32 s8, s8, 0x1000
	s_addc_u32 s9, s9, 0
	global_load_dwordx4 v[16:19], v168, s[8:9] offset:0 nt
	global_load_dwordx4 v[20:23], v168, s[8:9] offset:1024 nt
	global_load_dwordx4 v[24:27], v168, s[8:9] offset:2048 nt
	global_load_dwordx4 v[28:31], v168, s[8:9] offset:3072 nt
	s_add_u32 s8, s8, 0x1000
	s_addc_u32 s9, s9, 0
	global_load_dwordx4 v[32:35], v168, s[8:9] offset:0 nt
	global_load_dwordx4 v[36:39], v168, s[8:9] offset:1024 nt
	global_load_dwordx4 v[40:43], v168, s[8:9] offset:2048 nt
	global_load_dwordx4 v[44:47], v168, s[8:9] offset:3072 nt
	s_add_u32 s8, s8, 0x1000
	s_addc_u32 s9, s9, 0
	global_load_dwordx4 v[48:51], v168, s[8:9] offset:0 nt
	global_load_dwordx4 v[52:55], v168, s[8:9] offset:1024 nt
	global_load_dwordx4 v[56:59], v168, s[8:9] offset:2048 nt
	global_load_dwordx4 v[60:63], v168, s[8:9] offset:3072 nt
	s_add_u32 s8, s8, 0x1000
	s_addc_u32 s9, s9, 0
	global_load_dwordx4 v[64:67], v168, s[8:9] offset:0 nt
	global_load_dwordx4 v[68:71], v168, s[8:9] offset:1024 nt
	global_load_dwordx4 v[72:75], v168, s[8:9] offset:2048 nt
	global_load_dwordx4 v[76:79], v168, s[8:9] offset:3072 nt
	s_add_u32 s8, s8, 0x1000
	s_addc_u32 s9, s9, 0
	global_load_dwordx4 v[80:83], v168, s[8:9] offset:0 nt
	global_load_dwordx4 v[84:87], v168, s[8:9] offset:1024 nt
	global_load_dwordx4 v[88:91], v168, s[8:9] offset:2048 nt
	global_load_dwordx4 v[92:95], v168, s[8:9] offset:3072 nt
	s_add_u32 s8, s8, 0x1000
	s_addc_u32 s9, s9, 0
	global_load_dwordx4 v[96:99], v168, s[8:9] offset:0 nt
	global_load_dwordx4 v[100:103], v168, s[8:9] offset:1024 nt
	global_load_dwordx4 v[104:107], v168, s[8:9] offset:2048 nt
	global_load_dwordx4 v[108:111], v168, s[8:9] offset:3072 nt
	s_add_u32 s8, s8, 0x1000
	s_addc_u32 s9, s9, 0
	global_load_dwordx4 v[112:115], v168, s[8:9] offset:0 nt
	global_load_dwordx4 v[116:119], v168, s[8:9] offset:1024 nt
	global_load_dwordx4 v[120:123], v168, s[8:9] offset:2048 nt
	global_load_dwordx4 v[124:127], v168, s[8:9] offset:3072 nt
	s_waitcnt lgkmcnt(0)
	s_barrier
	ds_read_b128 v[178:181], v173 offset:0
	ds_read_b128 v[194:197], v173 offset:4096
	ds_read_b128 v[182:185], v173 offset:1024
	ds_read_b128 v[198:201], v173 offset:5120
	ds_read_b128 v[186:189], v173 offset:2048
	ds_read_b128 v[202:205], v173 offset:6144
	ds_read_b128 v[190:193], v173 offset:3072
	ds_read_b128 v[206:209], v173 offset:7168
	s_waitcnt vmcnt(28)
	v_mul_f32_e32 v160, v0, v0
	v_fmac_f32_e32 v160, v1, v1
	v_fmac_f32_e32 v160, v2, v2
	v_fmac_f32_e32 v160, v3, v3
	v_fmac_f32_e32 v160, v4, v4
	v_fmac_f32_e32 v160, v5, v5
	v_fmac_f32_e32 v160, v6, v6
	v_fmac_f32_e32 v160, v7, v7
	v_fmac_f32_e32 v160, v8, v8
	v_fmac_f32_e32 v160, v9, v9
	v_fmac_f32_e32 v160, v10, v10
	v_fmac_f32_e32 v160, v11, v11
	v_fmac_f32_e32 v160, v12, v12
	v_fmac_f32_e32 v160, v13, v13
	v_fmac_f32_e32 v160, v14, v14
	v_fmac_f32_e32 v160, v15, v15
	s_waitcnt vmcnt(24)
	v_mul_f32_e32 v161, v16, v16
	v_fmac_f32_e32 v161, v17, v17
	v_fmac_f32_e32 v161, v18, v18
	v_fmac_f32_e32 v161, v19, v19
	v_fmac_f32_e32 v161, v20, v20
	v_fmac_f32_e32 v161, v21, v21
	v_fmac_f32_e32 v161, v22, v22
	v_fmac_f32_e32 v161, v23, v23
	v_fmac_f32_e32 v161, v24, v24
	v_fmac_f32_e32 v161, v25, v25
	v_fmac_f32_e32 v161, v26, v26
	v_fmac_f32_e32 v161, v27, v27
	v_fmac_f32_e32 v161, v28, v28
	v_fmac_f32_e32 v161, v29, v29
	v_fmac_f32_e32 v161, v30, v30
	v_fmac_f32_e32 v161, v31, v31
	s_waitcnt vmcnt(20)
	v_mul_f32_e32 v162, v32, v32
	v_fmac_f32_e32 v162, v33, v33
	v_fmac_f32_e32 v162, v34, v34
	v_fmac_f32_e32 v162, v35, v35
	v_fmac_f32_e32 v162, v36, v36
	v_fmac_f32_e32 v162, v37, v37
	v_fmac_f32_e32 v162, v38, v38
	v_fmac_f32_e32 v162, v39, v39
	v_fmac_f32_e32 v162, v40, v40
	v_fmac_f32_e32 v162, v41, v41
	v_fmac_f32_e32 v162, v42, v42
	v_fmac_f32_e32 v162, v43, v43
	v_fmac_f32_e32 v162, v44, v44
	v_fmac_f32_e32 v162, v45, v45
	v_fmac_f32_e32 v162, v46, v46
	v_fmac_f32_e32 v162, v47, v47
	s_waitcnt vmcnt(16)
	v_mul_f32_e32 v163, v48, v48
	v_fmac_f32_e32 v163, v49, v49
	v_fmac_f32_e32 v163, v50, v50
	v_fmac_f32_e32 v163, v51, v51
	v_fmac_f32_e32 v163, v52, v52
	v_fmac_f32_e32 v163, v53, v53
	v_fmac_f32_e32 v163, v54, v54
	v_fmac_f32_e32 v163, v55, v55
	v_fmac_f32_e32 v163, v56, v56
	v_fmac_f32_e32 v163, v57, v57
	v_fmac_f32_e32 v163, v58, v58
	v_fmac_f32_e32 v163, v59, v59
	v_fmac_f32_e32 v163, v60, v60
	v_fmac_f32_e32 v163, v61, v61
	v_fmac_f32_e32 v163, v62, v62
	v_fmac_f32_e32 v163, v63, v63
	s_waitcnt vmcnt(12)
	v_mul_f32_e32 v164, v64, v64
	v_fmac_f32_e32 v164, v65, v65
	v_fmac_f32_e32 v164, v66, v66
	v_fmac_f32_e32 v164, v67, v67
	v_fmac_f32_e32 v164, v68, v68
	v_fmac_f32_e32 v164, v69, v69
	v_fmac_f32_e32 v164, v70, v70
	v_fmac_f32_e32 v164, v71, v71
	v_fmac_f32_e32 v164, v72, v72
	v_fmac_f32_e32 v164, v73, v73
	v_fmac_f32_e32 v164, v74, v74
	v_fmac_f32_e32 v164, v75, v75
	v_fmac_f32_e32 v164, v76, v76
	v_fmac_f32_e32 v164, v77, v77
	v_fmac_f32_e32 v164, v78, v78
	v_fmac_f32_e32 v164, v79, v79
	s_waitcnt vmcnt(8)
	v_mul_f32_e32 v165, v80, v80
	v_fmac_f32_e32 v165, v81, v81
	v_fmac_f32_e32 v165, v82, v82
	v_fmac_f32_e32 v165, v83, v83
	v_fmac_f32_e32 v165, v84, v84
	v_fmac_f32_e32 v165, v85, v85
	v_fmac_f32_e32 v165, v86, v86
	v_fmac_f32_e32 v165, v87, v87
	v_fmac_f32_e32 v165, v88, v88
	v_fmac_f32_e32 v165, v89, v89
	v_fmac_f32_e32 v165, v90, v90
	v_fmac_f32_e32 v165, v91, v91
	v_fmac_f32_e32 v165, v92, v92
	v_fmac_f32_e32 v165, v93, v93
	v_fmac_f32_e32 v165, v94, v94
	v_fmac_f32_e32 v165, v95, v95
	s_waitcnt vmcnt(4)
	v_mul_f32_e32 v166, v96, v96
	v_fmac_f32_e32 v166, v97, v97
	v_fmac_f32_e32 v166, v98, v98
	v_fmac_f32_e32 v166, v99, v99
	v_fmac_f32_e32 v166, v100, v100
	v_fmac_f32_e32 v166, v101, v101
	v_fmac_f32_e32 v166, v102, v102
	v_fmac_f32_e32 v166, v103, v103
	v_fmac_f32_e32 v166, v104, v104
	v_fmac_f32_e32 v166, v105, v105
	v_fmac_f32_e32 v166, v106, v106
	v_fmac_f32_e32 v166, v107, v107
	v_fmac_f32_e32 v166, v108, v108
	v_fmac_f32_e32 v166, v109, v109
	v_fmac_f32_e32 v166, v110, v110
	v_fmac_f32_e32 v166, v111, v111
	s_waitcnt vmcnt(0)
	v_mul_f32_e32 v167, v112, v112
	v_fmac_f32_e32 v167, v113, v113
	v_fmac_f32_e32 v167, v114, v114
	v_fmac_f32_e32 v167, v115, v115
	v_fmac_f32_e32 v167, v116, v116
	v_fmac_f32_e32 v167, v117, v117
	v_fmac_f32_e32 v167, v118, v118
	v_fmac_f32_e32 v167, v119, v119
	v_fmac_f32_e32 v167, v120, v120
	v_fmac_f32_e32 v167, v121, v121
	v_fmac_f32_e32 v167, v122, v122
	v_fmac_f32_e32 v167, v123, v123
	v_fmac_f32_e32 v167, v124, v124
	v_fmac_f32_e32 v167, v125, v125
	v_fmac_f32_e32 v167, v126, v126
	v_fmac_f32_e32 v167, v127, v127
	v_add_f32_dpp v160, v160, v160 quad_perm:[1,0,3,2] row_mask:0xf bank_mask:0xf
	v_add_f32_dpp v161, v161, v161 quad_perm:[1,0,3,2] row_mask:0xf bank_mask:0xf
	v_add_f32_dpp v162, v162, v162 quad_perm:[1,0,3,2] row_mask:0xf bank_mask:0xf
	v_add_f32_dpp v163, v163, v163 quad_perm:[1,0,3,2] row_mask:0xf bank_mask:0xf
	v_add_f32_dpp v164, v164, v164 quad_perm:[1,0,3,2] row_mask:0xf bank_mask:0xf
	v_add_f32_dpp v165, v165, v165 quad_perm:[1,0,3,2] row_mask:0xf bank_mask:0xf
	v_add_f32_dpp v166, v166, v166 quad_perm:[1,0,3,2] row_mask:0xf bank_mask:0xf
	v_add_f32_dpp v167, v167, v167 quad_perm:[1,0,3,2] row_mask:0xf bank_mask:0xf
	v_add_f32_dpp v160, v160, v160 quad_perm:[2,3,0,1] row_mask:0xf bank_mask:0xf
	v_add_f32_dpp v161, v161, v161 quad_perm:[2,3,0,1] row_mask:0xf bank_mask:0xf
	v_add_f32_dpp v162, v162, v162 quad_perm:[2,3,0,1] row_mask:0xf bank_mask:0xf
	v_add_f32_dpp v163, v163, v163 quad_perm:[2,3,0,1] row_mask:0xf bank_mask:0xf
	v_add_f32_dpp v164, v164, v164 quad_perm:[2,3,0,1] row_mask:0xf bank_mask:0xf
	v_add_f32_dpp v165, v165, v165 quad_perm:[2,3,0,1] row_mask:0xf bank_mask:0xf
	v_add_f32_dpp v166, v166, v166 quad_perm:[2,3,0,1] row_mask:0xf bank_mask:0xf
	v_add_f32_dpp v167, v167, v167 quad_perm:[2,3,0,1] row_mask:0xf bank_mask:0xf
	v_add_f32_dpp v160, v160, v160 row_half_mirror row_mask:0xf bank_mask:0xf
	v_add_f32_dpp v161, v161, v161 row_half_mirror row_mask:0xf bank_mask:0xf
	v_add_f32_dpp v162, v162, v162 row_half_mirror row_mask:0xf bank_mask:0xf
	v_add_f32_dpp v163, v163, v163 row_half_mirror row_mask:0xf bank_mask:0xf
	v_add_f32_dpp v164, v164, v164 row_half_mirror row_mask:0xf bank_mask:0xf
	v_add_f32_dpp v165, v165, v165 row_half_mirror row_mask:0xf bank_mask:0xf
	v_add_f32_dpp v166, v166, v166 row_half_mirror row_mask:0xf bank_mask:0xf
	v_add_f32_dpp v167, v167, v167 row_half_mirror row_mask:0xf bank_mask:0xf
	v_add_f32_dpp v160, v160, v160 row_mirror row_mask:0xf bank_mask:0xf
	v_add_f32_dpp v161, v161, v161 row_mirror row_mask:0xf bank_mask:0xf
	v_add_f32_dpp v162, v162, v162 row_mirror row_mask:0xf bank_mask:0xf
	v_add_f32_dpp v163, v163, v163 row_mirror row_mask:0xf bank_mask:0xf
	v_add_f32_dpp v164, v164, v164 row_mirror row_mask:0xf bank_mask:0xf
	v_add_f32_dpp v165, v165, v165 row_mirror row_mask:0xf bank_mask:0xf
	v_add_f32_dpp v166, v166, v166 row_mirror row_mask:0xf bank_mask:0xf
	v_add_f32_dpp v167, v167, v167 row_mirror row_mask:0xf bank_mask:0xf
	v_add_f32_dpp v160, v160, v160 row_bcast:15 row_mask:0xa bank_mask:0xf
	v_add_f32_dpp v161, v161, v161 row_bcast:15 row_mask:0xa bank_mask:0xf
	v_add_f32_dpp v162, v162, v162 row_bcast:15 row_mask:0xa bank_mask:0xf
	v_add_f32_dpp v163, v163, v163 row_bcast:15 row_mask:0xa bank_mask:0xf
	v_add_f32_dpp v164, v164, v164 row_bcast:15 row_mask:0xa bank_mask:0xf
	v_add_f32_dpp v165, v165, v165 row_bcast:15 row_mask:0xa bank_mask:0xf
	v_add_f32_dpp v166, v166, v166 row_bcast:15 row_mask:0xa bank_mask:0xf
	v_add_f32_dpp v167, v167, v167 row_bcast:15 row_mask:0xa bank_mask:0xf
	v_add_f32_dpp v160, v160, v160 row_bcast:31 row_mask:0xc bank_mask:0xf
	v_add_f32_dpp v161, v161, v161 row_bcast:31 row_mask:0xc bank_mask:0xf
	v_add_f32_dpp v162, v162, v162 row_bcast:31 row_mask:0xc bank_mask:0xf
	v_add_f32_dpp v163, v163, v163 row_bcast:31 row_mask:0xc bank_mask:0xf
	v_add_f32_dpp v164, v164, v164 row_bcast:31 row_mask:0xc bank_mask:0xf
	v_add_f32_dpp v165, v165, v165 row_bcast:31 row_mask:0xc bank_mask:0xf
	v_add_f32_dpp v166, v166, v166 row_bcast:31 row_mask:0xc bank_mask:0xf
	v_add_f32_dpp v167, v167, v167 row_bcast:31 row_mask:0xc bank_mask:0xf
	v_fmaak_f32 v160, v160, v174, 0x358637bd
	v_fmaak_f32 v161, v161, v174, 0x358637bd
	v_fmaak_f32 v162, v162, v174, 0x358637bd
	v_fmaak_f32 v163, v163, v174, 0x358637bd
	v_fmaak_f32 v164, v164, v174, 0x358637bd
	v_fmaak_f32 v165, v165, v174, 0x358637bd
	v_fmaak_f32 v166, v166, v174, 0x358637bd
	v_fmaak_f32 v167, v167, v174, 0x358637bd
	v_rsq_f32_e32 v160, v160
	v_rsq_f32_e32 v161, v161
	v_rsq_f32_e32 v162, v162
	v_rsq_f32_e32 v163, v163
	v_rsq_f32_e32 v164, v164
	v_rsq_f32_e32 v165, v165
	v_rsq_f32_e32 v166, v166
	v_rsq_f32_e32 v167, v167
	v_readlane_b32 s84, v160, 63
	v_readlane_b32 s85, v161, 63
	v_readlane_b32 s86, v162, 63
	v_readlane_b32 s87, v163, 63
	v_readlane_b32 s88, v164, 63
	v_readlane_b32 s89, v165, 63
	v_readlane_b32 s90, v166, 63
	v_readlane_b32 s91, v167, 63
	s_waitcnt lgkmcnt(0)
	v_mul_f32_e32 v0, s84, v0
	v_mul_f32_e32 v1, s84, v1
	v_mul_f32_e32 v2, s84, v2
	v_mul_f32_e32 v3, s84, v3
	v_fma_f32 v0, v0, v178, v194
	v_fma_f32 v1, v1, v179, v195
	v_fma_f32 v2, v2, v180, v196
	v_fma_f32 v3, v3, v181, v197
	v_cvt_pk_bf16_f32 v0, v0, v1
	v_cvt_pk_bf16_f32 v1, v2, v3
	global_store_dwordx2 v169, v[0:1], s[10:11] offset:0
	v_mul_f32_e32 v4, s84, v4
	v_mul_f32_e32 v5, s84, v5
	v_mul_f32_e32 v6, s84, v6
	v_mul_f32_e32 v7, s84, v7
	v_fma_f32 v4, v4, v182, v198
	v_fma_f32 v5, v5, v183, v199
	v_fma_f32 v6, v6, v184, v200
	v_fma_f32 v7, v7, v185, v201
	v_cvt_pk_bf16_f32 v4, v4, v5
	v_cvt_pk_bf16_f32 v5, v6, v7
	global_store_dwordx2 v170, v[4:5], s[10:11] offset:0
	v_mul_f32_e32 v8, s84, v8
	v_mul_f32_e32 v9, s84, v9
	v_mul_f32_e32 v10, s84, v10
	v_mul_f32_e32 v11, s84, v11
	v_fma_f32 v8, v8, v186, v202
	v_fma_f32 v9, v9, v187, v203
	v_fma_f32 v10, v10, v188, v204
	v_fma_f32 v11, v11, v189, v205
	v_cvt_pk_bf16_f32 v8, v8, v9
	v_cvt_pk_bf16_f32 v9, v10, v11
	global_store_dwordx2 v171, v[8:9], s[10:11] offset:0
	v_mul_f32_e32 v12, s84, v12
	v_mul_f32_e32 v13, s84, v13
	v_mul_f32_e32 v14, s84, v14
	v_mul_f32_e32 v15, s84, v15
	v_fma_f32 v12, v12, v190, v206
	v_fma_f32 v13, v13, v191, v207
	v_fma_f32 v14, v14, v192, v208
	v_fma_f32 v15, v15, v193, v209
	v_cvt_pk_bf16_f32 v12, v12, v13
	v_cvt_pk_bf16_f32 v13, v14, v15
	global_store_dwordx2 v172, v[12:13], s[10:11] offset:0
	v_mul_f32_e32 v16, s85, v16
	v_mul_f32_e32 v17, s85, v17
	v_mul_f32_e32 v18, s85, v18
	v_mul_f32_e32 v19, s85, v19
	v_fma_f32 v16, v16, v178, v194
	v_fma_f32 v17, v17, v179, v195
	v_fma_f32 v18, v18, v180, v196
	v_fma_f32 v19, v19, v181, v197
	v_cvt_pk_bf16_f32 v16, v16, v17
	v_cvt_pk_bf16_f32 v17, v18, v19
	global_store_dwordx2 v169, v[16:17], s[10:11] offset:16
	v_mul_f32_e32 v20, s85, v20
	v_mul_f32_e32 v21, s85, v21
	v_mul_f32_e32 v22, s85, v22
	v_mul_f32_e32 v23, s85, v23
	v_fma_f32 v20, v20, v182, v198
	v_fma_f32 v21, v21, v183, v199
	v_fma_f32 v22, v22, v184, v200
	v_fma_f32 v23, v23, v185, v201
	v_cvt_pk_bf16_f32 v20, v20, v21
	v_cvt_pk_bf16_f32 v21, v22, v23
	global_store_dwordx2 v170, v[20:21], s[10:11] offset:16
	v_mul_f32_e32 v24, s85, v24
	v_mul_f32_e32 v25, s85, v25
	v_mul_f32_e32 v26, s85, v26
	v_mul_f32_e32 v27, s85, v27
	v_fma_f32 v24, v24, v186, v202
	v_fma_f32 v25, v25, v187, v203
	v_fma_f32 v26, v26, v188, v204
	v_fma_f32 v27, v27, v189, v205
	v_cvt_pk_bf16_f32 v24, v24, v25
	v_cvt_pk_bf16_f32 v25, v26, v27
	global_store_dwordx2 v171, v[24:25], s[10:11] offset:16
	v_mul_f32_e32 v28, s85, v28
	v_mul_f32_e32 v29, s85, v29
	v_mul_f32_e32 v30, s85, v30
	v_mul_f32_e32 v31, s85, v31
	v_fma_f32 v28, v28, v190, v206
	v_fma_f32 v29, v29, v191, v207
	v_fma_f32 v30, v30, v192, v208
	v_fma_f32 v31, v31, v193, v209
	v_cvt_pk_bf16_f32 v28, v28, v29
	v_cvt_pk_bf16_f32 v29, v30, v31
	global_store_dwordx2 v172, v[28:29], s[10:11] offset:16
	v_mul_f32_e32 v32, s86, v32
	v_mul_f32_e32 v33, s86, v33
	v_mul_f32_e32 v34, s86, v34
	v_mul_f32_e32 v35, s86, v35
	v_fma_f32 v32, v32, v178, v194
	v_fma_f32 v33, v33, v179, v195
	v_fma_f32 v34, v34, v180, v196
	v_fma_f32 v35, v35, v181, v197
	v_cvt_pk_bf16_f32 v32, v32, v33
	v_cvt_pk_bf16_f32 v33, v34, v35
	global_store_dwordx2 v169, v[32:33], s[10:11] offset:32
	v_mul_f32_e32 v36, s86, v36
	v_mul_f32_e32 v37, s86, v37
	v_mul_f32_e32 v38, s86, v38
	v_mul_f32_e32 v39, s86, v39
	v_fma_f32 v36, v36, v182, v198
	v_fma_f32 v37, v37, v183, v199
	v_fma_f32 v38, v38, v184, v200
	v_fma_f32 v39, v39, v185, v201
	v_cvt_pk_bf16_f32 v36, v36, v37
	v_cvt_pk_bf16_f32 v37, v38, v39
	global_store_dwordx2 v170, v[36:37], s[10:11] offset:32
	v_mul_f32_e32 v40, s86, v40
	v_mul_f32_e32 v41, s86, v41
	v_mul_f32_e32 v42, s86, v42
	v_mul_f32_e32 v43, s86, v43
	v_fma_f32 v40, v40, v186, v202
	v_fma_f32 v41, v41, v187, v203
	v_fma_f32 v42, v42, v188, v204
	v_fma_f32 v43, v43, v189, v205
	v_cvt_pk_bf16_f32 v40, v40, v41
	v_cvt_pk_bf16_f32 v41, v42, v43
	global_store_dwordx2 v171, v[40:41], s[10:11] offset:32
	v_mul_f32_e32 v44, s86, v44
	v_mul_f32_e32 v45, s86, v45
	v_mul_f32_e32 v46, s86, v46
	v_mul_f32_e32 v47, s86, v47
	v_fma_f32 v44, v44, v190, v206
	v_fma_f32 v45, v45, v191, v207
	v_fma_f32 v46, v46, v192, v208
	v_fma_f32 v47, v47, v193, v209
	v_cvt_pk_bf16_f32 v44, v44, v45
	v_cvt_pk_bf16_f32 v45, v46, v47
	global_store_dwordx2 v172, v[44:45], s[10:11] offset:32
	v_mul_f32_e32 v48, s87, v48
	v_mul_f32_e32 v49, s87, v49
	v_mul_f32_e32 v50, s87, v50
	v_mul_f32_e32 v51, s87, v51
	v_fma_f32 v48, v48, v178, v194
	v_fma_f32 v49, v49, v179, v195
	v_fma_f32 v50, v50, v180, v196
	v_fma_f32 v51, v51, v181, v197
	v_cvt_pk_bf16_f32 v48, v48, v49
	v_cvt_pk_bf16_f32 v49, v50, v51
	global_store_dwordx2 v169, v[48:49], s[10:11] offset:48
	v_mul_f32_e32 v52, s87, v52
	v_mul_f32_e32 v53, s87, v53
	v_mul_f32_e32 v54, s87, v54
	v_mul_f32_e32 v55, s87, v55
	v_fma_f32 v52, v52, v182, v198
	v_fma_f32 v53, v53, v183, v199
	v_fma_f32 v54, v54, v184, v200
	v_fma_f32 v55, v55, v185, v201
	v_cvt_pk_bf16_f32 v52, v52, v53
	v_cvt_pk_bf16_f32 v53, v54, v55
	global_store_dwordx2 v170, v[52:53], s[10:11] offset:48
	v_mul_f32_e32 v56, s87, v56
	v_mul_f32_e32 v57, s87, v57
	v_mul_f32_e32 v58, s87, v58
	v_mul_f32_e32 v59, s87, v59
	v_fma_f32 v56, v56, v186, v202
	v_fma_f32 v57, v57, v187, v203
	v_fma_f32 v58, v58, v188, v204
	v_fma_f32 v59, v59, v189, v205
	v_cvt_pk_bf16_f32 v56, v56, v57
	v_cvt_pk_bf16_f32 v57, v58, v59
	global_store_dwordx2 v171, v[56:57], s[10:11] offset:48
	v_mul_f32_e32 v60, s87, v60
	v_mul_f32_e32 v61, s87, v61
	v_mul_f32_e32 v62, s87, v62
	v_mul_f32_e32 v63, s87, v63
	v_fma_f32 v60, v60, v190, v206
	v_fma_f32 v61, v61, v191, v207
	v_fma_f32 v62, v62, v192, v208
	v_fma_f32 v63, v63, v193, v209
	v_cvt_pk_bf16_f32 v60, v60, v61
	v_cvt_pk_bf16_f32 v61, v62, v63
	global_store_dwordx2 v172, v[60:61], s[10:11] offset:48
	v_mul_f32_e32 v64, s88, v64
	v_mul_f32_e32 v65, s88, v65
	v_mul_f32_e32 v66, s88, v66
	v_mul_f32_e32 v67, s88, v67
	v_fma_f32 v64, v64, v178, v194
	v_fma_f32 v65, v65, v179, v195
	v_fma_f32 v66, v66, v180, v196
	v_fma_f32 v67, v67, v181, v197
	v_cvt_pk_bf16_f32 v64, v64, v65
	v_cvt_pk_bf16_f32 v65, v66, v67
	global_store_dwordx2 v169, v[64:65], s[10:11] offset:64
	v_mul_f32_e32 v68, s88, v68
	v_mul_f32_e32 v69, s88, v69
	v_mul_f32_e32 v70, s88, v70
	v_mul_f32_e32 v71, s88, v71
	v_fma_f32 v68, v68, v182, v198
	v_fma_f32 v69, v69, v183, v199
	v_fma_f32 v70, v70, v184, v200
	v_fma_f32 v71, v71, v185, v201
	v_cvt_pk_bf16_f32 v68, v68, v69
	v_cvt_pk_bf16_f32 v69, v70, v71
	global_store_dwordx2 v170, v[68:69], s[10:11] offset:64
	v_mul_f32_e32 v72, s88, v72
	v_mul_f32_e32 v73, s88, v73
	v_mul_f32_e32 v74, s88, v74
	v_mul_f32_e32 v75, s88, v75
	v_fma_f32 v72, v72, v186, v202
	v_fma_f32 v73, v73, v187, v203
	v_fma_f32 v74, v74, v188, v204
	v_fma_f32 v75, v75, v189, v205
	v_cvt_pk_bf16_f32 v72, v72, v73
	v_cvt_pk_bf16_f32 v73, v74, v75
	global_store_dwordx2 v171, v[72:73], s[10:11] offset:64
	v_mul_f32_e32 v76, s88, v76
	v_mul_f32_e32 v77, s88, v77
	v_mul_f32_e32 v78, s88, v78
	v_mul_f32_e32 v79, s88, v79
	v_fma_f32 v76, v76, v190, v206
	v_fma_f32 v77, v77, v191, v207
	v_fma_f32 v78, v78, v192, v208
	v_fma_f32 v79, v79, v193, v209
	v_cvt_pk_bf16_f32 v76, v76, v77
	v_cvt_pk_bf16_f32 v77, v78, v79
	global_store_dwordx2 v172, v[76:77], s[10:11] offset:64
	v_mul_f32_e32 v80, s89, v80
	v_mul_f32_e32 v81, s89, v81
	v_mul_f32_e32 v82, s89, v82
	v_mul_f32_e32 v83, s89, v83
	v_fma_f32 v80, v80, v178, v194
	v_fma_f32 v81, v81, v179, v195
	v_fma_f32 v82, v82, v180, v196
	v_fma_f32 v83, v83, v181, v197
	v_cvt_pk_bf16_f32 v80, v80, v81
	v_cvt_pk_bf16_f32 v81, v82, v83
	global_store_dwordx2 v169, v[80:81], s[10:11] offset:80
	v_mul_f32_e32 v84, s89, v84
	v_mul_f32_e32 v85, s89, v85
	v_mul_f32_e32 v86, s89, v86
	v_mul_f32_e32 v87, s89, v87
	v_fma_f32 v84, v84, v182, v198
	v_fma_f32 v85, v85, v183, v199
	v_fma_f32 v86, v86, v184, v200
	v_fma_f32 v87, v87, v185, v201
	v_cvt_pk_bf16_f32 v84, v84, v85
	v_cvt_pk_bf16_f32 v85, v86, v87
	global_store_dwordx2 v170, v[84:85], s[10:11] offset:80
	v_mul_f32_e32 v88, s89, v88
	v_mul_f32_e32 v89, s89, v89
	v_mul_f32_e32 v90, s89, v90
	v_mul_f32_e32 v91, s89, v91
	v_fma_f32 v88, v88, v186, v202
	v_fma_f32 v89, v89, v187, v203
	v_fma_f32 v90, v90, v188, v204
	v_fma_f32 v91, v91, v189, v205
	v_cvt_pk_bf16_f32 v88, v88, v89
	v_cvt_pk_bf16_f32 v89, v90, v91
	global_store_dwordx2 v171, v[88:89], s[10:11] offset:80
	v_mul_f32_e32 v92, s89, v92
	v_mul_f32_e32 v93, s89, v93
	v_mul_f32_e32 v94, s89, v94
	v_mul_f32_e32 v95, s89, v95
	v_fma_f32 v92, v92, v190, v206
	v_fma_f32 v93, v93, v191, v207
	v_fma_f32 v94, v94, v192, v208
	v_fma_f32 v95, v95, v193, v209
	v_cvt_pk_bf16_f32 v92, v92, v93
	v_cvt_pk_bf16_f32 v93, v94, v95
	global_store_dwordx2 v172, v[92:93], s[10:11] offset:80
	v_mul_f32_e32 v96, s90, v96
	v_mul_f32_e32 v97, s90, v97
	v_mul_f32_e32 v98, s90, v98
	v_mul_f32_e32 v99, s90, v99
	v_fma_f32 v96, v96, v178, v194
	v_fma_f32 v97, v97, v179, v195
	v_fma_f32 v98, v98, v180, v196
	v_fma_f32 v99, v99, v181, v197
	v_cvt_pk_bf16_f32 v96, v96, v97
	v_cvt_pk_bf16_f32 v97, v98, v99
	global_store_dwordx2 v169, v[96:97], s[10:11] offset:96
	v_mul_f32_e32 v100, s90, v100
	v_mul_f32_e32 v101, s90, v101
	v_mul_f32_e32 v102, s90, v102
	v_mul_f32_e32 v103, s90, v103
	v_fma_f32 v100, v100, v182, v198
	v_fma_f32 v101, v101, v183, v199
	v_fma_f32 v102, v102, v184, v200
	v_fma_f32 v103, v103, v185, v201
	v_cvt_pk_bf16_f32 v100, v100, v101
	v_cvt_pk_bf16_f32 v101, v102, v103
	global_store_dwordx2 v170, v[100:101], s[10:11] offset:96
	v_mul_f32_e32 v104, s90, v104
	v_mul_f32_e32 v105, s90, v105
	v_mul_f32_e32 v106, s90, v106
	v_mul_f32_e32 v107, s90, v107
	v_fma_f32 v104, v104, v186, v202
	v_fma_f32 v105, v105, v187, v203
	v_fma_f32 v106, v106, v188, v204
	v_fma_f32 v107, v107, v189, v205
	v_cvt_pk_bf16_f32 v104, v104, v105
	v_cvt_pk_bf16_f32 v105, v106, v107
	global_store_dwordx2 v171, v[104:105], s[10:11] offset:96
	v_mul_f32_e32 v108, s90, v108
	v_mul_f32_e32 v109, s90, v109
	v_mul_f32_e32 v110, s90, v110
	v_mul_f32_e32 v111, s90, v111
	v_fma_f32 v108, v108, v190, v206
	v_fma_f32 v109, v109, v191, v207
	v_fma_f32 v110, v110, v192, v208
	v_fma_f32 v111, v111, v193, v209
	v_cvt_pk_bf16_f32 v108, v108, v109
	v_cvt_pk_bf16_f32 v109, v110, v111
	global_store_dwordx2 v172, v[108:109], s[10:11] offset:96
	v_mul_f32_e32 v112, s91, v112
	v_mul_f32_e32 v113, s91, v113
	v_mul_f32_e32 v114, s91, v114
	v_mul_f32_e32 v115, s91, v115
	v_fma_f32 v112, v112, v178, v194
	v_fma_f32 v113, v113, v179, v195
	v_fma_f32 v114, v114, v180, v196
	v_fma_f32 v115, v115, v181, v197
	v_cvt_pk_bf16_f32 v112, v112, v113
	v_cvt_pk_bf16_f32 v113, v114, v115
	global_store_dwordx2 v169, v[112:113], s[10:11] offset:112
	v_mul_f32_e32 v116, s91, v116
	v_mul_f32_e32 v117, s91, v117
	v_mul_f32_e32 v118, s91, v118
	v_mul_f32_e32 v119, s91, v119
	v_fma_f32 v116, v116, v182, v198
	v_fma_f32 v117, v117, v183, v199
	v_fma_f32 v118, v118, v184, v200
	v_fma_f32 v119, v119, v185, v201
	v_cvt_pk_bf16_f32 v116, v116, v117
	v_cvt_pk_bf16_f32 v117, v118, v119
	global_store_dwordx2 v170, v[116:117], s[10:11] offset:112
	v_mul_f32_e32 v120, s91, v120
	v_mul_f32_e32 v121, s91, v121
	v_mul_f32_e32 v122, s91, v122
	v_mul_f32_e32 v123, s91, v123
	v_fma_f32 v120, v120, v186, v202
	v_fma_f32 v121, v121, v187, v203
	v_fma_f32 v122, v122, v188, v204
	v_fma_f32 v123, v123, v189, v205
	v_cvt_pk_bf16_f32 v120, v120, v121
	v_cvt_pk_bf16_f32 v121, v122, v123
	global_store_dwordx2 v171, v[120:121], s[10:11] offset:112
	v_mul_f32_e32 v124, s91, v124
	v_mul_f32_e32 v125, s91, v125
	v_mul_f32_e32 v126, s91, v126
	v_mul_f32_e32 v127, s91, v127
	v_fma_f32 v124, v124, v190, v206
	v_fma_f32 v125, v125, v191, v207
	v_fma_f32 v126, v126, v192, v208
	v_fma_f32 v127, v127, v193, v209
	v_cvt_pk_bf16_f32 v124, v124, v125
	v_cvt_pk_bf16_f32 v125, v126, v127
	global_store_dwordx2 v172, v[124:125], s[10:11] offset:112
	s_add_i32 s4, s4, s3
	s_cmpk_lt_i32 s4, 0x200
	s_cbranch_scc1 .Lmy_hdn1_loop

.LBB0_427:
	s_or_b64 exec, exec, s[0:1]
	s_cmpk_gt_i32 s2, 0x17ff
	s_waitcnt lgkmcnt(0)
	s_barrier
	s_cbranch_scc1 .LBB0_448
	v_xor_b32_e32 v0, v128, v131
	v_and_b32_e32 v64, 0x3f800, v149
	v_mov_b32_e32 v65, 0
	v_lshlrev_b32_e32 v0, 4, v0
	v_and_b32_e32 v0, 0x70, v0
	v_mov_b32_e32 v1, v65
	v_lshl_add_u64 v[2:3], s[50:51], 0, v[64:65]
	v_lshl_add_u64 v[66:67], v[2:3], 0, v[0:1]
	v_and_b32_e32 v0, 0x1e0, v153
	v_or_b32_e32 v1, v0, v138
	v_bitop3_b32 v2, v128, v139, 3 bitop3:0x6c
	v_lshlrev_b32_e32 v161, 7, v1
	v_lshlrev_b32_e32 v1, 13, v135
	v_lshlrev_b32_e32 v160, 4, v2
	v_lshl_add_u32 v2, v134, 3, v138
	v_lshl_or_b32 v3, v134, 11, v1
	v_lshlrev_b32_e32 v5, 5, v138
	v_or3_b32 v163, v1, v137, v5
	v_lshl_or_b32 v164, v2, 2, v3
	v_add_u32_e32 v5, 0x60, v2
	v_add_u32_e32 v2, 0x70, v2
	v_and_b32_e32 v5, 0x7f, v5
	v_and_b32_e32 v2, 0x7f, v2
	v_lshl_or_b32 v165, v5, 2, v3
	v_lshl_or_b32 v166, v2, 2, v3
	v_add_u32_e32 v3, 8, v133
	v_and_b32_e32 v3, 0x78, v3
	v_lshlrev_b32_e32 v2, 9, v136
	v_lshlrev_b32_e32 v3, 2, v3
	v_or3_b32 v168, v1, v2, v3
	v_add_u32_e32 v3, 16, v133
	v_and_b32_e32 v3, 0x78, v3
	v_lshlrev_b32_e32 v2, 9, v132
	v_lshlrev_b32_e32 v3, 2, v3
	v_or3_b32 v170, v1, v2, v3
	v_add_u32_e32 v3, 24, v133
	v_and_b32_e32 v3, 0x78, v3
	s_add_u32 s47, s50, 0x1a00000
	v_lshlrev_b32_e32 v4, 5, v135
	v_lshlrev_b32_e32 v2, 9, v130
	v_lshlrev_b32_e32 v3, 2, v3
	s_addc_u32 s53, s51, 0
	s_mov_b64 s[0:1], 0x3a00000
	v_and_or_b32 v0, v154, 12, v0
	v_or3_b32 v172, v1, v2, v3
	v_or_b32_e32 v1, 16, v4
	v_add_u32_e32 v5, 0x100, v131
	v_add_u32_e32 v6, 0x200, v131
	v_add_u32_e32 v7, 0x300, v131
	v_add_u32_e32 v8, 0x500, v131
	v_add_u32_e32 v9, 0x600, v131
	v_add_u32_e32 v10, 0x700, v131
	s_add_u32 s6, s50, 0x1200000
	v_lshl_add_u64 v[68:69], v[66:67], 0, s[0:1]
	v_or_b32_e32 v174, v1, v134
	v_or_b32_e32 v175, v136, v1
	v_or_b32_e32 v176, v132, v1
	v_or_b32_e32 v177, v130, v1
	v_and_b32_e32 v1, 24, v153
	s_movk_i32 s0, 0x3c0
	v_lshrrev_b32_e32 v178, 4, v5
	v_lshrrev_b32_e32 v179, 4, v6
	v_lshrrev_b32_e32 v180, 4, v7
	v_lshrrev_b32_e32 v182, 4, v8
	v_lshrrev_b32_e32 v183, 4, v9
	v_lshrrev_b32_e32 v184, 4, v10
	s_addc_u32 s7, s51, 0
	v_lshl_or_b32 v72, v0, 6, v138
	v_bitop3_b32 v0, v128, 7, v131 bitop3:0x48
	v_or_b32_e32 v167, v134, v4
	v_or_b32_e32 v169, v136, v4
	v_or_b32_e32 v171, v132, v4
	v_or_b32_e32 v173, v130, v4
	v_and_or_b32 v1, v131, s0, v1
	v_mul_u32_u24_e32 v2, 0x110, v138
	v_lshlrev_b32_e32 v3, 4, v138
	v_mul_u32_u24_e32 v4, 0x110, v128
	v_mul_u32_u24_e32 v5, 0x110, v178
	v_mul_u32_u24_e32 v6, 0x110, v179
	v_mul_u32_u24_e32 v7, 0x110, v180
	v_mul_u32_u24_e32 v8, 0x110, v182
	v_mul_u32_u24_e32 v9, 0x110, v183
	v_mul_u32_u24_e32 v10, 0x110, v184
	s_add_u32 s8, s50, 0x1600000
	v_lshl_or_b32 v64, v0, 4, v64
	v_lshlrev_b32_e32 v71, 7, v138
	v_lshlrev_b32_e32 v162, 4, v152
	v_lshlrev_b32_e32 v70, 3, v138
	v_or_b32_e32 v181, 64, v128
	s_addc_u32 s9, s51, 0
	v_mov_b32_e32 v73, v65
	v_lshl_add_u64 v[74:75], s[50:51], 0, v[64:65]
	s_mov_b64 s[10:11], 0x10000
	v_add_u32_e32 v185, 0x1000, v129
	s_mov_b64 s[12:13], 0x20000
	v_add_u32_e32 v186, 0x2000, v129
	s_mov_b64 s[14:15], 0x30000
	v_add_u32_e32 v187, 0x3000, v129
	v_or_b32_e32 v188, 0x4000, v129
	v_add_u32_e32 v189, 0x5000, v129
	v_add_u32_e32 v190, 0x6000, v129
	v_add_u32_e32 v191, 0x7000, v129
	s_mov_b64 s[18:19], 0x3a00080
	s_mov_b64 s[20:21], 0x3a10080
	s_mov_b64 s[22:23], 0x3a20080
	s_mov_b64 s[24:25], 0x3a30080
	s_mov_b64 s[26:27], 0x80
	s_mov_b64 s[28:29], 0x10080
	s_mov_b64 s[30:31], 0x20080
	s_mov_b64 s[34:35], 0x30080
	s_mov_b32 s39, 0
	v_lshlrev_b32_e32 v192, 2, v138
	s_brev_b32 s46, 60
	s_mov_b32 s52, 0x358637bd
	s_mov_b32 s60, 0x800000
	s_mov_b32 s61, 0x9a00000
	s_movk_i32 s62, 0x7fff
	s_mov_b32 s63, 0x7060302
	v_add_u32_e32 v193, v1, v2
	v_add_u32_e32 v194, v3, v4
	v_add_u32_e32 v195, v3, v5
	v_add_u32_e32 v196, v3, v6
	v_add_u32_e32 v197, v3, v7
	v_add_u32_e32 v198, v3, v8
	v_add_u32_e32 v199, v3, v9
	v_add_u32_e32 v200, v3, v10
	v_mbcnt_hi_u32_b32 v201, -1, v155
	v_mov_b32_e32 v202, 0x3db504f3
	s_mov_b32 s64, s2
	s_mov_b32 s89, 0
	s_branch .LBB0_430
.LBB0_429:
	s_xor_b32 s89, s89, 1
	s_cmp_lg_u32 s89, 0
	s_cbranch_scc1 .LBB0_430
	s_add_i32 s64, s64, s3
	s_cmpk_lt_i32 s64, 0xc00
	s_cbranch_scc0 .LBB0_448
.LBB0_430:
	s_lshr_b32 s90, s64, 3
	s_lshl_b32 s90, s90, 4
	s_and_b32 s91, s64, 7
	s_or_b32 s90, s90, s91
	s_lshl_b32 s91, s89, 3
	s_add_i32 s90, s90, s91
	s_ashr_i32 s1, s90, 31
	s_lshr_b32 s1, s1, 23
	s_add_i32 s1, s90, s1
	s_ashr_i32 s1, s1, 9
	s_and_b32 s0, s90, 7
	s_lshl_b32 s1, s1, 3
	s_or_b32 s38, s1, s0
	s_mul_hi_i32 s66, s38, 0x2aaaaaab
	s_lshr_b32 s0, s66, 31
	s_add_i32 s66, s66, s0
	s_lshl_b32 s0, s66, 3
	s_bfe_u32 s1, s90, 0x30003
	s_or_b32 s0, s0, s1
	s_mul_i32 s1, s66, 6
	s_sub_i32 s65, s38, s1
	s_lshl_b32 s1, s65, 3
	s_bfe_u32 s33, s90, 0x30006
	s_or_b32 s4, s1, s33
	s_ashr_i32 s1, s0, 31
	s_ashr_i32 s5, s4, 31
	s_lshl_b64 s[54:55], s[4:5], 18
	s_lshl_b64 s[56:57], s[0:1], 18
	s_cmp_lg_u32 s89, 0
	s_cbranch_scc1 .Lmy_ip1_pass2
	s_barrier
	s_add_u32 s84, s50, 0x3a00000
	s_addc_u32 s85, s51, 0
	s_add_u32 s84, s84, s56
	s_addc_u32 s85, s85, s57
	s_add_u32 s92, s84, 0x40000
	s_addc_u32 s93, s85, 0
	s_add_u32 s86, s50, s54
	s_addc_u32 s87, s51, s55
	s_lshl_b64 s[54:55], s[0:1], 17
	v_readfirstlane_b32 s88, v129
	v_and_b32_e32 v200, 15, v131
	v_bfe_u32 v201, v131, 4, 2
	v_and_b32_e32 v202, 63, v131
	v_lshlrev_b32_e32 v202, 4, v202
	v_lshrrev_b32_e32 v203, 6, v131
	v_lshl_add_u32 v66, v203, 16, v202
	v_add_u32_e32 v67, 0x8000, v66
	v_bfe_u32 v202, v131, 1, 3
	v_xor_b32_e32 v202, v201, v202
	v_lshlrev_b32_e32 v202, 4, v202
	v_lshl_or_b32 v75, v200, 7, v202
	v_xor_b32_e32 v212, 64, v75
	v_bfe_u32 v200, v131, 4, 3
	v_and_b32_e32 v201, 7, v131
	v_xor_b32_e32 v200, v200, v201
	v_lshlrev_b32_e32 v200, 4, v200
	v_lshrrev_b32_e32 v201, 3, v131
	v_lshl_or_b32 v68, v201, 11, v200
	v_add_u32_e32 v69, 65536, v68
	v_add_u32_e32 v71, 131072, v68
	v_add_u32_e32 v74, 196608, v68
	s_add_u32 m0, s88, 0
	v_mov_b32_e32 v32, 0
	v_mov_b32_e32 v33, 0
	global_load_lds_dwordx4 v68, s[86:87]
	v_mov_b32_e32 v34, 0
	v_mov_b32_e32 v35, 0
	v_mov_b32_e32 v36, 0
	s_add_u32 m0, s88, 4096
	v_mov_b32_e32 v37, 0
	v_mov_b32_e32 v38, 0
	global_load_lds_dwordx4 v69, s[86:87]
	v_mov_b32_e32 v39, 0
	v_mov_b32_e32 v40, 0
	v_mov_b32_e32 v41, 0
	s_add_u32 m0, s88, 8192
	v_mov_b32_e32 v42, 0
	v_mov_b32_e32 v43, 0
	global_load_lds_dwordx4 v71, s[86:87]
	v_mov_b32_e32 v44, 0
	v_mov_b32_e32 v45, 0
	v_mov_b32_e32 v46, 0
	s_add_u32 m0, s88, 12288
	v_mov_b32_e32 v47, 0
	v_mov_b32_e32 v48, 0
	global_load_lds_dwordx4 v74, s[86:87]
	s_add_u32 s86, s86, 128
	s_addc_u32 s87, s87, 0
	v_mov_b32_e32 v49, 0
	v_mov_b32_e32 v50, 0
	v_mov_b32_e32 v51, 0
	global_load_dwordx4 v[76:79], v66, s[84:85] offset:0
	v_mov_b32_e32 v52, 0
	v_mov_b32_e32 v53, 0
	v_mov_b32_e32 v54, 0
	global_load_dwordx4 v[80:83], v67, s[84:85] offset:0
	v_mov_b32_e32 v55, 0
	v_mov_b32_e32 v56, 0
	v_mov_b32_e32 v57, 0
	global_load_dwordx4 v[84:87], v66, s[92:93] offset:0
	v_mov_b32_e32 v58, 0
	v_mov_b32_e32 v59, 0
	v_mov_b32_e32 v60, 0
	global_load_dwordx4 v[88:91], v67, s[92:93] offset:0
	v_mov_b32_e32 v61, 0
	v_mov_b32_e32 v62, 0
	v_mov_b32_e32 v63, 0
	global_load_dwordx4 v[140:143], v66, s[84:85] offset:1024
	v_mov_b32_e32 v4, 0
	v_mov_b32_e32 v5, 0
	v_mov_b32_e32 v6, 0
	global_load_dwordx4 v[144:147], v67, s[84:85] offset:1024
	v_mov_b32_e32 v7, 0
	v_mov_b32_e32 v12, 0
	v_mov_b32_e32 v13, 0
	global_load_dwordx4 v[148:151], v66, s[92:93] offset:1024
	v_mov_b32_e32 v14, 0
	v_mov_b32_e32 v15, 0
	v_mov_b32_e32 v16, 0
	global_load_dwordx4 v[204:207], v67, s[92:93] offset:1024
	s_add_u32 s84, s84, 0x800
	s_addc_u32 s85, s85, 0
	s_add_u32 s92, s92, 0x800
	s_addc_u32 s93, s93, 0
	v_mov_b32_e32 v17, 0
	v_mov_b32_e32 v18, 0
	v_mov_b32_e32 v19, 0
	s_add_u32 m0, s88, 16384
	v_mov_b32_e32 v20, 0
	v_mov_b32_e32 v21, 0
	global_load_lds_dwordx4 v68, s[86:87]
	v_mov_b32_e32 v22, 0
	v_mov_b32_e32 v23, 0
	v_mov_b32_e32 v0, 0
	s_add_u32 m0, s88, 20480
	v_mov_b32_e32 v1, 0
	v_mov_b32_e32 v2, 0
	global_load_lds_dwordx4 v69, s[86:87]
	v_mov_b32_e32 v3, 0
	v_mov_b32_e32 v8, 0
	v_mov_b32_e32 v9, 0
	s_add_u32 m0, s88, 24576
	v_mov_b32_e32 v10, 0
	v_mov_b32_e32 v11, 0
	global_load_lds_dwordx4 v71, s[86:87]
	v_mov_b32_e32 v24, 0
	v_mov_b32_e32 v25, 0
	v_mov_b32_e32 v26, 0
	s_add_u32 m0, s88, 28672
	v_mov_b32_e32 v27, 0
	v_mov_b32_e32 v28, 0
	global_load_lds_dwordx4 v74, s[86:87]
	s_add_u32 s86, s86, 128
	s_addc_u32 s87, s87, 0
	v_mov_b32_e32 v29, 0
	v_mov_b32_e32 v30, 0
	v_mov_b32_e32 v31, 0
	s_add_u32 m0, s88, 32768
	v_mov_b32_e32 v188, 0
	v_mov_b32_e32 v189, 0
	global_load_lds_dwordx4 v68, s[86:87]
	v_mov_b32_e32 v190, 0
	v_mov_b32_e32 v191, 0
	v_mov_b32_e32 v208, 0
	s_add_u32 m0, s88, 36864
	v_mov_b32_e32 v209, 0
	v_mov_b32_e32 v210, 0
	global_load_lds_dwordx4 v69, s[86:87]
	v_mov_b32_e32 v211, 0
	v_mov_b32_e32 v232, 0
	v_mov_b32_e32 v233, 0
	s_add_u32 m0, s88, 40960
	v_mov_b32_e32 v234, 0
	v_mov_b32_e32 v235, 0
	global_load_lds_dwordx4 v71, s[86:87]
	v_mov_b32_e32 v236, 0
	v_mov_b32_e32 v237, 0
	v_mov_b32_e32 v238, 0
	s_add_u32 m0, s88, 45056
	v_mov_b32_e32 v239, 0
	v_mov_b32_e32 v240, 0
	global_load_lds_dwordx4 v74, s[86:87]
	s_add_u32 s86, s86, 128
	s_addc_u32 s87, s87, 0
	v_mov_b32_e32 v241, 0
	v_mov_b32_e32 v242, 0
	v_mov_b32_e32 v243, 0
	v_mov_b32_e32 v248, 0
	v_mov_b32_e32 v249, 0
	v_mov_b32_e32 v250, 0
	v_mov_b32_e32 v251, 0
	v_mov_b32_e32 v252, 0
	v_mov_b32_e32 v253, 0
	v_mov_b32_e32 v254, 0
	v_mov_b32_e32 v255, 0
	v_mov_b32_e32 v92, 0
	v_mov_b32_e32 v93, 0
	v_mov_b32_e32 v94, 0
	v_mov_b32_e32 v95, 0
	v_mov_b32_e32 v96, 0
	v_mov_b32_e32 v97, 0
	v_mov_b32_e32 v98, 0
	v_mov_b32_e32 v99, 0
	v_mov_b32_e32 v100, 0
	v_mov_b32_e32 v101, 0
	v_mov_b32_e32 v102, 0
	v_mov_b32_e32 v103, 0
	v_mov_b32_e32 v104, 0
	v_mov_b32_e32 v105, 0
	v_mov_b32_e32 v106, 0
	v_mov_b32_e32 v107, 0
	v_mov_b32_e32 v108, 0
	v_mov_b32_e32 v109, 0
	v_mov_b32_e32 v110, 0
	v_mov_b32_e32 v111, 0
	v_mov_b32_e32 v112, 0
	v_mov_b32_e32 v113, 0
	v_mov_b32_e32 v114, 0
	v_mov_b32_e32 v115, 0
	v_mov_b32_e32 v116, 0
	v_mov_b32_e32 v117, 0
	v_mov_b32_e32 v118, 0
	v_mov_b32_e32 v119, 0
	v_mov_b32_e32 v120, 0
	v_mov_b32_e32 v121, 0
	v_mov_b32_e32 v122, 0
	v_mov_b32_e32 v123, 0
	v_mov_b32_e32 v124, 0
	v_mov_b32_e32 v125, 0
	v_mov_b32_e32 v126, 0
	v_mov_b32_e32 v127, 0
	s_waitcnt vmcnt(12)
	s_barrier
	ds_read_b128 v[176:179], v75 offset:0
	ds_read_b128 v[180:183], v75 offset:2048
	ds_read_b128 v[184:187], v75 offset:4096
	ds_read_b128 v[192:195], v75 offset:6144
	ds_read_b128 v[196:199], v75 offset:8192
	global_load_dwordx4 v[160:163], v66, s[84:85] offset:0
	s_waitcnt lgkmcnt(4)
	v_mfma_f32_16x16x32_bf16 v[32:35], v[76:79], v[176:179], v[32:35]
	v_mfma_f32_16x16x32_bf16 v[4:7], v[80:83], v[176:179], v[4:7]
	v_mfma_f32_16x16x32_bf16 v[188:191], v[84:87], v[176:179], v[188:191]
	v_mfma_f32_16x16x32_bf16 v[96:99], v[88:91], v[176:179], v[96:99]
	ds_read_b128 v[200:203], v75 offset:10240
	global_load_dwordx4 v[164:167], v67, s[84:85] offset:0
	s_waitcnt lgkmcnt(4)
	v_mfma_f32_16x16x32_bf16 v[36:39], v[76:79], v[180:183], v[36:39]
	v_mfma_f32_16x16x32_bf16 v[12:15], v[80:83], v[180:183], v[12:15]
	v_mfma_f32_16x16x32_bf16 v[208:211], v[84:87], v[180:183], v[208:211]
	v_mfma_f32_16x16x32_bf16 v[100:103], v[88:91], v[180:183], v[100:103]
	ds_read_b128 v[176:179], v75 offset:12288
	global_load_dwordx4 v[168:171], v66, s[92:93] offset:0
	s_waitcnt lgkmcnt(4)
	v_mfma_f32_16x16x32_bf16 v[40:43], v[76:79], v[184:187], v[40:43]
	v_mfma_f32_16x16x32_bf16 v[16:19], v[80:83], v[184:187], v[16:19]
	v_mfma_f32_16x16x32_bf16 v[232:235], v[84:87], v[184:187], v[232:235]
	v_mfma_f32_16x16x32_bf16 v[104:107], v[88:91], v[184:187], v[104:107]
	ds_read_b128 v[180:183], v75 offset:14336
	global_load_dwordx4 v[172:175], v67, s[92:93] offset:0
	s_waitcnt lgkmcnt(4)
	v_mfma_f32_16x16x32_bf16 v[44:47], v[76:79], v[192:195], v[44:47]
	v_mfma_f32_16x16x32_bf16 v[20:23], v[80:83], v[192:195], v[20:23]
	v_mfma_f32_16x16x32_bf16 v[236:239], v[84:87], v[192:195], v[236:239]
	v_mfma_f32_16x16x32_bf16 v[108:111], v[88:91], v[192:195], v[108:111]
	ds_read_b128 v[184:187], v212 offset:0
	s_waitcnt lgkmcnt(4)
	v_mfma_f32_16x16x32_bf16 v[48:51], v[76:79], v[196:199], v[48:51]
	v_mfma_f32_16x16x32_bf16 v[0:3], v[80:83], v[196:199], v[0:3]
	v_mfma_f32_16x16x32_bf16 v[240:243], v[84:87], v[196:199], v[240:243]
	v_mfma_f32_16x16x32_bf16 v[112:115], v[88:91], v[196:199], v[112:115]
	ds_read_b128 v[192:195], v212 offset:2048
	s_waitcnt lgkmcnt(4)
	v_mfma_f32_16x16x32_bf16 v[52:55], v[76:79], v[200:203], v[52:55]
	v_mfma_f32_16x16x32_bf16 v[8:11], v[80:83], v[200:203], v[8:11]
	v_mfma_f32_16x16x32_bf16 v[248:251], v[84:87], v[200:203], v[248:251]
	v_mfma_f32_16x16x32_bf16 v[116:119], v[88:91], v[200:203], v[116:119]
	ds_read_b128 v[196:199], v212 offset:4096
	s_waitcnt lgkmcnt(4)
	v_mfma_f32_16x16x32_bf16 v[56:59], v[76:79], v[176:179], v[56:59]
	v_mfma_f32_16x16x32_bf16 v[24:27], v[80:83], v[176:179], v[24:27]
	v_mfma_f32_16x16x32_bf16 v[252:255], v[84:87], v[176:179], v[252:255]
	v_mfma_f32_16x16x32_bf16 v[120:123], v[88:91], v[176:179], v[120:123]
	ds_read_b128 v[200:203], v212 offset:6144
	s_waitcnt lgkmcnt(4)
	v_mfma_f32_16x16x32_bf16 v[60:63], v[76:79], v[180:183], v[60:63]
	v_mfma_f32_16x16x32_bf16 v[28:31], v[80:83], v[180:183], v[28:31]
	v_mfma_f32_16x16x32_bf16 v[92:95], v[84:87], v[180:183], v[92:95]
	v_mfma_f32_16x16x32_bf16 v[124:127], v[88:91], v[180:183], v[124:127]
	s_waitcnt vmcnt(8)
	s_barrier
	s_waitcnt vmcnt(12)
	ds_read_b128 v[176:179], v212 offset:8192
	global_load_dwordx4 v[76:79], v66, s[84:85] offset:1024
	s_waitcnt lgkmcnt(4)
	v_mfma_f32_16x16x32_bf16 v[32:35], v[140:143], v[184:187], v[32:35]
	v_mfma_f32_16x16x32_bf16 v[4:7], v[144:147], v[184:187], v[4:7]
	v_mfma_f32_16x16x32_bf16 v[188:191], v[148:151], v[184:187], v[188:191]
	v_mfma_f32_16x16x32_bf16 v[96:99], v[204:207], v[184:187], v[96:99]
	ds_read_b128 v[180:183], v212 offset:10240
	global_load_dwordx4 v[80:83], v67, s[84:85] offset:1024
	s_waitcnt lgkmcnt(4)
	v_mfma_f32_16x16x32_bf16 v[36:39], v[140:143], v[192:195], v[36:39]
	v_mfma_f32_16x16x32_bf16 v[12:15], v[144:147], v[192:195], v[12:15]
	v_mfma_f32_16x16x32_bf16 v[208:211], v[148:151], v[192:195], v[208:211]
	v_mfma_f32_16x16x32_bf16 v[100:103], v[204:207], v[192:195], v[100:103]
	ds_read_b128 v[184:187], v212 offset:12288
	global_load_dwordx4 v[84:87], v66, s[92:93] offset:1024
	s_waitcnt lgkmcnt(4)
	v_mfma_f32_16x16x32_bf16 v[40:43], v[140:143], v[196:199], v[40:43]
	v_mfma_f32_16x16x32_bf16 v[16:19], v[144:147], v[196:199], v[16:19]
	v_mfma_f32_16x16x32_bf16 v[232:235], v[148:151], v[196:199], v[232:235]
	v_mfma_f32_16x16x32_bf16 v[104:107], v[204:207], v[196:199], v[104:107]
	ds_read_b128 v[192:195], v212 offset:14336
	global_load_dwordx4 v[88:91], v67, s[92:93] offset:1024
	s_add_u32 s84, s84, 0x800
	s_addc_u32 s85, s85, 0
	s_add_u32 s92, s92, 0x800
	s_addc_u32 s93, s93, 0
	s_waitcnt lgkmcnt(4)
	v_mfma_f32_16x16x32_bf16 v[44:47], v[140:143], v[200:203], v[44:47]
	v_mfma_f32_16x16x32_bf16 v[20:23], v[144:147], v[200:203], v[20:23]
	v_mfma_f32_16x16x32_bf16 v[236:239], v[148:151], v[200:203], v[236:239]
	v_mfma_f32_16x16x32_bf16 v[108:111], v[204:207], v[200:203], v[108:111]
	ds_read_b128 v[196:199], v75 offset:16384
	s_add_u32 m0, s88, 49152
	s_nop 0
	global_load_lds_dwordx4 v68, s[86:87]
	s_waitcnt lgkmcnt(4)
	v_mfma_f32_16x16x32_bf16 v[48:51], v[140:143], v[176:179], v[48:51]
	v_mfma_f32_16x16x32_bf16 v[0:3], v[144:147], v[176:179], v[0:3]
	v_mfma_f32_16x16x32_bf16 v[240:243], v[148:151], v[176:179], v[240:243]
	v_mfma_f32_16x16x32_bf16 v[112:115], v[204:207], v[176:179], v[112:115]
	ds_read_b128 v[200:203], v75 offset:18432
	s_add_u32 m0, s88, 53248
	s_nop 0
	global_load_lds_dwordx4 v69, s[86:87]
	s_waitcnt lgkmcnt(4)
	v_mfma_f32_16x16x32_bf16 v[52:55], v[140:143], v[180:183], v[52:55]
	v_mfma_f32_16x16x32_bf16 v[8:11], v[144:147], v[180:183], v[8:11]
	v_mfma_f32_16x16x32_bf16 v[248:251], v[148:151], v[180:183], v[248:251]
	v_mfma_f32_16x16x32_bf16 v[116:119], v[204:207], v[180:183], v[116:119]
	ds_read_b128 v[176:179], v75 offset:20480
	s_add_u32 m0, s88, 57344
	s_nop 0
	global_load_lds_dwordx4 v71, s[86:87]
	s_waitcnt lgkmcnt(4)
	v_mfma_f32_16x16x32_bf16 v[56:59], v[140:143], v[184:187], v[56:59]
	v_mfma_f32_16x16x32_bf16 v[24:27], v[144:147], v[184:187], v[24:27]
	v_mfma_f32_16x16x32_bf16 v[252:255], v[148:151], v[184:187], v[252:255]
	v_mfma_f32_16x16x32_bf16 v[120:123], v[204:207], v[184:187], v[120:123]
	ds_read_b128 v[180:183], v75 offset:22528
	s_add_u32 m0, s88, 61440
	s_nop 0
	global_load_lds_dwordx4 v74, s[86:87]
	s_add_u32 s86, s86, 128
	s_addc_u32 s87, s87, 0
	s_waitcnt lgkmcnt(4)
	v_mfma_f32_16x16x32_bf16 v[60:63], v[140:143], v[192:195], v[60:63]
	v_mfma_f32_16x16x32_bf16 v[28:31], v[144:147], v[192:195], v[28:31]
	v_mfma_f32_16x16x32_bf16 v[92:95], v[148:151], v[192:195], v[92:95]
	v_mfma_f32_16x16x32_bf16 v[124:127], v[204:207], v[192:195], v[124:127]
	s_waitcnt vmcnt(8)
	ds_read_b128 v[184:187], v75 offset:24576
	global_load_dwordx4 v[140:143], v66, s[84:85] offset:0
	s_waitcnt lgkmcnt(4)
	v_mfma_f32_16x16x32_bf16 v[32:35], v[160:163], v[196:199], v[32:35]
	v_mfma_f32_16x16x32_bf16 v[4:7], v[164:167], v[196:199], v[4:7]
	v_mfma_f32_16x16x32_bf16 v[188:191], v[168:171], v[196:199], v[188:191]
	v_mfma_f32_16x16x32_bf16 v[96:99], v[172:175], v[196:199], v[96:99]
	ds_read_b128 v[192:195], v75 offset:26624
	global_load_dwordx4 v[144:147], v67, s[84:85] offset:0
	s_waitcnt lgkmcnt(4)
	v_mfma_f32_16x16x32_bf16 v[36:39], v[160:163], v[200:203], v[36:39]
	v_mfma_f32_16x16x32_bf16 v[12:15], v[164:167], v[200:203], v[12:15]
	v_mfma_f32_16x16x32_bf16 v[208:211], v[168:171], v[200:203], v[208:211]
	v_mfma_f32_16x16x32_bf16 v[100:103], v[172:175], v[200:203], v[100:103]
	ds_read_b128 v[196:199], v75 offset:28672
	global_load_dwordx4 v[148:151], v66, s[92:93] offset:0
	s_waitcnt lgkmcnt(4)
	v_mfma_f32_16x16x32_bf16 v[40:43], v[160:163], v[176:179], v[40:43]
	v_mfma_f32_16x16x32_bf16 v[16:19], v[164:167], v[176:179], v[16:19]
	v_mfma_f32_16x16x32_bf16 v[232:235], v[168:171], v[176:179], v[232:235]
	v_mfma_f32_16x16x32_bf16 v[104:107], v[172:175], v[176:179], v[104:107]
	ds_read_b128 v[200:203], v75 offset:30720
	global_load_dwordx4 v[204:207], v67, s[92:93] offset:0
	s_waitcnt lgkmcnt(4)
	v_mfma_f32_16x16x32_bf16 v[44:47], v[160:163], v[180:183], v[44:47]
	v_mfma_f32_16x16x32_bf16 v[20:23], v[164:167], v[180:183], v[20:23]
	v_mfma_f32_16x16x32_bf16 v[236:239], v[168:171], v[180:183], v[236:239]
	v_mfma_f32_16x16x32_bf16 v[108:111], v[172:175], v[180:183], v[108:111]
	ds_read_b128 v[176:179], v212 offset:16384
	s_waitcnt lgkmcnt(4)
	v_mfma_f32_16x16x32_bf16 v[48:51], v[160:163], v[184:187], v[48:51]
	v_mfma_f32_16x16x32_bf16 v[0:3], v[164:167], v[184:187], v[0:3]
	v_mfma_f32_16x16x32_bf16 v[240:243], v[168:171], v[184:187], v[240:243]
	v_mfma_f32_16x16x32_bf16 v[112:115], v[172:175], v[184:187], v[112:115]
	ds_read_b128 v[180:183], v212 offset:18432
	s_waitcnt lgkmcnt(4)
	v_mfma_f32_16x16x32_bf16 v[52:55], v[160:163], v[192:195], v[52:55]
	v_mfma_f32_16x16x32_bf16 v[8:11], v[164:167], v[192:195], v[8:11]
	v_mfma_f32_16x16x32_bf16 v[248:251], v[168:171], v[192:195], v[248:251]
	v_mfma_f32_16x16x32_bf16 v[116:119], v[172:175], v[192:195], v[116:119]
	ds_read_b128 v[184:187], v212 offset:20480
	s_waitcnt lgkmcnt(4)
	v_mfma_f32_16x16x32_bf16 v[56:59], v[160:163], v[196:199], v[56:59]
	v_mfma_f32_16x16x32_bf16 v[24:27], v[164:167], v[196:199], v[24:27]
	v_mfma_f32_16x16x32_bf16 v[252:255], v[168:171], v[196:199], v[252:255]
	v_mfma_f32_16x16x32_bf16 v[120:123], v[172:175], v[196:199], v[120:123]
	ds_read_b128 v[192:195], v212 offset:22528
	s_waitcnt lgkmcnt(4)
	v_mfma_f32_16x16x32_bf16 v[60:63], v[160:163], v[200:203], v[60:63]
	v_mfma_f32_16x16x32_bf16 v[28:31], v[164:167], v[200:203], v[28:31]
	v_mfma_f32_16x16x32_bf16 v[92:95], v[168:171], v[200:203], v[92:95]
	v_mfma_f32_16x16x32_bf16 v[124:127], v[172:175], v[200:203], v[124:127]
	s_waitcnt vmcnt(16)
	s_barrier
	s_waitcnt vmcnt(8)
	ds_read_b128 v[196:199], v212 offset:24576
	global_load_dwordx4 v[160:163], v66, s[84:85] offset:1024
	s_waitcnt lgkmcnt(4)
	v_mfma_f32_16x16x32_bf16 v[32:35], v[76:79], v[176:179], v[32:35]
	v_mfma_f32_16x16x32_bf16 v[4:7], v[80:83], v[176:179], v[4:7]
	v_mfma_f32_16x16x32_bf16 v[188:191], v[84:87], v[176:179], v[188:191]
	v_mfma_f32_16x16x32_bf16 v[96:99], v[88:91], v[176:179], v[96:99]
	ds_read_b128 v[200:203], v212 offset:26624
	global_load_dwordx4 v[164:167], v67, s[84:85] offset:1024
	s_waitcnt lgkmcnt(4)
	v_mfma_f32_16x16x32_bf16 v[36:39], v[76:79], v[180:183], v[36:39]
	v_mfma_f32_16x16x32_bf16 v[12:15], v[80:83], v[180:183], v[12:15]
	v_mfma_f32_16x16x32_bf16 v[208:211], v[84:87], v[180:183], v[208:211]
	v_mfma_f32_16x16x32_bf16 v[100:103], v[88:91], v[180:183], v[100:103]
	ds_read_b128 v[176:179], v212 offset:28672
	global_load_dwordx4 v[168:171], v66, s[92:93] offset:1024
	s_waitcnt lgkmcnt(4)
	v_mfma_f32_16x16x32_bf16 v[40:43], v[76:79], v[184:187], v[40:43]
	v_mfma_f32_16x16x32_bf16 v[16:19], v[80:83], v[184:187], v[16:19]
	v_mfma_f32_16x16x32_bf16 v[232:235], v[84:87], v[184:187], v[232:235]
	v_mfma_f32_16x16x32_bf16 v[104:107], v[88:91], v[184:187], v[104:107]
	ds_read_b128 v[180:183], v212 offset:30720
	global_load_dwordx4 v[172:175], v67, s[92:93] offset:1024
	s_add_u32 s84, s84, 0x800
	s_addc_u32 s85, s85, 0
	s_add_u32 s92, s92, 0x800
	s_addc_u32 s93, s93, 0
	s_waitcnt lgkmcnt(4)
	v_mfma_f32_16x16x32_bf16 v[44:47], v[76:79], v[192:195], v[44:47]
	v_mfma_f32_16x16x32_bf16 v[20:23], v[80:83], v[192:195], v[20:23]
	v_mfma_f32_16x16x32_bf16 v[236:239], v[84:87], v[192:195], v[236:239]
	v_mfma_f32_16x16x32_bf16 v[108:111], v[88:91], v[192:195], v[108:111]
	ds_read_b128 v[184:187], v75 offset:32768
	s_add_u32 m0, s88, 0
	s_nop 0
	global_load_lds_dwordx4 v68, s[86:87]
	s_waitcnt lgkmcnt(4)
	v_mfma_f32_16x16x32_bf16 v[48:51], v[76:79], v[196:199], v[48:51]
	v_mfma_f32_16x16x32_bf16 v[0:3], v[80:83], v[196:199], v[0:3]
	v_mfma_f32_16x16x32_bf16 v[240:243], v[84:87], v[196:199], v[240:243]
	v_mfma_f32_16x16x32_bf16 v[112:115], v[88:91], v[196:199], v[112:115]
	ds_read_b128 v[192:195], v75 offset:34816
	s_add_u32 m0, s88, 4096
	s_nop 0
	global_load_lds_dwordx4 v69, s[86:87]
	s_waitcnt lgkmcnt(4)
	v_mfma_f32_16x16x32_bf16 v[52:55], v[76:79], v[200:203], v[52:55]
	v_mfma_f32_16x16x32_bf16 v[8:11], v[80:83], v[200:203], v[8:11]
	v_mfma_f32_16x16x32_bf16 v[248:251], v[84:87], v[200:203], v[248:251]
	v_mfma_f32_16x16x32_bf16 v[116:119], v[88:91], v[200:203], v[116:119]
	ds_read_b128 v[196:199], v75 offset:36864
	s_add_u32 m0, s88, 8192
	s_nop 0
	global_load_lds_dwordx4 v71, s[86:87]
	s_waitcnt lgkmcnt(4)
	v_mfma_f32_16x16x32_bf16 v[56:59], v[76:79], v[176:179], v[56:59]
	v_mfma_f32_16x16x32_bf16 v[24:27], v[80:83], v[176:179], v[24:27]
	v_mfma_f32_16x16x32_bf16 v[252:255], v[84:87], v[176:179], v[252:255]
	v_mfma_f32_16x16x32_bf16 v[120:123], v[88:91], v[176:179], v[120:123]
	ds_read_b128 v[200:203], v75 offset:38912
	s_add_u32 m0, s88, 12288
	s_nop 0
	global_load_lds_dwordx4 v74, s[86:87]
	s_add_u32 s86, s86, 128
	s_addc_u32 s87, s87, 0
	s_waitcnt lgkmcnt(4)
	v_mfma_f32_16x16x32_bf16 v[60:63], v[76:79], v[180:183], v[60:63]
	v_mfma_f32_16x16x32_bf16 v[28:31], v[80:83], v[180:183], v[28:31]
	v_mfma_f32_16x16x32_bf16 v[92:95], v[84:87], v[180:183], v[92:95]
	v_mfma_f32_16x16x32_bf16 v[124:127], v[88:91], v[180:183], v[124:127]
	s_waitcnt vmcnt(8)
	ds_read_b128 v[176:179], v75 offset:40960
	global_load_dwordx4 v[76:79], v66, s[84:85] offset:0
	s_waitcnt lgkmcnt(4)
	v_mfma_f32_16x16x32_bf16 v[32:35], v[140:143], v[184:187], v[32:35]
	v_mfma_f32_16x16x32_bf16 v[4:7], v[144:147], v[184:187], v[4:7]
	v_mfma_f32_16x16x32_bf16 v[188:191], v[148:151], v[184:187], v[188:191]
	v_mfma_f32_16x16x32_bf16 v[96:99], v[204:207], v[184:187], v[96:99]
	ds_read_b128 v[180:183], v75 offset:43008
	global_load_dwordx4 v[80:83], v67, s[84:85] offset:0
	s_waitcnt lgkmcnt(4)
	v_mfma_f32_16x16x32_bf16 v[36:39], v[140:143], v[192:195], v[36:39]
	v_mfma_f32_16x16x32_bf16 v[12:15], v[144:147], v[192:195], v[12:15]
	v_mfma_f32_16x16x32_bf16 v[208:211], v[148:151], v[192:195], v[208:211]
	v_mfma_f32_16x16x32_bf16 v[100:103], v[204:207], v[192:195], v[100:103]
	ds_read_b128 v[184:187], v75 offset:45056
	global_load_dwordx4 v[84:87], v66, s[92:93] offset:0
	s_waitcnt lgkmcnt(4)
	v_mfma_f32_16x16x32_bf16 v[40:43], v[140:143], v[196:199], v[40:43]
	v_mfma_f32_16x16x32_bf16 v[16:19], v[144:147], v[196:199], v[16:19]
	v_mfma_f32_16x16x32_bf16 v[232:235], v[148:151], v[196:199], v[232:235]
	v_mfma_f32_16x16x32_bf16 v[104:107], v[204:207], v[196:199], v[104:107]
	ds_read_b128 v[192:195], v75 offset:47104
	global_load_dwordx4 v[88:91], v67, s[92:93] offset:0
	s_waitcnt lgkmcnt(4)
	v_mfma_f32_16x16x32_bf16 v[44:47], v[140:143], v[200:203], v[44:47]
	v_mfma_f32_16x16x32_bf16 v[20:23], v[144:147], v[200:203], v[20:23]
	v_mfma_f32_16x16x32_bf16 v[236:239], v[148:151], v[200:203], v[236:239]
	v_mfma_f32_16x16x32_bf16 v[108:111], v[204:207], v[200:203], v[108:111]
	ds_read_b128 v[196:199], v212 offset:32768
	s_waitcnt lgkmcnt(4)
	v_mfma_f32_16x16x32_bf16 v[48:51], v[140:143], v[176:179], v[48:51]
	v_mfma_f32_16x16x32_bf16 v[0:3], v[144:147], v[176:179], v[0:3]
	v_mfma_f32_16x16x32_bf16 v[240:243], v[148:151], v[176:179], v[240:243]
	v_mfma_f32_16x16x32_bf16 v[112:115], v[204:207], v[176:179], v[112:115]
	ds_read_b128 v[200:203], v212 offset:34816
	s_waitcnt lgkmcnt(4)
	v_mfma_f32_16x16x32_bf16 v[52:55], v[140:143], v[180:183], v[52:55]
	v_mfma_f32_16x16x32_bf16 v[8:11], v[144:147], v[180:183], v[8:11]
	v_mfma_f32_16x16x32_bf16 v[248:251], v[148:151], v[180:183], v[248:251]
	v_mfma_f32_16x16x32_bf16 v[116:119], v[204:207], v[180:183], v[116:119]
	ds_read_b128 v[176:179], v212 offset:36864
	s_waitcnt lgkmcnt(4)
	v_mfma_f32_16x16x32_bf16 v[56:59], v[140:143], v[184:187], v[56:59]
	v_mfma_f32_16x16x32_bf16 v[24:27], v[144:147], v[184:187], v[24:27]
	v_mfma_f32_16x16x32_bf16 v[252:255], v[148:151], v[184:187], v[252:255]
	v_mfma_f32_16x16x32_bf16 v[120:123], v[204:207], v[184:187], v[120:123]
	ds_read_b128 v[180:183], v212 offset:38912
	s_waitcnt lgkmcnt(4)
	v_mfma_f32_16x16x32_bf16 v[60:63], v[140:143], v[192:195], v[60:63]
	v_mfma_f32_16x16x32_bf16 v[28:31], v[144:147], v[192:195], v[28:31]
	v_mfma_f32_16x16x32_bf16 v[92:95], v[148:151], v[192:195], v[92:95]
	v_mfma_f32_16x16x32_bf16 v[124:127], v[204:207], v[192:195], v[124:127]
	s_waitcnt vmcnt(16)
	s_barrier
	s_waitcnt vmcnt(8)
	ds_read_b128 v[184:187], v212 offset:40960
	global_load_dwordx4 v[140:143], v66, s[84:85] offset:1024
	s_waitcnt lgkmcnt(4)
	v_mfma_f32_16x16x32_bf16 v[32:35], v[160:163], v[196:199], v[32:35]
	v_mfma_f32_16x16x32_bf16 v[4:7], v[164:167], v[196:199], v[4:7]
	v_mfma_f32_16x16x32_bf16 v[188:191], v[168:171], v[196:199], v[188:191]
	v_mfma_f32_16x16x32_bf16 v[96:99], v[172:175], v[196:199], v[96:99]
	ds_read_b128 v[192:195], v212 offset:43008
	global_load_dwordx4 v[144:147], v67, s[84:85] offset:1024
	s_waitcnt lgkmcnt(4)
	v_mfma_f32_16x16x32_bf16 v[36:39], v[160:163], v[200:203], v[36:39]
	v_mfma_f32_16x16x32_bf16 v[12:15], v[164:167], v[200:203], v[12:15]
	v_mfma_f32_16x16x32_bf16 v[208:211], v[168:171], v[200:203], v[208:211]
	v_mfma_f32_16x16x32_bf16 v[100:103], v[172:175], v[200:203], v[100:103]
	ds_read_b128 v[196:199], v212 offset:45056
	global_load_dwordx4 v[148:151], v66, s[92:93] offset:1024
	s_waitcnt lgkmcnt(4)
	v_mfma_f32_16x16x32_bf16 v[40:43], v[160:163], v[176:179], v[40:43]
	v_mfma_f32_16x16x32_bf16 v[16:19], v[164:167], v[176:179], v[16:19]
	v_mfma_f32_16x16x32_bf16 v[232:235], v[168:171], v[176:179], v[232:235]
	v_mfma_f32_16x16x32_bf16 v[104:107], v[172:175], v[176:179], v[104:107]
	ds_read_b128 v[200:203], v212 offset:47104
	global_load_dwordx4 v[204:207], v67, s[92:93] offset:1024
	s_add_u32 s84, s84, 0x800
	s_addc_u32 s85, s85, 0
	s_add_u32 s92, s92, 0x800
	s_addc_u32 s93, s93, 0
	s_waitcnt lgkmcnt(4)
	v_mfma_f32_16x16x32_bf16 v[44:47], v[160:163], v[180:183], v[44:47]
	v_mfma_f32_16x16x32_bf16 v[20:23], v[164:167], v[180:183], v[20:23]
	v_mfma_f32_16x16x32_bf16 v[236:239], v[168:171], v[180:183], v[236:239]
	v_mfma_f32_16x16x32_bf16 v[108:111], v[172:175], v[180:183], v[108:111]
	ds_read_b128 v[176:179], v75 offset:49152
	s_add_u32 m0, s88, 16384
	s_nop 0
	global_load_lds_dwordx4 v68, s[86:87]
	s_waitcnt lgkmcnt(4)
	v_mfma_f32_16x16x32_bf16 v[48:51], v[160:163], v[184:187], v[48:51]
	v_mfma_f32_16x16x32_bf16 v[0:3], v[164:167], v[184:187], v[0:3]
	v_mfma_f32_16x16x32_bf16 v[240:243], v[168:171], v[184:187], v[240:243]
	v_mfma_f32_16x16x32_bf16 v[112:115], v[172:175], v[184:187], v[112:115]
	ds_read_b128 v[180:183], v75 offset:51200
	s_add_u32 m0, s88, 20480
	s_nop 0
	global_load_lds_dwordx4 v69, s[86:87]
	s_waitcnt lgkmcnt(4)
	v_mfma_f32_16x16x32_bf16 v[52:55], v[160:163], v[192:195], v[52:55]
	v_mfma_f32_16x16x32_bf16 v[8:11], v[164:167], v[192:195], v[8:11]
	v_mfma_f32_16x16x32_bf16 v[248:251], v[168:171], v[192:195], v[248:251]
	v_mfma_f32_16x16x32_bf16 v[116:119], v[172:175], v[192:195], v[116:119]
	ds_read_b128 v[184:187], v75 offset:53248
	s_add_u32 m0, s88, 24576
	s_nop 0
	global_load_lds_dwordx4 v71, s[86:87]
	s_waitcnt lgkmcnt(4)
	v_mfma_f32_16x16x32_bf16 v[56:59], v[160:163], v[196:199], v[56:59]
	v_mfma_f32_16x16x32_bf16 v[24:27], v[164:167], v[196:199], v[24:27]
	v_mfma_f32_16x16x32_bf16 v[252:255], v[168:171], v[196:199], v[252:255]
	v_mfma_f32_16x16x32_bf16 v[120:123], v[172:175], v[196:199], v[120:123]
	ds_read_b128 v[192:195], v75 offset:55296
	s_add_u32 m0, s88, 28672
	s_nop 0
	global_load_lds_dwordx4 v74, s[86:87]
	s_add_u32 s86, s86, 128
	s_addc_u32 s87, s87, 0
	s_waitcnt lgkmcnt(4)
	v_mfma_f32_16x16x32_bf16 v[60:63], v[160:163], v[200:203], v[60:63]
	v_mfma_f32_16x16x32_bf16 v[28:31], v[164:167], v[200:203], v[28:31]
	v_mfma_f32_16x16x32_bf16 v[92:95], v[168:171], v[200:203], v[92:95]
	v_mfma_f32_16x16x32_bf16 v[124:127], v[172:175], v[200:203], v[124:127]
	s_waitcnt vmcnt(8)
	ds_read_b128 v[196:199], v75 offset:57344
	global_load_dwordx4 v[160:163], v66, s[84:85] offset:0
	s_waitcnt lgkmcnt(4)
	v_mfma_f32_16x16x32_bf16 v[32:35], v[76:79], v[176:179], v[32:35]
	v_mfma_f32_16x16x32_bf16 v[4:7], v[80:83], v[176:179], v[4:7]
	v_mfma_f32_16x16x32_bf16 v[188:191], v[84:87], v[176:179], v[188:191]
	v_mfma_f32_16x16x32_bf16 v[96:99], v[88:91], v[176:179], v[96:99]
	ds_read_b128 v[200:203], v75 offset:59392
	global_load_dwordx4 v[164:167], v67, s[84:85] offset:0
	s_waitcnt lgkmcnt(4)
	v_mfma_f32_16x16x32_bf16 v[36:39], v[76:79], v[180:183], v[36:39]
	v_mfma_f32_16x16x32_bf16 v[12:15], v[80:83], v[180:183], v[12:15]
	v_mfma_f32_16x16x32_bf16 v[208:211], v[84:87], v[180:183], v[208:211]
	v_mfma_f32_16x16x32_bf16 v[100:103], v[88:91], v[180:183], v[100:103]
	ds_read_b128 v[176:179], v75 offset:61440
	global_load_dwordx4 v[168:171], v66, s[92:93] offset:0
	s_waitcnt lgkmcnt(4)
	v_mfma_f32_16x16x32_bf16 v[40:43], v[76:79], v[184:187], v[40:43]
	v_mfma_f32_16x16x32_bf16 v[16:19], v[80:83], v[184:187], v[16:19]
	v_mfma_f32_16x16x32_bf16 v[232:235], v[84:87], v[184:187], v[232:235]
	v_mfma_f32_16x16x32_bf16 v[104:107], v[88:91], v[184:187], v[104:107]
	ds_read_b128 v[180:183], v75 offset:63488
	global_load_dwordx4 v[172:175], v67, s[92:93] offset:0
	s_waitcnt lgkmcnt(4)
	v_mfma_f32_16x16x32_bf16 v[44:47], v[76:79], v[192:195], v[44:47]
	v_mfma_f32_16x16x32_bf16 v[20:23], v[80:83], v[192:195], v[20:23]
	v_mfma_f32_16x16x32_bf16 v[236:239], v[84:87], v[192:195], v[236:239]
	v_mfma_f32_16x16x32_bf16 v[108:111], v[88:91], v[192:195], v[108:111]
	ds_read_b128 v[184:187], v212 offset:49152
	s_waitcnt lgkmcnt(4)
	v_mfma_f32_16x16x32_bf16 v[48:51], v[76:79], v[196:199], v[48:51]
	v_mfma_f32_16x16x32_bf16 v[0:3], v[80:83], v[196:199], v[0:3]
	v_mfma_f32_16x16x32_bf16 v[240:243], v[84:87], v[196:199], v[240:243]
	v_mfma_f32_16x16x32_bf16 v[112:115], v[88:91], v[196:199], v[112:115]
	ds_read_b128 v[192:195], v212 offset:51200
	s_waitcnt lgkmcnt(4)
	v_mfma_f32_16x16x32_bf16 v[52:55], v[76:79], v[200:203], v[52:55]
	v_mfma_f32_16x16x32_bf16 v[8:11], v[80:83], v[200:203], v[8:11]
	v_mfma_f32_16x16x32_bf16 v[248:251], v[84:87], v[200:203], v[248:251]
	v_mfma_f32_16x16x32_bf16 v[116:119], v[88:91], v[200:203], v[116:119]
	ds_read_b128 v[196:199], v212 offset:53248
	s_waitcnt lgkmcnt(4)
	v_mfma_f32_16x16x32_bf16 v[56:59], v[76:79], v[176:179], v[56:59]
	v_mfma_f32_16x16x32_bf16 v[24:27], v[80:83], v[176:179], v[24:27]
	v_mfma_f32_16x16x32_bf16 v[252:255], v[84:87], v[176:179], v[252:255]
	v_mfma_f32_16x16x32_bf16 v[120:123], v[88:91], v[176:179], v[120:123]
	ds_read_b128 v[200:203], v212 offset:55296
	s_waitcnt lgkmcnt(4)
	v_mfma_f32_16x16x32_bf16 v[60:63], v[76:79], v[180:183], v[60:63]
	v_mfma_f32_16x16x32_bf16 v[28:31], v[80:83], v[180:183], v[28:31]
	v_mfma_f32_16x16x32_bf16 v[92:95], v[84:87], v[180:183], v[92:95]
	v_mfma_f32_16x16x32_bf16 v[124:127], v[88:91], v[180:183], v[124:127]
	s_waitcnt vmcnt(16)
	s_barrier
	s_waitcnt vmcnt(8)
	ds_read_b128 v[176:179], v212 offset:57344
	global_load_dwordx4 v[76:79], v66, s[84:85] offset:1024
	s_waitcnt lgkmcnt(4)
	v_mfma_f32_16x16x32_bf16 v[32:35], v[140:143], v[184:187], v[32:35]
	v_mfma_f32_16x16x32_bf16 v[4:7], v[144:147], v[184:187], v[4:7]
	v_mfma_f32_16x16x32_bf16 v[188:191], v[148:151], v[184:187], v[188:191]
	v_mfma_f32_16x16x32_bf16 v[96:99], v[204:207], v[184:187], v[96:99]
	ds_read_b128 v[180:183], v212 offset:59392
	global_load_dwordx4 v[80:83], v67, s[84:85] offset:1024
	s_waitcnt lgkmcnt(4)
	v_mfma_f32_16x16x32_bf16 v[36:39], v[140:143], v[192:195], v[36:39]
	v_mfma_f32_16x16x32_bf16 v[12:15], v[144:147], v[192:195], v[12:15]
	v_mfma_f32_16x16x32_bf16 v[208:211], v[148:151], v[192:195], v[208:211]
	v_mfma_f32_16x16x32_bf16 v[100:103], v[204:207], v[192:195], v[100:103]
	ds_read_b128 v[184:187], v212 offset:61440
	global_load_dwordx4 v[84:87], v66, s[92:93] offset:1024
	s_waitcnt lgkmcnt(4)
	v_mfma_f32_16x16x32_bf16 v[40:43], v[140:143], v[196:199], v[40:43]
	v_mfma_f32_16x16x32_bf16 v[16:19], v[144:147], v[196:199], v[16:19]
	v_mfma_f32_16x16x32_bf16 v[232:235], v[148:151], v[196:199], v[232:235]
	v_mfma_f32_16x16x32_bf16 v[104:107], v[204:207], v[196:199], v[104:107]
	ds_read_b128 v[192:195], v212 offset:63488
	global_load_dwordx4 v[88:91], v67, s[92:93] offset:1024
	s_add_u32 s84, s84, 0x800
	s_addc_u32 s85, s85, 0
	s_add_u32 s92, s92, 0x800
	s_addc_u32 s93, s93, 0
	s_waitcnt lgkmcnt(4)
	v_mfma_f32_16x16x32_bf16 v[44:47], v[140:143], v[200:203], v[44:47]
	v_mfma_f32_16x16x32_bf16 v[20:23], v[144:147], v[200:203], v[20:23]
	v_mfma_f32_16x16x32_bf16 v[236:239], v[148:151], v[200:203], v[236:239]
	v_mfma_f32_16x16x32_bf16 v[108:111], v[204:207], v[200:203], v[108:111]
	ds_read_b128 v[196:199], v75 offset:0
	s_add_u32 m0, s88, 32768
	s_nop 0
	global_load_lds_dwordx4 v68, s[86:87]
	s_waitcnt lgkmcnt(4)
	v_mfma_f32_16x16x32_bf16 v[48:51], v[140:143], v[176:179], v[48:51]
	v_mfma_f32_16x16x32_bf16 v[0:3], v[144:147], v[176:179], v[0:3]
	v_mfma_f32_16x16x32_bf16 v[240:243], v[148:151], v[176:179], v[240:243]
	v_mfma_f32_16x16x32_bf16 v[112:115], v[204:207], v[176:179], v[112:115]
	ds_read_b128 v[200:203], v75 offset:2048
	s_add_u32 m0, s88, 36864
	s_nop 0
	global_load_lds_dwordx4 v69, s[86:87]
	s_waitcnt lgkmcnt(4)
	v_mfma_f32_16x16x32_bf16 v[52:55], v[140:143], v[180:183], v[52:55]
	v_mfma_f32_16x16x32_bf16 v[8:11], v[144:147], v[180:183], v[8:11]
	v_mfma_f32_16x16x32_bf16 v[248:251], v[148:151], v[180:183], v[248:251]
	v_mfma_f32_16x16x32_bf16 v[116:119], v[204:207], v[180:183], v[116:119]
	ds_read_b128 v[176:179], v75 offset:4096
	s_add_u32 m0, s88, 40960
	s_nop 0
	global_load_lds_dwordx4 v71, s[86:87]
	s_waitcnt lgkmcnt(4)
	v_mfma_f32_16x16x32_bf16 v[56:59], v[140:143], v[184:187], v[56:59]
	v_mfma_f32_16x16x32_bf16 v[24:27], v[144:147], v[184:187], v[24:27]
	v_mfma_f32_16x16x32_bf16 v[252:255], v[148:151], v[184:187], v[252:255]
	v_mfma_f32_16x16x32_bf16 v[120:123], v[204:207], v[184:187], v[120:123]
	ds_read_b128 v[180:183], v75 offset:6144
	s_add_u32 m0, s88, 45056
	s_nop 0
	global_load_lds_dwordx4 v74, s[86:87]
	s_add_u32 s86, s86, 128
	s_addc_u32 s87, s87, 0
	s_waitcnt lgkmcnt(4)
	v_mfma_f32_16x16x32_bf16 v[60:63], v[140:143], v[192:195], v[60:63]
	v_mfma_f32_16x16x32_bf16 v[28:31], v[144:147], v[192:195], v[28:31]
	v_mfma_f32_16x16x32_bf16 v[92:95], v[148:151], v[192:195], v[92:95]
	v_mfma_f32_16x16x32_bf16 v[124:127], v[204:207], v[192:195], v[124:127]
	s_waitcnt vmcnt(8)
	ds_read_b128 v[184:187], v75 offset:8192
	global_load_dwordx4 v[140:143], v66, s[84:85] offset:0
	s_waitcnt lgkmcnt(4)
	v_mfma_f32_16x16x32_bf16 v[32:35], v[160:163], v[196:199], v[32:35]
	v_mfma_f32_16x16x32_bf16 v[4:7], v[164:167], v[196:199], v[4:7]
	v_mfma_f32_16x16x32_bf16 v[188:191], v[168:171], v[196:199], v[188:191]
	v_mfma_f32_16x16x32_bf16 v[96:99], v[172:175], v[196:199], v[96:99]
	ds_read_b128 v[192:195], v75 offset:10240
	global_load_dwordx4 v[144:147], v67, s[84:85] offset:0
	s_waitcnt lgkmcnt(4)
	v_mfma_f32_16x16x32_bf16 v[36:39], v[160:163], v[200:203], v[36:39]
	v_mfma_f32_16x16x32_bf16 v[12:15], v[164:167], v[200:203], v[12:15]
	v_mfma_f32_16x16x32_bf16 v[208:211], v[168:171], v[200:203], v[208:211]
	v_mfma_f32_16x16x32_bf16 v[100:103], v[172:175], v[200:203], v[100:103]
	ds_read_b128 v[196:199], v75 offset:12288
	global_load_dwordx4 v[148:151], v66, s[92:93] offset:0
	s_waitcnt lgkmcnt(4)
	v_mfma_f32_16x16x32_bf16 v[40:43], v[160:163], v[176:179], v[40:43]
	v_mfma_f32_16x16x32_bf16 v[16:19], v[164:167], v[176:179], v[16:19]
	v_mfma_f32_16x16x32_bf16 v[232:235], v[168:171], v[176:179], v[232:235]
	v_mfma_f32_16x16x32_bf16 v[104:107], v[172:175], v[176:179], v[104:107]
	ds_read_b128 v[200:203], v75 offset:14336
	global_load_dwordx4 v[204:207], v67, s[92:93] offset:0
	s_waitcnt lgkmcnt(4)
	v_mfma_f32_16x16x32_bf16 v[44:47], v[160:163], v[180:183], v[44:47]
	v_mfma_f32_16x16x32_bf16 v[20:23], v[164:167], v[180:183], v[20:23]
	v_mfma_f32_16x16x32_bf16 v[236:239], v[168:171], v[180:183], v[236:239]
	v_mfma_f32_16x16x32_bf16 v[108:111], v[172:175], v[180:183], v[108:111]
	ds_read_b128 v[176:179], v212 offset:0
	s_waitcnt lgkmcnt(4)
	v_mfma_f32_16x16x32_bf16 v[48:51], v[160:163], v[184:187], v[48:51]
	v_mfma_f32_16x16x32_bf16 v[0:3], v[164:167], v[184:187], v[0:3]
	v_mfma_f32_16x16x32_bf16 v[240:243], v[168:171], v[184:187], v[240:243]
	v_mfma_f32_16x16x32_bf16 v[112:115], v[172:175], v[184:187], v[112:115]
	ds_read_b128 v[180:183], v212 offset:2048
	s_waitcnt lgkmcnt(4)
	v_mfma_f32_16x16x32_bf16 v[52:55], v[160:163], v[192:195], v[52:55]
	v_mfma_f32_16x16x32_bf16 v[8:11], v[164:167], v[192:195], v[8:11]
	v_mfma_f32_16x16x32_bf16 v[248:251], v[168:171], v[192:195], v[248:251]
	v_mfma_f32_16x16x32_bf16 v[116:119], v[172:175], v[192:195], v[116:119]
	ds_read_b128 v[184:187], v212 offset:4096
	s_waitcnt lgkmcnt(4)
	v_mfma_f32_16x16x32_bf16 v[56:59], v[160:163], v[196:199], v[56:59]
	v_mfma_f32_16x16x32_bf16 v[24:27], v[164:167], v[196:199], v[24:27]
	v_mfma_f32_16x16x32_bf16 v[252:255], v[168:171], v[196:199], v[252:255]
	v_mfma_f32_16x16x32_bf16 v[120:123], v[172:175], v[196:199], v[120:123]
	ds_read_b128 v[192:195], v212 offset:6144
	s_waitcnt lgkmcnt(4)
	v_mfma_f32_16x16x32_bf16 v[60:63], v[160:163], v[200:203], v[60:63]
	v_mfma_f32_16x16x32_bf16 v[28:31], v[164:167], v[200:203], v[28:31]
	v_mfma_f32_16x16x32_bf16 v[92:95], v[168:171], v[200:203], v[92:95]
	v_mfma_f32_16x16x32_bf16 v[124:127], v[172:175], v[200:203], v[124:127]
	s_waitcnt vmcnt(16)
	s_barrier
	s_waitcnt vmcnt(8)
	ds_read_b128 v[196:199], v212 offset:8192
	global_load_dwordx4 v[160:163], v66, s[84:85] offset:1024
	s_waitcnt lgkmcnt(4)
	v_mfma_f32_16x16x32_bf16 v[32:35], v[76:79], v[176:179], v[32:35]
	v_mfma_f32_16x16x32_bf16 v[4:7], v[80:83], v[176:179], v[4:7]
	v_mfma_f32_16x16x32_bf16 v[188:191], v[84:87], v[176:179], v[188:191]
	v_mfma_f32_16x16x32_bf16 v[96:99], v[88:91], v[176:179], v[96:99]
	ds_read_b128 v[200:203], v212 offset:10240
	global_load_dwordx4 v[164:167], v67, s[84:85] offset:1024
	s_waitcnt lgkmcnt(4)
	v_mfma_f32_16x16x32_bf16 v[36:39], v[76:79], v[180:183], v[36:39]
	v_mfma_f32_16x16x32_bf16 v[12:15], v[80:83], v[180:183], v[12:15]
	v_mfma_f32_16x16x32_bf16 v[208:211], v[84:87], v[180:183], v[208:211]
	v_mfma_f32_16x16x32_bf16 v[100:103], v[88:91], v[180:183], v[100:103]
	ds_read_b128 v[176:179], v212 offset:12288
	global_load_dwordx4 v[168:171], v66, s[92:93] offset:1024
	s_waitcnt lgkmcnt(4)
	v_mfma_f32_16x16x32_bf16 v[40:43], v[76:79], v[184:187], v[40:43]
	v_mfma_f32_16x16x32_bf16 v[16:19], v[80:83], v[184:187], v[16:19]
	v_mfma_f32_16x16x32_bf16 v[232:235], v[84:87], v[184:187], v[232:235]
	v_mfma_f32_16x16x32_bf16 v[104:107], v[88:91], v[184:187], v[104:107]
	ds_read_b128 v[180:183], v212 offset:14336
	global_load_dwordx4 v[172:175], v67, s[92:93] offset:1024
	s_add_u32 s84, s84, 0x800
	s_addc_u32 s85, s85, 0
	s_add_u32 s92, s92, 0x800
	s_addc_u32 s93, s93, 0
	s_waitcnt lgkmcnt(4)
	v_mfma_f32_16x16x32_bf16 v[44:47], v[76:79], v[192:195], v[44:47]
	v_mfma_f32_16x16x32_bf16 v[20:23], v[80:83], v[192:195], v[20:23]
	v_mfma_f32_16x16x32_bf16 v[236:239], v[84:87], v[192:195], v[236:239]
	v_mfma_f32_16x16x32_bf16 v[108:111], v[88:91], v[192:195], v[108:111]
	ds_read_b128 v[184:187], v75 offset:16384
	s_add_u32 m0, s88, 49152
	s_nop 0
	global_load_lds_dwordx4 v68, s[86:87]
	s_waitcnt lgkmcnt(4)
	v_mfma_f32_16x16x32_bf16 v[48:51], v[76:79], v[196:199], v[48:51]
	v_mfma_f32_16x16x32_bf16 v[0:3], v[80:83], v[196:199], v[0:3]
	v_mfma_f32_16x16x32_bf16 v[240:243], v[84:87], v[196:199], v[240:243]
	v_mfma_f32_16x16x32_bf16 v[112:115], v[88:91], v[196:199], v[112:115]
	ds_read_b128 v[192:195], v75 offset:18432
	s_add_u32 m0, s88, 53248
	s_nop 0
	global_load_lds_dwordx4 v69, s[86:87]
	s_waitcnt lgkmcnt(4)
	v_mfma_f32_16x16x32_bf16 v[52:55], v[76:79], v[200:203], v[52:55]
	v_mfma_f32_16x16x32_bf16 v[8:11], v[80:83], v[200:203], v[8:11]
	v_mfma_f32_16x16x32_bf16 v[248:251], v[84:87], v[200:203], v[248:251]
	v_mfma_f32_16x16x32_bf16 v[116:119], v[88:91], v[200:203], v[116:119]
	ds_read_b128 v[196:199], v75 offset:20480
	s_add_u32 m0, s88, 57344
	s_nop 0
	global_load_lds_dwordx4 v71, s[86:87]
	s_waitcnt lgkmcnt(4)
	v_mfma_f32_16x16x32_bf16 v[56:59], v[76:79], v[176:179], v[56:59]
	v_mfma_f32_16x16x32_bf16 v[24:27], v[80:83], v[176:179], v[24:27]
	v_mfma_f32_16x16x32_bf16 v[252:255], v[84:87], v[176:179], v[252:255]
	v_mfma_f32_16x16x32_bf16 v[120:123], v[88:91], v[176:179], v[120:123]
	ds_read_b128 v[200:203], v75 offset:22528
	s_add_u32 m0, s88, 61440
	s_nop 0
	global_load_lds_dwordx4 v74, s[86:87]
	s_add_u32 s86, s86, 128
	s_addc_u32 s87, s87, 0
	s_waitcnt lgkmcnt(4)
	v_mfma_f32_16x16x32_bf16 v[60:63], v[76:79], v[180:183], v[60:63]
	v_mfma_f32_16x16x32_bf16 v[28:31], v[80:83], v[180:183], v[28:31]
	v_mfma_f32_16x16x32_bf16 v[92:95], v[84:87], v[180:183], v[92:95]
	v_mfma_f32_16x16x32_bf16 v[124:127], v[88:91], v[180:183], v[124:127]
	s_waitcnt vmcnt(8)
	ds_read_b128 v[176:179], v75 offset:24576
	global_load_dwordx4 v[76:79], v66, s[84:85] offset:0
	s_waitcnt lgkmcnt(4)
	v_mfma_f32_16x16x32_bf16 v[32:35], v[140:143], v[184:187], v[32:35]
	v_mfma_f32_16x16x32_bf16 v[4:7], v[144:147], v[184:187], v[4:7]
	v_mfma_f32_16x16x32_bf16 v[188:191], v[148:151], v[184:187], v[188:191]
	v_mfma_f32_16x16x32_bf16 v[96:99], v[204:207], v[184:187], v[96:99]
	ds_read_b128 v[180:183], v75 offset:26624
	global_load_dwordx4 v[80:83], v67, s[84:85] offset:0
	s_waitcnt lgkmcnt(4)
	v_mfma_f32_16x16x32_bf16 v[36:39], v[140:143], v[192:195], v[36:39]
	v_mfma_f32_16x16x32_bf16 v[12:15], v[144:147], v[192:195], v[12:15]
	v_mfma_f32_16x16x32_bf16 v[208:211], v[148:151], v[192:195], v[208:211]
	v_mfma_f32_16x16x32_bf16 v[100:103], v[204:207], v[192:195], v[100:103]
	ds_read_b128 v[184:187], v75 offset:28672
	global_load_dwordx4 v[84:87], v66, s[92:93] offset:0
	s_waitcnt lgkmcnt(4)
	v_mfma_f32_16x16x32_bf16 v[40:43], v[140:143], v[196:199], v[40:43]
	v_mfma_f32_16x16x32_bf16 v[16:19], v[144:147], v[196:199], v[16:19]
	v_mfma_f32_16x16x32_bf16 v[232:235], v[148:151], v[196:199], v[232:235]
	v_mfma_f32_16x16x32_bf16 v[104:107], v[204:207], v[196:199], v[104:107]
	ds_read_b128 v[192:195], v75 offset:30720
	global_load_dwordx4 v[88:91], v67, s[92:93] offset:0
	s_waitcnt lgkmcnt(4)
	v_mfma_f32_16x16x32_bf16 v[44:47], v[140:143], v[200:203], v[44:47]
	v_mfma_f32_16x16x32_bf16 v[20:23], v[144:147], v[200:203], v[20:23]
	v_mfma_f32_16x16x32_bf16 v[236:239], v[148:151], v[200:203], v[236:239]
	v_mfma_f32_16x16x32_bf16 v[108:111], v[204:207], v[200:203], v[108:111]
	ds_read_b128 v[196:199], v212 offset:16384
	s_waitcnt lgkmcnt(4)
	v_mfma_f32_16x16x32_bf16 v[48:51], v[140:143], v[176:179], v[48:51]
	v_mfma_f32_16x16x32_bf16 v[0:3], v[144:147], v[176:179], v[0:3]
	v_mfma_f32_16x16x32_bf16 v[240:243], v[148:151], v[176:179], v[240:243]
	v_mfma_f32_16x16x32_bf16 v[112:115], v[204:207], v[176:179], v[112:115]
	ds_read_b128 v[200:203], v212 offset:18432
	s_waitcnt lgkmcnt(4)
	v_mfma_f32_16x16x32_bf16 v[52:55], v[140:143], v[180:183], v[52:55]
	v_mfma_f32_16x16x32_bf16 v[8:11], v[144:147], v[180:183], v[8:11]
	v_mfma_f32_16x16x32_bf16 v[248:251], v[148:151], v[180:183], v[248:251]
	v_mfma_f32_16x16x32_bf16 v[116:119], v[204:207], v[180:183], v[116:119]
	ds_read_b128 v[176:179], v212 offset:20480
	s_waitcnt lgkmcnt(4)
	v_mfma_f32_16x16x32_bf16 v[56:59], v[140:143], v[184:187], v[56:59]
	v_mfma_f32_16x16x32_bf16 v[24:27], v[144:147], v[184:187], v[24:27]
	v_mfma_f32_16x16x32_bf16 v[252:255], v[148:151], v[184:187], v[252:255]
	v_mfma_f32_16x16x32_bf16 v[120:123], v[204:207], v[184:187], v[120:123]
	ds_read_b128 v[180:183], v212 offset:22528
	s_waitcnt lgkmcnt(4)
	v_mfma_f32_16x16x32_bf16 v[60:63], v[140:143], v[192:195], v[60:63]
	v_mfma_f32_16x16x32_bf16 v[28:31], v[144:147], v[192:195], v[28:31]
	v_mfma_f32_16x16x32_bf16 v[92:95], v[148:151], v[192:195], v[92:95]
	v_mfma_f32_16x16x32_bf16 v[124:127], v[204:207], v[192:195], v[124:127]
	s_waitcnt vmcnt(16)
	s_barrier
	s_waitcnt vmcnt(8)
	ds_read_b128 v[184:187], v212 offset:24576
	global_load_dwordx4 v[140:143], v66, s[84:85] offset:1024
	s_waitcnt lgkmcnt(4)
	v_mfma_f32_16x16x32_bf16 v[32:35], v[160:163], v[196:199], v[32:35]
	v_mfma_f32_16x16x32_bf16 v[4:7], v[164:167], v[196:199], v[4:7]
	v_mfma_f32_16x16x32_bf16 v[188:191], v[168:171], v[196:199], v[188:191]
	v_mfma_f32_16x16x32_bf16 v[96:99], v[172:175], v[196:199], v[96:99]
	ds_read_b128 v[192:195], v212 offset:26624
	global_load_dwordx4 v[144:147], v67, s[84:85] offset:1024
	s_waitcnt lgkmcnt(4)
	v_mfma_f32_16x16x32_bf16 v[36:39], v[160:163], v[200:203], v[36:39]
	v_mfma_f32_16x16x32_bf16 v[12:15], v[164:167], v[200:203], v[12:15]
	v_mfma_f32_16x16x32_bf16 v[208:211], v[168:171], v[200:203], v[208:211]
	v_mfma_f32_16x16x32_bf16 v[100:103], v[172:175], v[200:203], v[100:103]
	ds_read_b128 v[196:199], v212 offset:28672
	global_load_dwordx4 v[148:151], v66, s[92:93] offset:1024
	s_waitcnt lgkmcnt(4)
	v_mfma_f32_16x16x32_bf16 v[40:43], v[160:163], v[176:179], v[40:43]
	v_mfma_f32_16x16x32_bf16 v[16:19], v[164:167], v[176:179], v[16:19]
	v_mfma_f32_16x16x32_bf16 v[232:235], v[168:171], v[176:179], v[232:235]
	v_mfma_f32_16x16x32_bf16 v[104:107], v[172:175], v[176:179], v[104:107]
	ds_read_b128 v[200:203], v212 offset:30720
	global_load_dwordx4 v[204:207], v67, s[92:93] offset:1024
	s_add_u32 s84, s84, 0x800
	s_addc_u32 s85, s85, 0
	s_add_u32 s92, s92, 0x800
	s_addc_u32 s93, s93, 0
	s_waitcnt lgkmcnt(4)
	v_mfma_f32_16x16x32_bf16 v[44:47], v[160:163], v[180:183], v[44:47]
	v_mfma_f32_16x16x32_bf16 v[20:23], v[164:167], v[180:183], v[20:23]
	v_mfma_f32_16x16x32_bf16 v[236:239], v[168:171], v[180:183], v[236:239]
	v_mfma_f32_16x16x32_bf16 v[108:111], v[172:175], v[180:183], v[108:111]
	ds_read_b128 v[176:179], v75 offset:32768
	s_add_u32 m0, s88, 0
	s_nop 0
	global_load_lds_dwordx4 v68, s[86:87]
	s_waitcnt lgkmcnt(4)
	v_mfma_f32_16x16x32_bf16 v[48:51], v[160:163], v[184:187], v[48:51]
	v_mfma_f32_16x16x32_bf16 v[0:3], v[164:167], v[184:187], v[0:3]
	v_mfma_f32_16x16x32_bf16 v[240:243], v[168:171], v[184:187], v[240:243]
	v_mfma_f32_16x16x32_bf16 v[112:115], v[172:175], v[184:187], v[112:115]
	ds_read_b128 v[180:183], v75 offset:34816
	s_add_u32 m0, s88, 4096
	s_nop 0
	global_load_lds_dwordx4 v69, s[86:87]
	s_waitcnt lgkmcnt(4)
	v_mfma_f32_16x16x32_bf16 v[52:55], v[160:163], v[192:195], v[52:55]
	v_mfma_f32_16x16x32_bf16 v[8:11], v[164:167], v[192:195], v[8:11]
	v_mfma_f32_16x16x32_bf16 v[248:251], v[168:171], v[192:195], v[248:251]
	v_mfma_f32_16x16x32_bf16 v[116:119], v[172:175], v[192:195], v[116:119]
	ds_read_b128 v[184:187], v75 offset:36864
	s_add_u32 m0, s88, 8192
	s_nop 0
	global_load_lds_dwordx4 v71, s[86:87]
	s_waitcnt lgkmcnt(4)
	v_mfma_f32_16x16x32_bf16 v[56:59], v[160:163], v[196:199], v[56:59]
	v_mfma_f32_16x16x32_bf16 v[24:27], v[164:167], v[196:199], v[24:27]
	v_mfma_f32_16x16x32_bf16 v[252:255], v[168:171], v[196:199], v[252:255]
	v_mfma_f32_16x16x32_bf16 v[120:123], v[172:175], v[196:199], v[120:123]
	ds_read_b128 v[192:195], v75 offset:38912
	s_add_u32 m0, s88, 12288
	s_nop 0
	global_load_lds_dwordx4 v74, s[86:87]
	s_add_u32 s86, s86, 128
	s_addc_u32 s87, s87, 0
	s_waitcnt lgkmcnt(4)
	v_mfma_f32_16x16x32_bf16 v[60:63], v[160:163], v[200:203], v[60:63]
	v_mfma_f32_16x16x32_bf16 v[28:31], v[164:167], v[200:203], v[28:31]
	v_mfma_f32_16x16x32_bf16 v[92:95], v[168:171], v[200:203], v[92:95]
	v_mfma_f32_16x16x32_bf16 v[124:127], v[172:175], v[200:203], v[124:127]
	s_waitcnt vmcnt(8)
	ds_read_b128 v[196:199], v75 offset:40960
	global_load_dwordx4 v[160:163], v66, s[84:85] offset:0
	s_waitcnt lgkmcnt(4)
	v_mfma_f32_16x16x32_bf16 v[32:35], v[76:79], v[176:179], v[32:35]
	v_mfma_f32_16x16x32_bf16 v[4:7], v[80:83], v[176:179], v[4:7]
	v_mfma_f32_16x16x32_bf16 v[188:191], v[84:87], v[176:179], v[188:191]
	v_mfma_f32_16x16x32_bf16 v[96:99], v[88:91], v[176:179], v[96:99]
	ds_read_b128 v[200:203], v75 offset:43008
	global_load_dwordx4 v[164:167], v67, s[84:85] offset:0
	s_waitcnt lgkmcnt(4)
	v_mfma_f32_16x16x32_bf16 v[36:39], v[76:79], v[180:183], v[36:39]
	v_mfma_f32_16x16x32_bf16 v[12:15], v[80:83], v[180:183], v[12:15]
	v_mfma_f32_16x16x32_bf16 v[208:211], v[84:87], v[180:183], v[208:211]
	v_mfma_f32_16x16x32_bf16 v[100:103], v[88:91], v[180:183], v[100:103]
	ds_read_b128 v[176:179], v75 offset:45056
	global_load_dwordx4 v[168:171], v66, s[92:93] offset:0
	s_waitcnt lgkmcnt(4)
	v_mfma_f32_16x16x32_bf16 v[40:43], v[76:79], v[184:187], v[40:43]
	v_mfma_f32_16x16x32_bf16 v[16:19], v[80:83], v[184:187], v[16:19]
	v_mfma_f32_16x16x32_bf16 v[232:235], v[84:87], v[184:187], v[232:235]
	v_mfma_f32_16x16x32_bf16 v[104:107], v[88:91], v[184:187], v[104:107]
	ds_read_b128 v[180:183], v75 offset:47104
	global_load_dwordx4 v[172:175], v67, s[92:93] offset:0
	s_waitcnt lgkmcnt(4)
	v_mfma_f32_16x16x32_bf16 v[44:47], v[76:79], v[192:195], v[44:47]
	v_mfma_f32_16x16x32_bf16 v[20:23], v[80:83], v[192:195], v[20:23]
	v_mfma_f32_16x16x32_bf16 v[236:239], v[84:87], v[192:195], v[236:239]
	v_mfma_f32_16x16x32_bf16 v[108:111], v[88:91], v[192:195], v[108:111]
	ds_read_b128 v[184:187], v212 offset:32768
	s_waitcnt lgkmcnt(4)
	v_mfma_f32_16x16x32_bf16 v[48:51], v[76:79], v[196:199], v[48:51]
	v_mfma_f32_16x16x32_bf16 v[0:3], v[80:83], v[196:199], v[0:3]
	v_mfma_f32_16x16x32_bf16 v[240:243], v[84:87], v[196:199], v[240:243]
	v_mfma_f32_16x16x32_bf16 v[112:115], v[88:91], v[196:199], v[112:115]
	ds_read_b128 v[192:195], v212 offset:34816
	s_waitcnt lgkmcnt(4)
	v_mfma_f32_16x16x32_bf16 v[52:55], v[76:79], v[200:203], v[52:55]
	v_mfma_f32_16x16x32_bf16 v[8:11], v[80:83], v[200:203], v[8:11]
	v_mfma_f32_16x16x32_bf16 v[248:251], v[84:87], v[200:203], v[248:251]
	v_mfma_f32_16x16x32_bf16 v[116:119], v[88:91], v[200:203], v[116:119]
	ds_read_b128 v[196:199], v212 offset:36864
	s_waitcnt lgkmcnt(4)
	v_mfma_f32_16x16x32_bf16 v[56:59], v[76:79], v[176:179], v[56:59]
	v_mfma_f32_16x16x32_bf16 v[24:27], v[80:83], v[176:179], v[24:27]
	v_mfma_f32_16x16x32_bf16 v[252:255], v[84:87], v[176:179], v[252:255]
	v_mfma_f32_16x16x32_bf16 v[120:123], v[88:91], v[176:179], v[120:123]
	ds_read_b128 v[200:203], v212 offset:38912
	s_waitcnt lgkmcnt(4)
	v_mfma_f32_16x16x32_bf16 v[60:63], v[76:79], v[180:183], v[60:63]
	v_mfma_f32_16x16x32_bf16 v[28:31], v[80:83], v[180:183], v[28:31]
	v_mfma_f32_16x16x32_bf16 v[92:95], v[84:87], v[180:183], v[92:95]
	v_mfma_f32_16x16x32_bf16 v[124:127], v[88:91], v[180:183], v[124:127]
	s_waitcnt vmcnt(16)
	s_barrier
	s_waitcnt vmcnt(8)
	ds_read_b128 v[176:179], v212 offset:40960
	global_load_dwordx4 v[76:79], v66, s[84:85] offset:1024
	s_waitcnt lgkmcnt(4)
	v_mfma_f32_16x16x32_bf16 v[32:35], v[140:143], v[184:187], v[32:35]
	v_mfma_f32_16x16x32_bf16 v[4:7], v[144:147], v[184:187], v[4:7]
	v_mfma_f32_16x16x32_bf16 v[188:191], v[148:151], v[184:187], v[188:191]
	v_mfma_f32_16x16x32_bf16 v[96:99], v[204:207], v[184:187], v[96:99]
	ds_read_b128 v[180:183], v212 offset:43008
	global_load_dwordx4 v[80:83], v67, s[84:85] offset:1024
	s_waitcnt lgkmcnt(4)
	v_mfma_f32_16x16x32_bf16 v[36:39], v[140:143], v[192:195], v[36:39]
	v_mfma_f32_16x16x32_bf16 v[12:15], v[144:147], v[192:195], v[12:15]
	v_mfma_f32_16x16x32_bf16 v[208:211], v[148:151], v[192:195], v[208:211]
	v_mfma_f32_16x16x32_bf16 v[100:103], v[204:207], v[192:195], v[100:103]
	ds_read_b128 v[184:187], v212 offset:45056
	global_load_dwordx4 v[84:87], v66, s[92:93] offset:1024
	s_waitcnt lgkmcnt(4)
	v_mfma_f32_16x16x32_bf16 v[40:43], v[140:143], v[196:199], v[40:43]
	v_mfma_f32_16x16x32_bf16 v[16:19], v[144:147], v[196:199], v[16:19]
	v_mfma_f32_16x16x32_bf16 v[232:235], v[148:151], v[196:199], v[232:235]
	v_mfma_f32_16x16x32_bf16 v[104:107], v[204:207], v[196:199], v[104:107]
	ds_read_b128 v[192:195], v212 offset:47104
	global_load_dwordx4 v[88:91], v67, s[92:93] offset:1024
	s_add_u32 s84, s84, 0x800
	s_addc_u32 s85, s85, 0
	s_add_u32 s92, s92, 0x800
	s_addc_u32 s93, s93, 0
	s_waitcnt lgkmcnt(4)
	v_mfma_f32_16x16x32_bf16 v[44:47], v[140:143], v[200:203], v[44:47]
	v_mfma_f32_16x16x32_bf16 v[20:23], v[144:147], v[200:203], v[20:23]
	v_mfma_f32_16x16x32_bf16 v[236:239], v[148:151], v[200:203], v[236:239]
	v_mfma_f32_16x16x32_bf16 v[108:111], v[204:207], v[200:203], v[108:111]
	ds_read_b128 v[196:199], v75 offset:49152
	s_add_u32 m0, s88, 16384
	s_nop 0
	global_load_lds_dwordx4 v68, s[86:87]
	s_waitcnt lgkmcnt(4)
	v_mfma_f32_16x16x32_bf16 v[48:51], v[140:143], v[176:179], v[48:51]
	v_mfma_f32_16x16x32_bf16 v[0:3], v[144:147], v[176:179], v[0:3]
	v_mfma_f32_16x16x32_bf16 v[240:243], v[148:151], v[176:179], v[240:243]
	v_mfma_f32_16x16x32_bf16 v[112:115], v[204:207], v[176:179], v[112:115]
	ds_read_b128 v[200:203], v75 offset:51200
	s_add_u32 m0, s88, 20480
	s_nop 0
	global_load_lds_dwordx4 v69, s[86:87]
	s_waitcnt lgkmcnt(4)
	v_mfma_f32_16x16x32_bf16 v[52:55], v[140:143], v[180:183], v[52:55]
	v_mfma_f32_16x16x32_bf16 v[8:11], v[144:147], v[180:183], v[8:11]
	v_mfma_f32_16x16x32_bf16 v[248:251], v[148:151], v[180:183], v[248:251]
	v_mfma_f32_16x16x32_bf16 v[116:119], v[204:207], v[180:183], v[116:119]
	ds_read_b128 v[176:179], v75 offset:53248
	s_add_u32 m0, s88, 24576
	s_nop 0
	global_load_lds_dwordx4 v71, s[86:87]
	s_waitcnt lgkmcnt(4)
	v_mfma_f32_16x16x32_bf16 v[56:59], v[140:143], v[184:187], v[56:59]
	v_mfma_f32_16x16x32_bf16 v[24:27], v[144:147], v[184:187], v[24:27]
	v_mfma_f32_16x16x32_bf16 v[252:255], v[148:151], v[184:187], v[252:255]
	v_mfma_f32_16x16x32_bf16 v[120:123], v[204:207], v[184:187], v[120:123]
	ds_read_b128 v[180:183], v75 offset:55296
	s_add_u32 m0, s88, 28672
	s_nop 0
	global_load_lds_dwordx4 v74, s[86:87]
	s_add_u32 s86, s86, 128
	s_addc_u32 s87, s87, 0
	s_waitcnt lgkmcnt(4)
	v_mfma_f32_16x16x32_bf16 v[60:63], v[140:143], v[192:195], v[60:63]
	v_mfma_f32_16x16x32_bf16 v[28:31], v[144:147], v[192:195], v[28:31]
	v_mfma_f32_16x16x32_bf16 v[92:95], v[148:151], v[192:195], v[92:95]
	v_mfma_f32_16x16x32_bf16 v[124:127], v[204:207], v[192:195], v[124:127]
	s_waitcnt vmcnt(8)
	ds_read_b128 v[184:187], v75 offset:57344
	global_load_dwordx4 v[140:143], v66, s[84:85] offset:0
	s_waitcnt lgkmcnt(4)
	v_mfma_f32_16x16x32_bf16 v[32:35], v[160:163], v[196:199], v[32:35]
	v_mfma_f32_16x16x32_bf16 v[4:7], v[164:167], v[196:199], v[4:7]
	v_mfma_f32_16x16x32_bf16 v[188:191], v[168:171], v[196:199], v[188:191]
	v_mfma_f32_16x16x32_bf16 v[96:99], v[172:175], v[196:199], v[96:99]
	ds_read_b128 v[192:195], v75 offset:59392
	global_load_dwordx4 v[144:147], v67, s[84:85] offset:0
	s_waitcnt lgkmcnt(4)
	v_mfma_f32_16x16x32_bf16 v[36:39], v[160:163], v[200:203], v[36:39]
	v_mfma_f32_16x16x32_bf16 v[12:15], v[164:167], v[200:203], v[12:15]
	v_mfma_f32_16x16x32_bf16 v[208:211], v[168:171], v[200:203], v[208:211]
	v_mfma_f32_16x16x32_bf16 v[100:103], v[172:175], v[200:203], v[100:103]
	ds_read_b128 v[196:199], v75 offset:61440
	global_load_dwordx4 v[148:151], v66, s[92:93] offset:0
	s_waitcnt lgkmcnt(4)
	v_mfma_f32_16x16x32_bf16 v[40:43], v[160:163], v[176:179], v[40:43]
	v_mfma_f32_16x16x32_bf16 v[16:19], v[164:167], v[176:179], v[16:19]
	v_mfma_f32_16x16x32_bf16 v[232:235], v[168:171], v[176:179], v[232:235]
	v_mfma_f32_16x16x32_bf16 v[104:107], v[172:175], v[176:179], v[104:107]
	ds_read_b128 v[200:203], v75 offset:63488
	global_load_dwordx4 v[204:207], v67, s[92:93] offset:0
	s_waitcnt lgkmcnt(4)
	v_mfma_f32_16x16x32_bf16 v[44:47], v[160:163], v[180:183], v[44:47]
	v_mfma_f32_16x16x32_bf16 v[20:23], v[164:167], v[180:183], v[20:23]
	v_mfma_f32_16x16x32_bf16 v[236:239], v[168:171], v[180:183], v[236:239]
	v_mfma_f32_16x16x32_bf16 v[108:111], v[172:175], v[180:183], v[108:111]
	ds_read_b128 v[176:179], v212 offset:49152
	s_waitcnt lgkmcnt(4)
	v_mfma_f32_16x16x32_bf16 v[48:51], v[160:163], v[184:187], v[48:51]
	v_mfma_f32_16x16x32_bf16 v[0:3], v[164:167], v[184:187], v[0:3]
	v_mfma_f32_16x16x32_bf16 v[240:243], v[168:171], v[184:187], v[240:243]
	v_mfma_f32_16x16x32_bf16 v[112:115], v[172:175], v[184:187], v[112:115]
	ds_read_b128 v[180:183], v212 offset:51200
	s_waitcnt lgkmcnt(4)
	v_mfma_f32_16x16x32_bf16 v[52:55], v[160:163], v[192:195], v[52:55]
	v_mfma_f32_16x16x32_bf16 v[8:11], v[164:167], v[192:195], v[8:11]
	v_mfma_f32_16x16x32_bf16 v[248:251], v[168:171], v[192:195], v[248:251]
	v_mfma_f32_16x16x32_bf16 v[116:119], v[172:175], v[192:195], v[116:119]
	ds_read_b128 v[184:187], v212 offset:53248
	s_waitcnt lgkmcnt(4)
	v_mfma_f32_16x16x32_bf16 v[56:59], v[160:163], v[196:199], v[56:59]
	v_mfma_f32_16x16x32_bf16 v[24:27], v[164:167], v[196:199], v[24:27]
	v_mfma_f32_16x16x32_bf16 v[252:255], v[168:171], v[196:199], v[252:255]
	v_mfma_f32_16x16x32_bf16 v[120:123], v[172:175], v[196:199], v[120:123]
	ds_read_b128 v[192:195], v212 offset:55296
	s_waitcnt lgkmcnt(4)
	v_mfma_f32_16x16x32_bf16 v[60:63], v[160:163], v[200:203], v[60:63]
	v_mfma_f32_16x16x32_bf16 v[28:31], v[164:167], v[200:203], v[28:31]
	v_mfma_f32_16x16x32_bf16 v[92:95], v[168:171], v[200:203], v[92:95]
	v_mfma_f32_16x16x32_bf16 v[124:127], v[172:175], v[200:203], v[124:127]
	s_waitcnt vmcnt(16)
	s_barrier
	s_waitcnt vmcnt(8)
	ds_read_b128 v[196:199], v212 offset:57344
	global_load_dwordx4 v[160:163], v66, s[84:85] offset:1024
	s_waitcnt lgkmcnt(4)
	v_mfma_f32_16x16x32_bf16 v[32:35], v[76:79], v[176:179], v[32:35]
	v_mfma_f32_16x16x32_bf16 v[4:7], v[80:83], v[176:179], v[4:7]
	v_mfma_f32_16x16x32_bf16 v[188:191], v[84:87], v[176:179], v[188:191]
	v_mfma_f32_16x16x32_bf16 v[96:99], v[88:91], v[176:179], v[96:99]
	ds_read_b128 v[200:203], v212 offset:59392
	global_load_dwordx4 v[164:167], v67, s[84:85] offset:1024
	s_waitcnt lgkmcnt(4)
	v_mfma_f32_16x16x32_bf16 v[36:39], v[76:79], v[180:183], v[36:39]
	v_mfma_f32_16x16x32_bf16 v[12:15], v[80:83], v[180:183], v[12:15]
	v_mfma_f32_16x16x32_bf16 v[208:211], v[84:87], v[180:183], v[208:211]
	v_mfma_f32_16x16x32_bf16 v[100:103], v[88:91], v[180:183], v[100:103]
	ds_read_b128 v[176:179], v212 offset:61440
	global_load_dwordx4 v[168:171], v66, s[92:93] offset:1024
	s_waitcnt lgkmcnt(4)
	v_mfma_f32_16x16x32_bf16 v[40:43], v[76:79], v[184:187], v[40:43]
	v_mfma_f32_16x16x32_bf16 v[16:19], v[80:83], v[184:187], v[16:19]
	v_mfma_f32_16x16x32_bf16 v[232:235], v[84:87], v[184:187], v[232:235]
	v_mfma_f32_16x16x32_bf16 v[104:107], v[88:91], v[184:187], v[104:107]
	ds_read_b128 v[180:183], v212 offset:63488
	global_load_dwordx4 v[172:175], v67, s[92:93] offset:1024
	s_add_u32 s84, s84, 0x800
	s_addc_u32 s85, s85, 0
	s_add_u32 s92, s92, 0x800
	s_addc_u32 s93, s93, 0
	s_waitcnt lgkmcnt(4)
	v_mfma_f32_16x16x32_bf16 v[44:47], v[76:79], v[192:195], v[44:47]
	v_mfma_f32_16x16x32_bf16 v[20:23], v[80:83], v[192:195], v[20:23]
	v_mfma_f32_16x16x32_bf16 v[236:239], v[84:87], v[192:195], v[236:239]
	v_mfma_f32_16x16x32_bf16 v[108:111], v[88:91], v[192:195], v[108:111]
	ds_read_b128 v[184:187], v75 offset:0
	s_add_u32 m0, s88, 32768
	s_nop 0
	global_load_lds_dwordx4 v68, s[86:87]
	s_waitcnt lgkmcnt(4)
	v_mfma_f32_16x16x32_bf16 v[48:51], v[76:79], v[196:199], v[48:51]
	v_mfma_f32_16x16x32_bf16 v[0:3], v[80:83], v[196:199], v[0:3]
	v_mfma_f32_16x16x32_bf16 v[240:243], v[84:87], v[196:199], v[240:243]
	v_mfma_f32_16x16x32_bf16 v[112:115], v[88:91], v[196:199], v[112:115]
	ds_read_b128 v[192:195], v75 offset:2048
	s_add_u32 m0, s88, 36864
	s_nop 0
	global_load_lds_dwordx4 v69, s[86:87]
	s_waitcnt lgkmcnt(4)
	v_mfma_f32_16x16x32_bf16 v[52:55], v[76:79], v[200:203], v[52:55]
	v_mfma_f32_16x16x32_bf16 v[8:11], v[80:83], v[200:203], v[8:11]
	v_mfma_f32_16x16x32_bf16 v[248:251], v[84:87], v[200:203], v[248:251]
	v_mfma_f32_16x16x32_bf16 v[116:119], v[88:91], v[200:203], v[116:119]
	ds_read_b128 v[196:199], v75 offset:4096
	s_add_u32 m0, s88, 40960
	s_nop 0
	global_load_lds_dwordx4 v71, s[86:87]
	s_waitcnt lgkmcnt(4)
	v_mfma_f32_16x16x32_bf16 v[56:59], v[76:79], v[176:179], v[56:59]
	v_mfma_f32_16x16x32_bf16 v[24:27], v[80:83], v[176:179], v[24:27]
	v_mfma_f32_16x16x32_bf16 v[252:255], v[84:87], v[176:179], v[252:255]
	v_mfma_f32_16x16x32_bf16 v[120:123], v[88:91], v[176:179], v[120:123]
	ds_read_b128 v[200:203], v75 offset:6144
	s_add_u32 m0, s88, 45056
	s_nop 0
	global_load_lds_dwordx4 v74, s[86:87]
	s_add_u32 s86, s86, 128
	s_addc_u32 s87, s87, 0
	s_waitcnt lgkmcnt(4)
	v_mfma_f32_16x16x32_bf16 v[60:63], v[76:79], v[180:183], v[60:63]
	v_mfma_f32_16x16x32_bf16 v[28:31], v[80:83], v[180:183], v[28:31]
	v_mfma_f32_16x16x32_bf16 v[92:95], v[84:87], v[180:183], v[92:95]
	v_mfma_f32_16x16x32_bf16 v[124:127], v[88:91], v[180:183], v[124:127]
	s_waitcnt vmcnt(8)
	ds_read_b128 v[176:179], v75 offset:8192
	global_load_dwordx4 v[76:79], v66, s[84:85] offset:0
	s_waitcnt lgkmcnt(4)
	v_mfma_f32_16x16x32_bf16 v[32:35], v[140:143], v[184:187], v[32:35]
	v_mfma_f32_16x16x32_bf16 v[4:7], v[144:147], v[184:187], v[4:7]
	v_mfma_f32_16x16x32_bf16 v[188:191], v[148:151], v[184:187], v[188:191]
	v_mfma_f32_16x16x32_bf16 v[96:99], v[204:207], v[184:187], v[96:99]
	ds_read_b128 v[180:183], v75 offset:10240
	global_load_dwordx4 v[80:83], v67, s[84:85] offset:0
	s_waitcnt lgkmcnt(4)
	v_mfma_f32_16x16x32_bf16 v[36:39], v[140:143], v[192:195], v[36:39]
	v_mfma_f32_16x16x32_bf16 v[12:15], v[144:147], v[192:195], v[12:15]
	v_mfma_f32_16x16x32_bf16 v[208:211], v[148:151], v[192:195], v[208:211]
	v_mfma_f32_16x16x32_bf16 v[100:103], v[204:207], v[192:195], v[100:103]
	ds_read_b128 v[184:187], v75 offset:12288
	global_load_dwordx4 v[84:87], v66, s[92:93] offset:0
	s_waitcnt lgkmcnt(4)
	v_mfma_f32_16x16x32_bf16 v[40:43], v[140:143], v[196:199], v[40:43]
	v_mfma_f32_16x16x32_bf16 v[16:19], v[144:147], v[196:199], v[16:19]
	v_mfma_f32_16x16x32_bf16 v[232:235], v[148:151], v[196:199], v[232:235]
	v_mfma_f32_16x16x32_bf16 v[104:107], v[204:207], v[196:199], v[104:107]
	ds_read_b128 v[192:195], v75 offset:14336
	global_load_dwordx4 v[88:91], v67, s[92:93] offset:0
	s_waitcnt lgkmcnt(4)
	v_mfma_f32_16x16x32_bf16 v[44:47], v[140:143], v[200:203], v[44:47]
	v_mfma_f32_16x16x32_bf16 v[20:23], v[144:147], v[200:203], v[20:23]
	v_mfma_f32_16x16x32_bf16 v[236:239], v[148:151], v[200:203], v[236:239]
	v_mfma_f32_16x16x32_bf16 v[108:111], v[204:207], v[200:203], v[108:111]
	ds_read_b128 v[196:199], v212 offset:0
	s_waitcnt lgkmcnt(4)
	v_mfma_f32_16x16x32_bf16 v[48:51], v[140:143], v[176:179], v[48:51]
	v_mfma_f32_16x16x32_bf16 v[0:3], v[144:147], v[176:179], v[0:3]
	v_mfma_f32_16x16x32_bf16 v[240:243], v[148:151], v[176:179], v[240:243]
	v_mfma_f32_16x16x32_bf16 v[112:115], v[204:207], v[176:179], v[112:115]
	ds_read_b128 v[200:203], v212 offset:2048
	s_waitcnt lgkmcnt(4)
	v_mfma_f32_16x16x32_bf16 v[52:55], v[140:143], v[180:183], v[52:55]
	v_mfma_f32_16x16x32_bf16 v[8:11], v[144:147], v[180:183], v[8:11]
	v_mfma_f32_16x16x32_bf16 v[248:251], v[148:151], v[180:183], v[248:251]
	v_mfma_f32_16x16x32_bf16 v[116:119], v[204:207], v[180:183], v[116:119]
	ds_read_b128 v[176:179], v212 offset:4096
	s_waitcnt lgkmcnt(4)
	v_mfma_f32_16x16x32_bf16 v[56:59], v[140:143], v[184:187], v[56:59]
	v_mfma_f32_16x16x32_bf16 v[24:27], v[144:147], v[184:187], v[24:27]
	v_mfma_f32_16x16x32_bf16 v[252:255], v[148:151], v[184:187], v[252:255]
	v_mfma_f32_16x16x32_bf16 v[120:123], v[204:207], v[184:187], v[120:123]
	ds_read_b128 v[180:183], v212 offset:6144
	s_waitcnt lgkmcnt(4)
	v_mfma_f32_16x16x32_bf16 v[60:63], v[140:143], v[192:195], v[60:63]
	v_mfma_f32_16x16x32_bf16 v[28:31], v[144:147], v[192:195], v[28:31]
	v_mfma_f32_16x16x32_bf16 v[92:95], v[148:151], v[192:195], v[92:95]
	v_mfma_f32_16x16x32_bf16 v[124:127], v[204:207], v[192:195], v[124:127]
	s_waitcnt vmcnt(16)
	s_barrier
	s_waitcnt vmcnt(8)
	ds_read_b128 v[184:187], v212 offset:8192
	global_load_dwordx4 v[140:143], v66, s[84:85] offset:1024
	s_waitcnt lgkmcnt(4)
	v_mfma_f32_16x16x32_bf16 v[32:35], v[160:163], v[196:199], v[32:35]
	v_mfma_f32_16x16x32_bf16 v[4:7], v[164:167], v[196:199], v[4:7]
	v_mfma_f32_16x16x32_bf16 v[188:191], v[168:171], v[196:199], v[188:191]
	v_mfma_f32_16x16x32_bf16 v[96:99], v[172:175], v[196:199], v[96:99]
	ds_read_b128 v[192:195], v212 offset:10240
	global_load_dwordx4 v[144:147], v67, s[84:85] offset:1024
	s_waitcnt lgkmcnt(4)
	v_mfma_f32_16x16x32_bf16 v[36:39], v[160:163], v[200:203], v[36:39]
	v_mfma_f32_16x16x32_bf16 v[12:15], v[164:167], v[200:203], v[12:15]
	v_mfma_f32_16x16x32_bf16 v[208:211], v[168:171], v[200:203], v[208:211]
	v_mfma_f32_16x16x32_bf16 v[100:103], v[172:175], v[200:203], v[100:103]
	ds_read_b128 v[196:199], v212 offset:12288
	global_load_dwordx4 v[148:151], v66, s[92:93] offset:1024
	s_waitcnt lgkmcnt(4)
	v_mfma_f32_16x16x32_bf16 v[40:43], v[160:163], v[176:179], v[40:43]
	v_mfma_f32_16x16x32_bf16 v[16:19], v[164:167], v[176:179], v[16:19]
	v_mfma_f32_16x16x32_bf16 v[232:235], v[168:171], v[176:179], v[232:235]
	v_mfma_f32_16x16x32_bf16 v[104:107], v[172:175], v[176:179], v[104:107]
	ds_read_b128 v[200:203], v212 offset:14336
	global_load_dwordx4 v[204:207], v67, s[92:93] offset:1024
	s_add_u32 s84, s84, 0x800
	s_addc_u32 s85, s85, 0
	s_add_u32 s92, s92, 0x800
	s_addc_u32 s93, s93, 0
	s_waitcnt lgkmcnt(4)
	v_mfma_f32_16x16x32_bf16 v[44:47], v[160:163], v[180:183], v[44:47]
	v_mfma_f32_16x16x32_bf16 v[20:23], v[164:167], v[180:183], v[20:23]
	v_mfma_f32_16x16x32_bf16 v[236:239], v[168:171], v[180:183], v[236:239]
	v_mfma_f32_16x16x32_bf16 v[108:111], v[172:175], v[180:183], v[108:111]
	ds_read_b128 v[176:179], v75 offset:16384
	s_add_u32 m0, s88, 49152
	s_nop 0
	global_load_lds_dwordx4 v68, s[86:87]
	s_waitcnt lgkmcnt(4)
	v_mfma_f32_16x16x32_bf16 v[48:51], v[160:163], v[184:187], v[48:51]
	v_mfma_f32_16x16x32_bf16 v[0:3], v[164:167], v[184:187], v[0:3]
	v_mfma_f32_16x16x32_bf16 v[240:243], v[168:171], v[184:187], v[240:243]
	v_mfma_f32_16x16x32_bf16 v[112:115], v[172:175], v[184:187], v[112:115]
	ds_read_b128 v[180:183], v75 offset:18432
	s_add_u32 m0, s88, 53248
	s_nop 0
	global_load_lds_dwordx4 v69, s[86:87]
	s_waitcnt lgkmcnt(4)
	v_mfma_f32_16x16x32_bf16 v[52:55], v[160:163], v[192:195], v[52:55]
	v_mfma_f32_16x16x32_bf16 v[8:11], v[164:167], v[192:195], v[8:11]
	v_mfma_f32_16x16x32_bf16 v[248:251], v[168:171], v[192:195], v[248:251]
	v_mfma_f32_16x16x32_bf16 v[116:119], v[172:175], v[192:195], v[116:119]
	ds_read_b128 v[184:187], v75 offset:20480
	s_add_u32 m0, s88, 57344
	s_nop 0
	global_load_lds_dwordx4 v71, s[86:87]
	s_waitcnt lgkmcnt(4)
	v_mfma_f32_16x16x32_bf16 v[56:59], v[160:163], v[196:199], v[56:59]
	v_mfma_f32_16x16x32_bf16 v[24:27], v[164:167], v[196:199], v[24:27]
	v_mfma_f32_16x16x32_bf16 v[252:255], v[168:171], v[196:199], v[252:255]
	v_mfma_f32_16x16x32_bf16 v[120:123], v[172:175], v[196:199], v[120:123]
	ds_read_b128 v[192:195], v75 offset:22528
	s_add_u32 m0, s88, 61440
	s_nop 0
	global_load_lds_dwordx4 v74, s[86:87]
	s_add_u32 s86, s86, 128
	s_addc_u32 s87, s87, 0
	s_waitcnt lgkmcnt(4)
	v_mfma_f32_16x16x32_bf16 v[60:63], v[160:163], v[200:203], v[60:63]
	v_mfma_f32_16x16x32_bf16 v[28:31], v[164:167], v[200:203], v[28:31]
	v_mfma_f32_16x16x32_bf16 v[92:95], v[168:171], v[200:203], v[92:95]
	v_mfma_f32_16x16x32_bf16 v[124:127], v[172:175], v[200:203], v[124:127]
	s_waitcnt vmcnt(8)
	ds_read_b128 v[196:199], v75 offset:24576
	global_load_dwordx4 v[160:163], v66, s[84:85] offset:0
	s_waitcnt lgkmcnt(4)
	v_mfma_f32_16x16x32_bf16 v[32:35], v[76:79], v[176:179], v[32:35]
	v_mfma_f32_16x16x32_bf16 v[4:7], v[80:83], v[176:179], v[4:7]
	v_mfma_f32_16x16x32_bf16 v[188:191], v[84:87], v[176:179], v[188:191]
	v_mfma_f32_16x16x32_bf16 v[96:99], v[88:91], v[176:179], v[96:99]
	ds_read_b128 v[200:203], v75 offset:26624
	global_load_dwordx4 v[164:167], v67, s[84:85] offset:0
	s_waitcnt lgkmcnt(4)
	v_mfma_f32_16x16x32_bf16 v[36:39], v[76:79], v[180:183], v[36:39]
	v_mfma_f32_16x16x32_bf16 v[12:15], v[80:83], v[180:183], v[12:15]
	v_mfma_f32_16x16x32_bf16 v[208:211], v[84:87], v[180:183], v[208:211]
	v_mfma_f32_16x16x32_bf16 v[100:103], v[88:91], v[180:183], v[100:103]
	ds_read_b128 v[176:179], v75 offset:28672
	global_load_dwordx4 v[168:171], v66, s[92:93] offset:0
	s_waitcnt lgkmcnt(4)
	v_mfma_f32_16x16x32_bf16 v[40:43], v[76:79], v[184:187], v[40:43]
	v_mfma_f32_16x16x32_bf16 v[16:19], v[80:83], v[184:187], v[16:19]
	v_mfma_f32_16x16x32_bf16 v[232:235], v[84:87], v[184:187], v[232:235]
	v_mfma_f32_16x16x32_bf16 v[104:107], v[88:91], v[184:187], v[104:107]
	ds_read_b128 v[180:183], v75 offset:30720
	global_load_dwordx4 v[172:175], v67, s[92:93] offset:0
	s_waitcnt lgkmcnt(4)
	v_mfma_f32_16x16x32_bf16 v[44:47], v[76:79], v[192:195], v[44:47]
	v_mfma_f32_16x16x32_bf16 v[20:23], v[80:83], v[192:195], v[20:23]
	v_mfma_f32_16x16x32_bf16 v[236:239], v[84:87], v[192:195], v[236:239]
	v_mfma_f32_16x16x32_bf16 v[108:111], v[88:91], v[192:195], v[108:111]
	ds_read_b128 v[184:187], v212 offset:16384
	s_waitcnt lgkmcnt(4)
	v_mfma_f32_16x16x32_bf16 v[48:51], v[76:79], v[196:199], v[48:51]
	v_mfma_f32_16x16x32_bf16 v[0:3], v[80:83], v[196:199], v[0:3]
	v_mfma_f32_16x16x32_bf16 v[240:243], v[84:87], v[196:199], v[240:243]
	v_mfma_f32_16x16x32_bf16 v[112:115], v[88:91], v[196:199], v[112:115]
	ds_read_b128 v[192:195], v212 offset:18432
	s_waitcnt lgkmcnt(4)
	v_mfma_f32_16x16x32_bf16 v[52:55], v[76:79], v[200:203], v[52:55]
	v_mfma_f32_16x16x32_bf16 v[8:11], v[80:83], v[200:203], v[8:11]
	v_mfma_f32_16x16x32_bf16 v[248:251], v[84:87], v[200:203], v[248:251]
	v_mfma_f32_16x16x32_bf16 v[116:119], v[88:91], v[200:203], v[116:119]
	ds_read_b128 v[196:199], v212 offset:20480
	s_waitcnt lgkmcnt(4)
	v_mfma_f32_16x16x32_bf16 v[56:59], v[76:79], v[176:179], v[56:59]
	v_mfma_f32_16x16x32_bf16 v[24:27], v[80:83], v[176:179], v[24:27]
	v_mfma_f32_16x16x32_bf16 v[252:255], v[84:87], v[176:179], v[252:255]
	v_mfma_f32_16x16x32_bf16 v[120:123], v[88:91], v[176:179], v[120:123]
	ds_read_b128 v[200:203], v212 offset:22528
	s_waitcnt lgkmcnt(4)
	v_mfma_f32_16x16x32_bf16 v[60:63], v[76:79], v[180:183], v[60:63]
	v_mfma_f32_16x16x32_bf16 v[28:31], v[80:83], v[180:183], v[28:31]
	v_mfma_f32_16x16x32_bf16 v[92:95], v[84:87], v[180:183], v[92:95]
	v_mfma_f32_16x16x32_bf16 v[124:127], v[88:91], v[180:183], v[124:127]
	s_waitcnt vmcnt(16)
	s_barrier
	s_waitcnt vmcnt(8)
	ds_read_b128 v[176:179], v212 offset:24576
	global_load_dwordx4 v[76:79], v66, s[84:85] offset:1024
	s_waitcnt lgkmcnt(4)
	v_mfma_f32_16x16x32_bf16 v[32:35], v[140:143], v[184:187], v[32:35]
	v_mfma_f32_16x16x32_bf16 v[4:7], v[144:147], v[184:187], v[4:7]
	v_mfma_f32_16x16x32_bf16 v[188:191], v[148:151], v[184:187], v[188:191]
	v_mfma_f32_16x16x32_bf16 v[96:99], v[204:207], v[184:187], v[96:99]
	ds_read_b128 v[180:183], v212 offset:26624
	global_load_dwordx4 v[80:83], v67, s[84:85] offset:1024
	s_waitcnt lgkmcnt(4)
	v_mfma_f32_16x16x32_bf16 v[36:39], v[140:143], v[192:195], v[36:39]
	v_mfma_f32_16x16x32_bf16 v[12:15], v[144:147], v[192:195], v[12:15]
	v_mfma_f32_16x16x32_bf16 v[208:211], v[148:151], v[192:195], v[208:211]
	v_mfma_f32_16x16x32_bf16 v[100:103], v[204:207], v[192:195], v[100:103]
	ds_read_b128 v[184:187], v212 offset:28672
	global_load_dwordx4 v[84:87], v66, s[92:93] offset:1024
	s_waitcnt lgkmcnt(4)
	v_mfma_f32_16x16x32_bf16 v[40:43], v[140:143], v[196:199], v[40:43]
	v_mfma_f32_16x16x32_bf16 v[16:19], v[144:147], v[196:199], v[16:19]
	v_mfma_f32_16x16x32_bf16 v[232:235], v[148:151], v[196:199], v[232:235]
	v_mfma_f32_16x16x32_bf16 v[104:107], v[204:207], v[196:199], v[104:107]
	ds_read_b128 v[192:195], v212 offset:30720
	global_load_dwordx4 v[88:91], v67, s[92:93] offset:1024
	s_add_u32 s84, s84, 0x800
	s_addc_u32 s85, s85, 0
	s_add_u32 s92, s92, 0x800
	s_addc_u32 s93, s93, 0
	s_waitcnt lgkmcnt(4)
	v_mfma_f32_16x16x32_bf16 v[44:47], v[140:143], v[200:203], v[44:47]
	v_mfma_f32_16x16x32_bf16 v[20:23], v[144:147], v[200:203], v[20:23]
	v_mfma_f32_16x16x32_bf16 v[236:239], v[148:151], v[200:203], v[236:239]
	v_mfma_f32_16x16x32_bf16 v[108:111], v[204:207], v[200:203], v[108:111]
	ds_read_b128 v[196:199], v75 offset:32768
	s_add_u32 m0, s88, 0
	s_nop 0
	global_load_lds_dwordx4 v68, s[86:87]
	s_waitcnt lgkmcnt(4)
	v_mfma_f32_16x16x32_bf16 v[48:51], v[140:143], v[176:179], v[48:51]
	v_mfma_f32_16x16x32_bf16 v[0:3], v[144:147], v[176:179], v[0:3]
	v_mfma_f32_16x16x32_bf16 v[240:243], v[148:151], v[176:179], v[240:243]
	v_mfma_f32_16x16x32_bf16 v[112:115], v[204:207], v[176:179], v[112:115]
	ds_read_b128 v[200:203], v75 offset:34816
	s_add_u32 m0, s88, 4096
	s_nop 0
	global_load_lds_dwordx4 v69, s[86:87]
	s_waitcnt lgkmcnt(4)
	v_mfma_f32_16x16x32_bf16 v[52:55], v[140:143], v[180:183], v[52:55]
	v_mfma_f32_16x16x32_bf16 v[8:11], v[144:147], v[180:183], v[8:11]
	v_mfma_f32_16x16x32_bf16 v[248:251], v[148:151], v[180:183], v[248:251]
	v_mfma_f32_16x16x32_bf16 v[116:119], v[204:207], v[180:183], v[116:119]
	ds_read_b128 v[176:179], v75 offset:36864
	s_add_u32 m0, s88, 8192
	s_nop 0
	global_load_lds_dwordx4 v71, s[86:87]
	s_waitcnt lgkmcnt(4)
	v_mfma_f32_16x16x32_bf16 v[56:59], v[140:143], v[184:187], v[56:59]
	v_mfma_f32_16x16x32_bf16 v[24:27], v[144:147], v[184:187], v[24:27]
	v_mfma_f32_16x16x32_bf16 v[252:255], v[148:151], v[184:187], v[252:255]
	v_mfma_f32_16x16x32_bf16 v[120:123], v[204:207], v[184:187], v[120:123]
	ds_read_b128 v[180:183], v75 offset:38912
	s_add_u32 m0, s88, 12288
	s_nop 0
	global_load_lds_dwordx4 v74, s[86:87]
	s_add_u32 s86, s86, 128
	s_addc_u32 s87, s87, 0
	s_waitcnt lgkmcnt(4)
	v_mfma_f32_16x16x32_bf16 v[60:63], v[140:143], v[192:195], v[60:63]
	v_mfma_f32_16x16x32_bf16 v[28:31], v[144:147], v[192:195], v[28:31]
	v_mfma_f32_16x16x32_bf16 v[92:95], v[148:151], v[192:195], v[92:95]
	v_mfma_f32_16x16x32_bf16 v[124:127], v[204:207], v[192:195], v[124:127]
	s_waitcnt vmcnt(8)
	ds_read_b128 v[184:187], v75 offset:40960
	global_load_dwordx4 v[140:143], v66, s[84:85] offset:0
	s_waitcnt lgkmcnt(4)
	v_mfma_f32_16x16x32_bf16 v[32:35], v[160:163], v[196:199], v[32:35]
	v_mfma_f32_16x16x32_bf16 v[4:7], v[164:167], v[196:199], v[4:7]
	v_mfma_f32_16x16x32_bf16 v[188:191], v[168:171], v[196:199], v[188:191]
	v_mfma_f32_16x16x32_bf16 v[96:99], v[172:175], v[196:199], v[96:99]
	ds_read_b128 v[192:195], v75 offset:43008
	global_load_dwordx4 v[144:147], v67, s[84:85] offset:0
	s_waitcnt lgkmcnt(4)
	v_mfma_f32_16x16x32_bf16 v[36:39], v[160:163], v[200:203], v[36:39]
	v_mfma_f32_16x16x32_bf16 v[12:15], v[164:167], v[200:203], v[12:15]
	v_mfma_f32_16x16x32_bf16 v[208:211], v[168:171], v[200:203], v[208:211]
	v_mfma_f32_16x16x32_bf16 v[100:103], v[172:175], v[200:203], v[100:103]
	ds_read_b128 v[196:199], v75 offset:45056
	global_load_dwordx4 v[148:151], v66, s[92:93] offset:0
	s_waitcnt lgkmcnt(4)
	v_mfma_f32_16x16x32_bf16 v[40:43], v[160:163], v[176:179], v[40:43]
	v_mfma_f32_16x16x32_bf16 v[16:19], v[164:167], v[176:179], v[16:19]
	v_mfma_f32_16x16x32_bf16 v[232:235], v[168:171], v[176:179], v[232:235]
	v_mfma_f32_16x16x32_bf16 v[104:107], v[172:175], v[176:179], v[104:107]
	ds_read_b128 v[200:203], v75 offset:47104
	global_load_dwordx4 v[204:207], v67, s[92:93] offset:0
	s_waitcnt lgkmcnt(4)
	v_mfma_f32_16x16x32_bf16 v[44:47], v[160:163], v[180:183], v[44:47]
	v_mfma_f32_16x16x32_bf16 v[20:23], v[164:167], v[180:183], v[20:23]
	v_mfma_f32_16x16x32_bf16 v[236:239], v[168:171], v[180:183], v[236:239]
	v_mfma_f32_16x16x32_bf16 v[108:111], v[172:175], v[180:183], v[108:111]
	ds_read_b128 v[176:179], v212 offset:32768
	s_waitcnt lgkmcnt(4)
	v_mfma_f32_16x16x32_bf16 v[48:51], v[160:163], v[184:187], v[48:51]
	v_mfma_f32_16x16x32_bf16 v[0:3], v[164:167], v[184:187], v[0:3]
	v_mfma_f32_16x16x32_bf16 v[240:243], v[168:171], v[184:187], v[240:243]
	v_mfma_f32_16x16x32_bf16 v[112:115], v[172:175], v[184:187], v[112:115]
	ds_read_b128 v[180:183], v212 offset:34816
	s_waitcnt lgkmcnt(4)
	v_mfma_f32_16x16x32_bf16 v[52:55], v[160:163], v[192:195], v[52:55]
	v_mfma_f32_16x16x32_bf16 v[8:11], v[164:167], v[192:195], v[8:11]
	v_mfma_f32_16x16x32_bf16 v[248:251], v[168:171], v[192:195], v[248:251]
	v_mfma_f32_16x16x32_bf16 v[116:119], v[172:175], v[192:195], v[116:119]
	ds_read_b128 v[184:187], v212 offset:36864
	s_waitcnt lgkmcnt(4)
	v_mfma_f32_16x16x32_bf16 v[56:59], v[160:163], v[196:199], v[56:59]
	v_mfma_f32_16x16x32_bf16 v[24:27], v[164:167], v[196:199], v[24:27]
	v_mfma_f32_16x16x32_bf16 v[252:255], v[168:171], v[196:199], v[252:255]
	v_mfma_f32_16x16x32_bf16 v[120:123], v[172:175], v[196:199], v[120:123]
	ds_read_b128 v[192:195], v212 offset:38912
	s_waitcnt lgkmcnt(4)
	v_mfma_f32_16x16x32_bf16 v[60:63], v[160:163], v[200:203], v[60:63]
	v_mfma_f32_16x16x32_bf16 v[28:31], v[164:167], v[200:203], v[28:31]
	v_mfma_f32_16x16x32_bf16 v[92:95], v[168:171], v[200:203], v[92:95]
	v_mfma_f32_16x16x32_bf16 v[124:127], v[172:175], v[200:203], v[124:127]
	s_waitcnt vmcnt(16)
	s_barrier
	s_waitcnt vmcnt(8)
	ds_read_b128 v[196:199], v212 offset:40960
	global_load_dwordx4 v[160:163], v66, s[84:85] offset:1024
	s_waitcnt lgkmcnt(4)
	v_mfma_f32_16x16x32_bf16 v[32:35], v[76:79], v[176:179], v[32:35]
	v_mfma_f32_16x16x32_bf16 v[4:7], v[80:83], v[176:179], v[4:7]
	v_mfma_f32_16x16x32_bf16 v[188:191], v[84:87], v[176:179], v[188:191]
	v_mfma_f32_16x16x32_bf16 v[96:99], v[88:91], v[176:179], v[96:99]
	ds_read_b128 v[200:203], v212 offset:43008
	global_load_dwordx4 v[164:167], v67, s[84:85] offset:1024
	s_waitcnt lgkmcnt(4)
	v_mfma_f32_16x16x32_bf16 v[36:39], v[76:79], v[180:183], v[36:39]
	v_mfma_f32_16x16x32_bf16 v[12:15], v[80:83], v[180:183], v[12:15]
	v_mfma_f32_16x16x32_bf16 v[208:211], v[84:87], v[180:183], v[208:211]
	v_mfma_f32_16x16x32_bf16 v[100:103], v[88:91], v[180:183], v[100:103]
	ds_read_b128 v[176:179], v212 offset:45056
	global_load_dwordx4 v[168:171], v66, s[92:93] offset:1024
	s_waitcnt lgkmcnt(4)
	v_mfma_f32_16x16x32_bf16 v[40:43], v[76:79], v[184:187], v[40:43]
	v_mfma_f32_16x16x32_bf16 v[16:19], v[80:83], v[184:187], v[16:19]
	v_mfma_f32_16x16x32_bf16 v[232:235], v[84:87], v[184:187], v[232:235]
	v_mfma_f32_16x16x32_bf16 v[104:107], v[88:91], v[184:187], v[104:107]
	ds_read_b128 v[180:183], v212 offset:47104
	global_load_dwordx4 v[172:175], v67, s[92:93] offset:1024
	s_add_u32 s84, s84, 0x800
	s_addc_u32 s85, s85, 0
	s_add_u32 s92, s92, 0x800
	s_addc_u32 s93, s93, 0
	s_waitcnt lgkmcnt(4)
	v_mfma_f32_16x16x32_bf16 v[44:47], v[76:79], v[192:195], v[44:47]
	v_mfma_f32_16x16x32_bf16 v[20:23], v[80:83], v[192:195], v[20:23]
	v_mfma_f32_16x16x32_bf16 v[236:239], v[84:87], v[192:195], v[236:239]
	v_mfma_f32_16x16x32_bf16 v[108:111], v[88:91], v[192:195], v[108:111]
	ds_read_b128 v[184:187], v75 offset:49152
	s_add_u32 m0, s88, 16384
	s_nop 0
	global_load_lds_dwordx4 v68, s[86:87]
	s_waitcnt lgkmcnt(4)
	v_mfma_f32_16x16x32_bf16 v[48:51], v[76:79], v[196:199], v[48:51]
	v_mfma_f32_16x16x32_bf16 v[0:3], v[80:83], v[196:199], v[0:3]
	v_mfma_f32_16x16x32_bf16 v[240:243], v[84:87], v[196:199], v[240:243]
	v_mfma_f32_16x16x32_bf16 v[112:115], v[88:91], v[196:199], v[112:115]
	ds_read_b128 v[192:195], v75 offset:51200
	s_add_u32 m0, s88, 20480
	s_nop 0
	global_load_lds_dwordx4 v69, s[86:87]
	s_waitcnt lgkmcnt(4)
	v_mfma_f32_16x16x32_bf16 v[52:55], v[76:79], v[200:203], v[52:55]
	v_mfma_f32_16x16x32_bf16 v[8:11], v[80:83], v[200:203], v[8:11]
	v_mfma_f32_16x16x32_bf16 v[248:251], v[84:87], v[200:203], v[248:251]
	v_mfma_f32_16x16x32_bf16 v[116:119], v[88:91], v[200:203], v[116:119]
	ds_read_b128 v[196:199], v75 offset:53248
	s_add_u32 m0, s88, 24576
	s_nop 0
	global_load_lds_dwordx4 v71, s[86:87]
	s_waitcnt lgkmcnt(4)
	v_mfma_f32_16x16x32_bf16 v[56:59], v[76:79], v[176:179], v[56:59]
	v_mfma_f32_16x16x32_bf16 v[24:27], v[80:83], v[176:179], v[24:27]
	v_mfma_f32_16x16x32_bf16 v[252:255], v[84:87], v[176:179], v[252:255]
	v_mfma_f32_16x16x32_bf16 v[120:123], v[88:91], v[176:179], v[120:123]
	ds_read_b128 v[200:203], v75 offset:55296
	s_add_u32 m0, s88, 28672
	s_nop 0
	global_load_lds_dwordx4 v74, s[86:87]
	s_add_u32 s86, s86, 128
	s_addc_u32 s87, s87, 0
	s_waitcnt lgkmcnt(4)
	v_mfma_f32_16x16x32_bf16 v[60:63], v[76:79], v[180:183], v[60:63]
	v_mfma_f32_16x16x32_bf16 v[28:31], v[80:83], v[180:183], v[28:31]
	v_mfma_f32_16x16x32_bf16 v[92:95], v[84:87], v[180:183], v[92:95]
	v_mfma_f32_16x16x32_bf16 v[124:127], v[88:91], v[180:183], v[124:127]
	s_waitcnt vmcnt(8)
	ds_read_b128 v[176:179], v75 offset:57344
	global_load_dwordx4 v[76:79], v66, s[84:85] offset:0
	s_waitcnt lgkmcnt(4)
	v_mfma_f32_16x16x32_bf16 v[32:35], v[140:143], v[184:187], v[32:35]
	v_mfma_f32_16x16x32_bf16 v[4:7], v[144:147], v[184:187], v[4:7]
	v_mfma_f32_16x16x32_bf16 v[188:191], v[148:151], v[184:187], v[188:191]
	v_mfma_f32_16x16x32_bf16 v[96:99], v[204:207], v[184:187], v[96:99]
	ds_read_b128 v[180:183], v75 offset:59392
	global_load_dwordx4 v[80:83], v67, s[84:85] offset:0
	s_waitcnt lgkmcnt(4)
	v_mfma_f32_16x16x32_bf16 v[36:39], v[140:143], v[192:195], v[36:39]
	v_mfma_f32_16x16x32_bf16 v[12:15], v[144:147], v[192:195], v[12:15]
	v_mfma_f32_16x16x32_bf16 v[208:211], v[148:151], v[192:195], v[208:211]
	v_mfma_f32_16x16x32_bf16 v[100:103], v[204:207], v[192:195], v[100:103]
	ds_read_b128 v[184:187], v75 offset:61440
	global_load_dwordx4 v[84:87], v66, s[92:93] offset:0
	s_waitcnt lgkmcnt(4)
	v_mfma_f32_16x16x32_bf16 v[40:43], v[140:143], v[196:199], v[40:43]
	v_mfma_f32_16x16x32_bf16 v[16:19], v[144:147], v[196:199], v[16:19]
	v_mfma_f32_16x16x32_bf16 v[232:235], v[148:151], v[196:199], v[232:235]
	v_mfma_f32_16x16x32_bf16 v[104:107], v[204:207], v[196:199], v[104:107]
	ds_read_b128 v[192:195], v75 offset:63488
	global_load_dwordx4 v[88:91], v67, s[92:93] offset:0
	s_waitcnt lgkmcnt(4)
	v_mfma_f32_16x16x32_bf16 v[44:47], v[140:143], v[200:203], v[44:47]
	v_mfma_f32_16x16x32_bf16 v[20:23], v[144:147], v[200:203], v[20:23]
	v_mfma_f32_16x16x32_bf16 v[236:239], v[148:151], v[200:203], v[236:239]
	v_mfma_f32_16x16x32_bf16 v[108:111], v[204:207], v[200:203], v[108:111]
	ds_read_b128 v[196:199], v212 offset:49152
	s_waitcnt lgkmcnt(4)
	v_mfma_f32_16x16x32_bf16 v[48:51], v[140:143], v[176:179], v[48:51]
	v_mfma_f32_16x16x32_bf16 v[0:3], v[144:147], v[176:179], v[0:3]
	v_mfma_f32_16x16x32_bf16 v[240:243], v[148:151], v[176:179], v[240:243]
	v_mfma_f32_16x16x32_bf16 v[112:115], v[204:207], v[176:179], v[112:115]
	ds_read_b128 v[200:203], v212 offset:51200
	s_waitcnt lgkmcnt(4)
	v_mfma_f32_16x16x32_bf16 v[52:55], v[140:143], v[180:183], v[52:55]
	v_mfma_f32_16x16x32_bf16 v[8:11], v[144:147], v[180:183], v[8:11]
	v_mfma_f32_16x16x32_bf16 v[248:251], v[148:151], v[180:183], v[248:251]
	v_mfma_f32_16x16x32_bf16 v[116:119], v[204:207], v[180:183], v[116:119]
	ds_read_b128 v[176:179], v212 offset:53248
	s_waitcnt lgkmcnt(4)
	v_mfma_f32_16x16x32_bf16 v[56:59], v[140:143], v[184:187], v[56:59]
	v_mfma_f32_16x16x32_bf16 v[24:27], v[144:147], v[184:187], v[24:27]
	v_mfma_f32_16x16x32_bf16 v[252:255], v[148:151], v[184:187], v[252:255]
	v_mfma_f32_16x16x32_bf16 v[120:123], v[204:207], v[184:187], v[120:123]
	ds_read_b128 v[180:183], v212 offset:55296
	s_waitcnt lgkmcnt(4)
	v_mfma_f32_16x16x32_bf16 v[60:63], v[140:143], v[192:195], v[60:63]
	v_mfma_f32_16x16x32_bf16 v[28:31], v[144:147], v[192:195], v[28:31]
	v_mfma_f32_16x16x32_bf16 v[92:95], v[148:151], v[192:195], v[92:95]
	v_mfma_f32_16x16x32_bf16 v[124:127], v[204:207], v[192:195], v[124:127]
	s_waitcnt vmcnt(16)
	s_barrier
	s_waitcnt vmcnt(8)
	ds_read_b128 v[184:187], v212 offset:57344
	global_load_dwordx4 v[140:143], v66, s[84:85] offset:1024
	s_waitcnt lgkmcnt(4)
	v_mfma_f32_16x16x32_bf16 v[32:35], v[160:163], v[196:199], v[32:35]
	v_mfma_f32_16x16x32_bf16 v[4:7], v[164:167], v[196:199], v[4:7]
	v_mfma_f32_16x16x32_bf16 v[188:191], v[168:171], v[196:199], v[188:191]
	v_mfma_f32_16x16x32_bf16 v[96:99], v[172:175], v[196:199], v[96:99]
	ds_read_b128 v[192:195], v212 offset:59392
	global_load_dwordx4 v[144:147], v67, s[84:85] offset:1024
	s_waitcnt lgkmcnt(4)
	v_mfma_f32_16x16x32_bf16 v[36:39], v[160:163], v[200:203], v[36:39]
	v_mfma_f32_16x16x32_bf16 v[12:15], v[164:167], v[200:203], v[12:15]
	v_mfma_f32_16x16x32_bf16 v[208:211], v[168:171], v[200:203], v[208:211]
	v_mfma_f32_16x16x32_bf16 v[100:103], v[172:175], v[200:203], v[100:103]
	ds_read_b128 v[196:199], v212 offset:61440
	global_load_dwordx4 v[148:151], v66, s[92:93] offset:1024
	s_waitcnt lgkmcnt(4)
	v_mfma_f32_16x16x32_bf16 v[40:43], v[160:163], v[176:179], v[40:43]
	v_mfma_f32_16x16x32_bf16 v[16:19], v[164:167], v[176:179], v[16:19]
	v_mfma_f32_16x16x32_bf16 v[232:235], v[168:171], v[176:179], v[232:235]
	v_mfma_f32_16x16x32_bf16 v[104:107], v[172:175], v[176:179], v[104:107]
	ds_read_b128 v[200:203], v212 offset:63488
	global_load_dwordx4 v[204:207], v67, s[92:93] offset:1024
	s_add_u32 s84, s84, 0x800
	s_addc_u32 s85, s85, 0
	s_add_u32 s92, s92, 0x800
	s_addc_u32 s93, s93, 0
	s_waitcnt lgkmcnt(4)
	v_mfma_f32_16x16x32_bf16 v[44:47], v[160:163], v[180:183], v[44:47]
	v_mfma_f32_16x16x32_bf16 v[20:23], v[164:167], v[180:183], v[20:23]
	v_mfma_f32_16x16x32_bf16 v[236:239], v[168:171], v[180:183], v[236:239]
	v_mfma_f32_16x16x32_bf16 v[108:111], v[172:175], v[180:183], v[108:111]
	ds_read_b128 v[176:179], v75 offset:0
	s_add_u32 m0, s88, 32768
	s_nop 0
	global_load_lds_dwordx4 v68, s[86:87]
	s_waitcnt lgkmcnt(4)
	v_mfma_f32_16x16x32_bf16 v[48:51], v[160:163], v[184:187], v[48:51]
	v_mfma_f32_16x16x32_bf16 v[0:3], v[164:167], v[184:187], v[0:3]
	v_mfma_f32_16x16x32_bf16 v[240:243], v[168:171], v[184:187], v[240:243]
	v_mfma_f32_16x16x32_bf16 v[112:115], v[172:175], v[184:187], v[112:115]
	ds_read_b128 v[180:183], v75 offset:2048
	s_add_u32 m0, s88, 36864
	s_nop 0
	global_load_lds_dwordx4 v69, s[86:87]
	s_waitcnt lgkmcnt(4)
	v_mfma_f32_16x16x32_bf16 v[52:55], v[160:163], v[192:195], v[52:55]
	v_mfma_f32_16x16x32_bf16 v[8:11], v[164:167], v[192:195], v[8:11]
	v_mfma_f32_16x16x32_bf16 v[248:251], v[168:171], v[192:195], v[248:251]
	v_mfma_f32_16x16x32_bf16 v[116:119], v[172:175], v[192:195], v[116:119]
	ds_read_b128 v[184:187], v75 offset:4096
	s_add_u32 m0, s88, 40960
	s_nop 0
	global_load_lds_dwordx4 v71, s[86:87]
	s_waitcnt lgkmcnt(4)
	v_mfma_f32_16x16x32_bf16 v[56:59], v[160:163], v[196:199], v[56:59]
	v_mfma_f32_16x16x32_bf16 v[24:27], v[164:167], v[196:199], v[24:27]
	v_mfma_f32_16x16x32_bf16 v[252:255], v[168:171], v[196:199], v[252:255]
	v_mfma_f32_16x16x32_bf16 v[120:123], v[172:175], v[196:199], v[120:123]
	ds_read_b128 v[192:195], v75 offset:6144
	s_add_u32 m0, s88, 45056
	s_nop 0
	global_load_lds_dwordx4 v74, s[86:87]
	s_add_u32 s86, s86, 128
	s_addc_u32 s87, s87, 0
	s_waitcnt lgkmcnt(4)
	v_mfma_f32_16x16x32_bf16 v[60:63], v[160:163], v[200:203], v[60:63]
	v_mfma_f32_16x16x32_bf16 v[28:31], v[164:167], v[200:203], v[28:31]
	v_mfma_f32_16x16x32_bf16 v[92:95], v[168:171], v[200:203], v[92:95]
	v_mfma_f32_16x16x32_bf16 v[124:127], v[172:175], v[200:203], v[124:127]
	s_waitcnt vmcnt(8)
	ds_read_b128 v[196:199], v75 offset:8192
	global_load_dwordx4 v[160:163], v66, s[84:85] offset:0
	s_waitcnt lgkmcnt(4)
	v_mfma_f32_16x16x32_bf16 v[32:35], v[76:79], v[176:179], v[32:35]
	v_mfma_f32_16x16x32_bf16 v[4:7], v[80:83], v[176:179], v[4:7]
	v_mfma_f32_16x16x32_bf16 v[188:191], v[84:87], v[176:179], v[188:191]
	v_mfma_f32_16x16x32_bf16 v[96:99], v[88:91], v[176:179], v[96:99]
	ds_read_b128 v[200:203], v75 offset:10240
	global_load_dwordx4 v[164:167], v67, s[84:85] offset:0
	s_waitcnt lgkmcnt(4)
	v_mfma_f32_16x16x32_bf16 v[36:39], v[76:79], v[180:183], v[36:39]
	v_mfma_f32_16x16x32_bf16 v[12:15], v[80:83], v[180:183], v[12:15]
	v_mfma_f32_16x16x32_bf16 v[208:211], v[84:87], v[180:183], v[208:211]
	v_mfma_f32_16x16x32_bf16 v[100:103], v[88:91], v[180:183], v[100:103]
	ds_read_b128 v[176:179], v75 offset:12288
	global_load_dwordx4 v[168:171], v66, s[92:93] offset:0
	s_waitcnt lgkmcnt(4)
	v_mfma_f32_16x16x32_bf16 v[40:43], v[76:79], v[184:187], v[40:43]
	v_mfma_f32_16x16x32_bf16 v[16:19], v[80:83], v[184:187], v[16:19]
	v_mfma_f32_16x16x32_bf16 v[232:235], v[84:87], v[184:187], v[232:235]
	v_mfma_f32_16x16x32_bf16 v[104:107], v[88:91], v[184:187], v[104:107]
	ds_read_b128 v[180:183], v75 offset:14336
	global_load_dwordx4 v[172:175], v67, s[92:93] offset:0
	s_waitcnt lgkmcnt(4)
	v_mfma_f32_16x16x32_bf16 v[44:47], v[76:79], v[192:195], v[44:47]
	v_mfma_f32_16x16x32_bf16 v[20:23], v[80:83], v[192:195], v[20:23]
	v_mfma_f32_16x16x32_bf16 v[236:239], v[84:87], v[192:195], v[236:239]
	v_mfma_f32_16x16x32_bf16 v[108:111], v[88:91], v[192:195], v[108:111]
	ds_read_b128 v[184:187], v212 offset:0
	s_waitcnt lgkmcnt(4)
	v_mfma_f32_16x16x32_bf16 v[48:51], v[76:79], v[196:199], v[48:51]
	v_mfma_f32_16x16x32_bf16 v[0:3], v[80:83], v[196:199], v[0:3]
	v_mfma_f32_16x16x32_bf16 v[240:243], v[84:87], v[196:199], v[240:243]
	v_mfma_f32_16x16x32_bf16 v[112:115], v[88:91], v[196:199], v[112:115]
	ds_read_b128 v[192:195], v212 offset:2048
	s_waitcnt lgkmcnt(4)
	v_mfma_f32_16x16x32_bf16 v[52:55], v[76:79], v[200:203], v[52:55]
	v_mfma_f32_16x16x32_bf16 v[8:11], v[80:83], v[200:203], v[8:11]
	v_mfma_f32_16x16x32_bf16 v[248:251], v[84:87], v[200:203], v[248:251]
	v_mfma_f32_16x16x32_bf16 v[116:119], v[88:91], v[200:203], v[116:119]
	ds_read_b128 v[196:199], v212 offset:4096
	s_waitcnt lgkmcnt(4)
	v_mfma_f32_16x16x32_bf16 v[56:59], v[76:79], v[176:179], v[56:59]
	v_mfma_f32_16x16x32_bf16 v[24:27], v[80:83], v[176:179], v[24:27]
	v_mfma_f32_16x16x32_bf16 v[252:255], v[84:87], v[176:179], v[252:255]
	v_mfma_f32_16x16x32_bf16 v[120:123], v[88:91], v[176:179], v[120:123]
	ds_read_b128 v[200:203], v212 offset:6144
	s_waitcnt lgkmcnt(4)
	v_mfma_f32_16x16x32_bf16 v[60:63], v[76:79], v[180:183], v[60:63]
	v_mfma_f32_16x16x32_bf16 v[28:31], v[80:83], v[180:183], v[28:31]
	v_mfma_f32_16x16x32_bf16 v[92:95], v[84:87], v[180:183], v[92:95]
	v_mfma_f32_16x16x32_bf16 v[124:127], v[88:91], v[180:183], v[124:127]
	s_waitcnt vmcnt(16)
	s_barrier
	s_waitcnt vmcnt(8)
	ds_read_b128 v[176:179], v212 offset:8192
	global_load_dwordx4 v[76:79], v66, s[84:85] offset:1024
	s_waitcnt lgkmcnt(4)
	v_mfma_f32_16x16x32_bf16 v[32:35], v[140:143], v[184:187], v[32:35]
	v_mfma_f32_16x16x32_bf16 v[4:7], v[144:147], v[184:187], v[4:7]
	v_mfma_f32_16x16x32_bf16 v[188:191], v[148:151], v[184:187], v[188:191]
	v_mfma_f32_16x16x32_bf16 v[96:99], v[204:207], v[184:187], v[96:99]
	ds_read_b128 v[180:183], v212 offset:10240
	global_load_dwordx4 v[80:83], v67, s[84:85] offset:1024
	s_waitcnt lgkmcnt(4)
	v_mfma_f32_16x16x32_bf16 v[36:39], v[140:143], v[192:195], v[36:39]
	v_mfma_f32_16x16x32_bf16 v[12:15], v[144:147], v[192:195], v[12:15]
	v_mfma_f32_16x16x32_bf16 v[208:211], v[148:151], v[192:195], v[208:211]
	v_mfma_f32_16x16x32_bf16 v[100:103], v[204:207], v[192:195], v[100:103]
	ds_read_b128 v[184:187], v212 offset:12288
	global_load_dwordx4 v[84:87], v66, s[92:93] offset:1024
	s_waitcnt lgkmcnt(4)
	v_mfma_f32_16x16x32_bf16 v[40:43], v[140:143], v[196:199], v[40:43]
	v_mfma_f32_16x16x32_bf16 v[16:19], v[144:147], v[196:199], v[16:19]
	v_mfma_f32_16x16x32_bf16 v[232:235], v[148:151], v[196:199], v[232:235]
	v_mfma_f32_16x16x32_bf16 v[104:107], v[204:207], v[196:199], v[104:107]
	ds_read_b128 v[192:195], v212 offset:14336
	global_load_dwordx4 v[88:91], v67, s[92:93] offset:1024
	s_add_u32 s84, s84, 0x800
	s_addc_u32 s85, s85, 0
	s_add_u32 s92, s92, 0x800
	s_addc_u32 s93, s93, 0
	s_waitcnt lgkmcnt(4)
	v_mfma_f32_16x16x32_bf16 v[44:47], v[140:143], v[200:203], v[44:47]
	v_mfma_f32_16x16x32_bf16 v[20:23], v[144:147], v[200:203], v[20:23]
	v_mfma_f32_16x16x32_bf16 v[236:239], v[148:151], v[200:203], v[236:239]
	v_mfma_f32_16x16x32_bf16 v[108:111], v[204:207], v[200:203], v[108:111]
	ds_read_b128 v[196:199], v75 offset:16384
	s_add_u32 m0, s88, 49152
	s_nop 0
	global_load_lds_dwordx4 v68, s[86:87]
	s_waitcnt lgkmcnt(4)
	v_mfma_f32_16x16x32_bf16 v[48:51], v[140:143], v[176:179], v[48:51]
	v_mfma_f32_16x16x32_bf16 v[0:3], v[144:147], v[176:179], v[0:3]
	v_mfma_f32_16x16x32_bf16 v[240:243], v[148:151], v[176:179], v[240:243]
	v_mfma_f32_16x16x32_bf16 v[112:115], v[204:207], v[176:179], v[112:115]
	ds_read_b128 v[200:203], v75 offset:18432
	s_add_u32 m0, s88, 53248
	s_nop 0
	global_load_lds_dwordx4 v69, s[86:87]
	s_waitcnt lgkmcnt(4)
	v_mfma_f32_16x16x32_bf16 v[52:55], v[140:143], v[180:183], v[52:55]
	v_mfma_f32_16x16x32_bf16 v[8:11], v[144:147], v[180:183], v[8:11]
	v_mfma_f32_16x16x32_bf16 v[248:251], v[148:151], v[180:183], v[248:251]
	v_mfma_f32_16x16x32_bf16 v[116:119], v[204:207], v[180:183], v[116:119]
	ds_read_b128 v[176:179], v75 offset:20480
	s_add_u32 m0, s88, 57344
	s_nop 0
	global_load_lds_dwordx4 v71, s[86:87]
	s_waitcnt lgkmcnt(4)
	v_mfma_f32_16x16x32_bf16 v[56:59], v[140:143], v[184:187], v[56:59]
	v_mfma_f32_16x16x32_bf16 v[24:27], v[144:147], v[184:187], v[24:27]
	v_mfma_f32_16x16x32_bf16 v[252:255], v[148:151], v[184:187], v[252:255]
	v_mfma_f32_16x16x32_bf16 v[120:123], v[204:207], v[184:187], v[120:123]
	ds_read_b128 v[180:183], v75 offset:22528
	s_add_u32 m0, s88, 61440
	s_nop 0
	global_load_lds_dwordx4 v74, s[86:87]
	s_add_u32 s86, s86, 128
	s_addc_u32 s87, s87, 0
	s_waitcnt lgkmcnt(4)
	v_mfma_f32_16x16x32_bf16 v[60:63], v[140:143], v[192:195], v[60:63]
	v_mfma_f32_16x16x32_bf16 v[28:31], v[144:147], v[192:195], v[28:31]
	v_mfma_f32_16x16x32_bf16 v[92:95], v[148:151], v[192:195], v[92:95]
	v_mfma_f32_16x16x32_bf16 v[124:127], v[204:207], v[192:195], v[124:127]
	s_waitcnt vmcnt(8)
	ds_read_b128 v[184:187], v75 offset:24576
	global_load_dwordx4 v[140:143], v66, s[84:85] offset:0
	s_waitcnt lgkmcnt(4)
	v_mfma_f32_16x16x32_bf16 v[32:35], v[160:163], v[196:199], v[32:35]
	v_mfma_f32_16x16x32_bf16 v[4:7], v[164:167], v[196:199], v[4:7]
	v_mfma_f32_16x16x32_bf16 v[188:191], v[168:171], v[196:199], v[188:191]
	v_mfma_f32_16x16x32_bf16 v[96:99], v[172:175], v[196:199], v[96:99]
	ds_read_b128 v[192:195], v75 offset:26624
	global_load_dwordx4 v[144:147], v67, s[84:85] offset:0
	s_waitcnt lgkmcnt(4)
	v_mfma_f32_16x16x32_bf16 v[36:39], v[160:163], v[200:203], v[36:39]
	v_mfma_f32_16x16x32_bf16 v[12:15], v[164:167], v[200:203], v[12:15]
	v_mfma_f32_16x16x32_bf16 v[208:211], v[168:171], v[200:203], v[208:211]
	v_mfma_f32_16x16x32_bf16 v[100:103], v[172:175], v[200:203], v[100:103]
	ds_read_b128 v[196:199], v75 offset:28672
	global_load_dwordx4 v[148:151], v66, s[92:93] offset:0
	s_waitcnt lgkmcnt(4)
	v_mfma_f32_16x16x32_bf16 v[40:43], v[160:163], v[176:179], v[40:43]
	v_mfma_f32_16x16x32_bf16 v[16:19], v[164:167], v[176:179], v[16:19]
	v_mfma_f32_16x16x32_bf16 v[232:235], v[168:171], v[176:179], v[232:235]
	v_mfma_f32_16x16x32_bf16 v[104:107], v[172:175], v[176:179], v[104:107]
	ds_read_b128 v[200:203], v75 offset:30720
	global_load_dwordx4 v[204:207], v67, s[92:93] offset:0
	s_waitcnt lgkmcnt(4)
	v_mfma_f32_16x16x32_bf16 v[44:47], v[160:163], v[180:183], v[44:47]
	v_mfma_f32_16x16x32_bf16 v[20:23], v[164:167], v[180:183], v[20:23]
	v_mfma_f32_16x16x32_bf16 v[236:239], v[168:171], v[180:183], v[236:239]
	v_mfma_f32_16x16x32_bf16 v[108:111], v[172:175], v[180:183], v[108:111]
	ds_read_b128 v[176:179], v212 offset:16384
	s_waitcnt lgkmcnt(4)
	v_mfma_f32_16x16x32_bf16 v[48:51], v[160:163], v[184:187], v[48:51]
	v_mfma_f32_16x16x32_bf16 v[0:3], v[164:167], v[184:187], v[0:3]
	v_mfma_f32_16x16x32_bf16 v[240:243], v[168:171], v[184:187], v[240:243]
	v_mfma_f32_16x16x32_bf16 v[112:115], v[172:175], v[184:187], v[112:115]
	ds_read_b128 v[180:183], v212 offset:18432
	s_waitcnt lgkmcnt(4)
	v_mfma_f32_16x16x32_bf16 v[52:55], v[160:163], v[192:195], v[52:55]
	v_mfma_f32_16x16x32_bf16 v[8:11], v[164:167], v[192:195], v[8:11]
	v_mfma_f32_16x16x32_bf16 v[248:251], v[168:171], v[192:195], v[248:251]
	v_mfma_f32_16x16x32_bf16 v[116:119], v[172:175], v[192:195], v[116:119]
	ds_read_b128 v[184:187], v212 offset:20480
	s_waitcnt lgkmcnt(4)
	v_mfma_f32_16x16x32_bf16 v[56:59], v[160:163], v[196:199], v[56:59]
	v_mfma_f32_16x16x32_bf16 v[24:27], v[164:167], v[196:199], v[24:27]
	v_mfma_f32_16x16x32_bf16 v[252:255], v[168:171], v[196:199], v[252:255]
	v_mfma_f32_16x16x32_bf16 v[120:123], v[172:175], v[196:199], v[120:123]
	ds_read_b128 v[192:195], v212 offset:22528
	s_waitcnt lgkmcnt(4)
	v_mfma_f32_16x16x32_bf16 v[60:63], v[160:163], v[200:203], v[60:63]
	v_mfma_f32_16x16x32_bf16 v[28:31], v[164:167], v[200:203], v[28:31]
	v_mfma_f32_16x16x32_bf16 v[92:95], v[168:171], v[200:203], v[92:95]
	v_mfma_f32_16x16x32_bf16 v[124:127], v[172:175], v[200:203], v[124:127]
	s_waitcnt vmcnt(16)
	s_barrier
	s_waitcnt vmcnt(8)
	ds_read_b128 v[196:199], v212 offset:24576
	global_load_dwordx4 v[160:163], v66, s[84:85] offset:1024
	s_waitcnt lgkmcnt(4)
	v_mfma_f32_16x16x32_bf16 v[32:35], v[76:79], v[176:179], v[32:35]
	v_mfma_f32_16x16x32_bf16 v[4:7], v[80:83], v[176:179], v[4:7]
	v_mfma_f32_16x16x32_bf16 v[188:191], v[84:87], v[176:179], v[188:191]
	v_mfma_f32_16x16x32_bf16 v[96:99], v[88:91], v[176:179], v[96:99]
	ds_read_b128 v[200:203], v212 offset:26624
	global_load_dwordx4 v[164:167], v67, s[84:85] offset:1024
	s_waitcnt lgkmcnt(4)
	v_mfma_f32_16x16x32_bf16 v[36:39], v[76:79], v[180:183], v[36:39]
	v_mfma_f32_16x16x32_bf16 v[12:15], v[80:83], v[180:183], v[12:15]
	v_mfma_f32_16x16x32_bf16 v[208:211], v[84:87], v[180:183], v[208:211]
	v_mfma_f32_16x16x32_bf16 v[100:103], v[88:91], v[180:183], v[100:103]
	ds_read_b128 v[176:179], v212 offset:28672
	global_load_dwordx4 v[168:171], v66, s[92:93] offset:1024
	s_waitcnt lgkmcnt(4)
	v_mfma_f32_16x16x32_bf16 v[40:43], v[76:79], v[184:187], v[40:43]
	v_mfma_f32_16x16x32_bf16 v[16:19], v[80:83], v[184:187], v[16:19]
	v_mfma_f32_16x16x32_bf16 v[232:235], v[84:87], v[184:187], v[232:235]
	v_mfma_f32_16x16x32_bf16 v[104:107], v[88:91], v[184:187], v[104:107]
	ds_read_b128 v[180:183], v212 offset:30720
	global_load_dwordx4 v[172:175], v67, s[92:93] offset:1024
	s_add_u32 s84, s84, 0x800
	s_addc_u32 s85, s85, 0
	s_add_u32 s92, s92, 0x800
	s_addc_u32 s93, s93, 0
	s_waitcnt lgkmcnt(4)
	v_mfma_f32_16x16x32_bf16 v[44:47], v[76:79], v[192:195], v[44:47]
	v_mfma_f32_16x16x32_bf16 v[20:23], v[80:83], v[192:195], v[20:23]
	v_mfma_f32_16x16x32_bf16 v[236:239], v[84:87], v[192:195], v[236:239]
	v_mfma_f32_16x16x32_bf16 v[108:111], v[88:91], v[192:195], v[108:111]
	ds_read_b128 v[184:187], v75 offset:32768
	s_waitcnt lgkmcnt(4)
	v_mfma_f32_16x16x32_bf16 v[48:51], v[76:79], v[196:199], v[48:51]
	v_mfma_f32_16x16x32_bf16 v[0:3], v[80:83], v[196:199], v[0:3]
	v_mfma_f32_16x16x32_bf16 v[240:243], v[84:87], v[196:199], v[240:243]
	v_mfma_f32_16x16x32_bf16 v[112:115], v[88:91], v[196:199], v[112:115]
	ds_read_b128 v[192:195], v75 offset:34816
	s_waitcnt lgkmcnt(4)
	v_mfma_f32_16x16x32_bf16 v[52:55], v[76:79], v[200:203], v[52:55]
	v_mfma_f32_16x16x32_bf16 v[8:11], v[80:83], v[200:203], v[8:11]
	v_mfma_f32_16x16x32_bf16 v[248:251], v[84:87], v[200:203], v[248:251]
	v_mfma_f32_16x16x32_bf16 v[116:119], v[88:91], v[200:203], v[116:119]
	ds_read_b128 v[196:199], v75 offset:36864
	s_waitcnt lgkmcnt(4)
	v_mfma_f32_16x16x32_bf16 v[56:59], v[76:79], v[176:179], v[56:59]
	v_mfma_f32_16x16x32_bf16 v[24:27], v[80:83], v[176:179], v[24:27]
	v_mfma_f32_16x16x32_bf16 v[252:255], v[84:87], v[176:179], v[252:255]
	v_mfma_f32_16x16x32_bf16 v[120:123], v[88:91], v[176:179], v[120:123]
	ds_read_b128 v[200:203], v75 offset:38912
	s_waitcnt lgkmcnt(4)
	v_mfma_f32_16x16x32_bf16 v[60:63], v[76:79], v[180:183], v[60:63]
	v_mfma_f32_16x16x32_bf16 v[28:31], v[80:83], v[180:183], v[28:31]
	v_mfma_f32_16x16x32_bf16 v[92:95], v[84:87], v[180:183], v[92:95]
	v_mfma_f32_16x16x32_bf16 v[124:127], v[88:91], v[180:183], v[124:127]
	s_waitcnt vmcnt(4)
	ds_read_b128 v[176:179], v75 offset:40960
	global_load_dwordx4 v[76:79], v66, s[84:85] offset:0
	s_waitcnt lgkmcnt(4)
	v_mfma_f32_16x16x32_bf16 v[32:35], v[140:143], v[184:187], v[32:35]
	v_mfma_f32_16x16x32_bf16 v[4:7], v[144:147], v[184:187], v[4:7]
	v_mfma_f32_16x16x32_bf16 v[188:191], v[148:151], v[184:187], v[188:191]
	v_mfma_f32_16x16x32_bf16 v[96:99], v[204:207], v[184:187], v[96:99]
	ds_read_b128 v[180:183], v75 offset:43008
	global_load_dwordx4 v[80:83], v67, s[84:85] offset:0
	s_waitcnt lgkmcnt(4)
	v_mfma_f32_16x16x32_bf16 v[36:39], v[140:143], v[192:195], v[36:39]
	v_mfma_f32_16x16x32_bf16 v[12:15], v[144:147], v[192:195], v[12:15]
	v_mfma_f32_16x16x32_bf16 v[208:211], v[148:151], v[192:195], v[208:211]
	v_mfma_f32_16x16x32_bf16 v[100:103], v[204:207], v[192:195], v[100:103]
	ds_read_b128 v[184:187], v75 offset:45056
	global_load_dwordx4 v[84:87], v66, s[92:93] offset:0
	s_waitcnt lgkmcnt(4)
	v_mfma_f32_16x16x32_bf16 v[40:43], v[140:143], v[196:199], v[40:43]
	v_mfma_f32_16x16x32_bf16 v[16:19], v[144:147], v[196:199], v[16:19]
	v_mfma_f32_16x16x32_bf16 v[232:235], v[148:151], v[196:199], v[232:235]
	v_mfma_f32_16x16x32_bf16 v[104:107], v[204:207], v[196:199], v[104:107]
	ds_read_b128 v[192:195], v75 offset:47104
	global_load_dwordx4 v[88:91], v67, s[92:93] offset:0
	s_waitcnt lgkmcnt(4)
	v_mfma_f32_16x16x32_bf16 v[44:47], v[140:143], v[200:203], v[44:47]
	v_mfma_f32_16x16x32_bf16 v[20:23], v[144:147], v[200:203], v[20:23]
	v_mfma_f32_16x16x32_bf16 v[236:239], v[148:151], v[200:203], v[236:239]
	v_mfma_f32_16x16x32_bf16 v[108:111], v[204:207], v[200:203], v[108:111]
	ds_read_b128 v[196:199], v212 offset:32768
	s_waitcnt lgkmcnt(4)
	v_mfma_f32_16x16x32_bf16 v[48:51], v[140:143], v[176:179], v[48:51]
	v_mfma_f32_16x16x32_bf16 v[0:3], v[144:147], v[176:179], v[0:3]
	v_mfma_f32_16x16x32_bf16 v[240:243], v[148:151], v[176:179], v[240:243]
	v_mfma_f32_16x16x32_bf16 v[112:115], v[204:207], v[176:179], v[112:115]
	ds_read_b128 v[200:203], v212 offset:34816
	s_waitcnt lgkmcnt(4)
	v_mfma_f32_16x16x32_bf16 v[52:55], v[140:143], v[180:183], v[52:55]
	v_mfma_f32_16x16x32_bf16 v[8:11], v[144:147], v[180:183], v[8:11]
	v_mfma_f32_16x16x32_bf16 v[248:251], v[148:151], v[180:183], v[248:251]
	v_mfma_f32_16x16x32_bf16 v[116:119], v[204:207], v[180:183], v[116:119]
	ds_read_b128 v[176:179], v212 offset:36864
	s_waitcnt lgkmcnt(4)
	v_mfma_f32_16x16x32_bf16 v[56:59], v[140:143], v[184:187], v[56:59]
	v_mfma_f32_16x16x32_bf16 v[24:27], v[144:147], v[184:187], v[24:27]
	v_mfma_f32_16x16x32_bf16 v[252:255], v[148:151], v[184:187], v[252:255]
	v_mfma_f32_16x16x32_bf16 v[120:123], v[204:207], v[184:187], v[120:123]
	ds_read_b128 v[180:183], v212 offset:38912
	s_waitcnt lgkmcnt(4)
	v_mfma_f32_16x16x32_bf16 v[60:63], v[140:143], v[192:195], v[60:63]
	v_mfma_f32_16x16x32_bf16 v[28:31], v[144:147], v[192:195], v[28:31]
	v_mfma_f32_16x16x32_bf16 v[92:95], v[148:151], v[192:195], v[92:95]
	v_mfma_f32_16x16x32_bf16 v[124:127], v[204:207], v[192:195], v[124:127]
	s_waitcnt vmcnt(12)
	s_barrier
	s_waitcnt vmcnt(4)
	ds_read_b128 v[184:187], v212 offset:40960
	global_load_dwordx4 v[140:143], v66, s[84:85] offset:1024
	s_waitcnt lgkmcnt(4)
	v_mfma_f32_16x16x32_bf16 v[32:35], v[160:163], v[196:199], v[32:35]
	v_mfma_f32_16x16x32_bf16 v[4:7], v[164:167], v[196:199], v[4:7]
	v_mfma_f32_16x16x32_bf16 v[188:191], v[168:171], v[196:199], v[188:191]
	v_mfma_f32_16x16x32_bf16 v[96:99], v[172:175], v[196:199], v[96:99]
	ds_read_b128 v[192:195], v212 offset:43008
	global_load_dwordx4 v[144:147], v67, s[84:85] offset:1024
	s_waitcnt lgkmcnt(4)
	v_mfma_f32_16x16x32_bf16 v[36:39], v[160:163], v[200:203], v[36:39]
	v_mfma_f32_16x16x32_bf16 v[12:15], v[164:167], v[200:203], v[12:15]
	v_mfma_f32_16x16x32_bf16 v[208:211], v[168:171], v[200:203], v[208:211]
	v_mfma_f32_16x16x32_bf16 v[100:103], v[172:175], v[200:203], v[100:103]
	ds_read_b128 v[196:199], v212 offset:45056
	global_load_dwordx4 v[148:151], v66, s[92:93] offset:1024
	s_waitcnt lgkmcnt(4)
	v_mfma_f32_16x16x32_bf16 v[40:43], v[160:163], v[176:179], v[40:43]
	v_mfma_f32_16x16x32_bf16 v[16:19], v[164:167], v[176:179], v[16:19]
	v_mfma_f32_16x16x32_bf16 v[232:235], v[168:171], v[176:179], v[232:235]
	v_mfma_f32_16x16x32_bf16 v[104:107], v[172:175], v[176:179], v[104:107]
	ds_read_b128 v[200:203], v212 offset:47104
	global_load_dwordx4 v[204:207], v67, s[92:93] offset:1024
	s_add_u32 s84, s84, 0x800
	s_addc_u32 s85, s85, 0
	s_add_u32 s92, s92, 0x800
	s_addc_u32 s93, s93, 0
	s_waitcnt lgkmcnt(4)
	v_mfma_f32_16x16x32_bf16 v[44:47], v[160:163], v[180:183], v[44:47]
	v_mfma_f32_16x16x32_bf16 v[20:23], v[164:167], v[180:183], v[20:23]
	v_mfma_f32_16x16x32_bf16 v[236:239], v[168:171], v[180:183], v[236:239]
	v_mfma_f32_16x16x32_bf16 v[108:111], v[172:175], v[180:183], v[108:111]
	ds_read_b128 v[176:179], v75 offset:49152
	s_waitcnt lgkmcnt(4)
	v_mfma_f32_16x16x32_bf16 v[48:51], v[160:163], v[184:187], v[48:51]
	v_mfma_f32_16x16x32_bf16 v[0:3], v[164:167], v[184:187], v[0:3]
	v_mfma_f32_16x16x32_bf16 v[240:243], v[168:171], v[184:187], v[240:243]
	v_mfma_f32_16x16x32_bf16 v[112:115], v[172:175], v[184:187], v[112:115]
	ds_read_b128 v[180:183], v75 offset:51200
	s_waitcnt lgkmcnt(4)
	v_mfma_f32_16x16x32_bf16 v[52:55], v[160:163], v[192:195], v[52:55]
	v_mfma_f32_16x16x32_bf16 v[8:11], v[164:167], v[192:195], v[8:11]
	v_mfma_f32_16x16x32_bf16 v[248:251], v[168:171], v[192:195], v[248:251]
	v_mfma_f32_16x16x32_bf16 v[116:119], v[172:175], v[192:195], v[116:119]
	ds_read_b128 v[184:187], v75 offset:53248
	s_waitcnt lgkmcnt(4)
	v_mfma_f32_16x16x32_bf16 v[56:59], v[160:163], v[196:199], v[56:59]
	v_mfma_f32_16x16x32_bf16 v[24:27], v[164:167], v[196:199], v[24:27]
	v_mfma_f32_16x16x32_bf16 v[252:255], v[168:171], v[196:199], v[252:255]
	v_mfma_f32_16x16x32_bf16 v[120:123], v[172:175], v[196:199], v[120:123]
	ds_read_b128 v[192:195], v75 offset:55296
	s_waitcnt lgkmcnt(4)
	v_mfma_f32_16x16x32_bf16 v[60:63], v[160:163], v[200:203], v[60:63]
	v_mfma_f32_16x16x32_bf16 v[28:31], v[164:167], v[200:203], v[28:31]
	v_mfma_f32_16x16x32_bf16 v[92:95], v[168:171], v[200:203], v[92:95]
	v_mfma_f32_16x16x32_bf16 v[124:127], v[172:175], v[200:203], v[124:127]
	s_waitcnt vmcnt(4)
	ds_read_b128 v[196:199], v75 offset:57344
	s_waitcnt lgkmcnt(4)
	v_mfma_f32_16x16x32_bf16 v[32:35], v[76:79], v[176:179], v[32:35]
	v_mfma_f32_16x16x32_bf16 v[4:7], v[80:83], v[176:179], v[4:7]
	v_mfma_f32_16x16x32_bf16 v[188:191], v[84:87], v[176:179], v[188:191]
	v_mfma_f32_16x16x32_bf16 v[96:99], v[88:91], v[176:179], v[96:99]
	ds_read_b128 v[200:203], v75 offset:59392
	s_waitcnt lgkmcnt(4)
	v_mfma_f32_16x16x32_bf16 v[36:39], v[76:79], v[180:183], v[36:39]
	v_mfma_f32_16x16x32_bf16 v[12:15], v[80:83], v[180:183], v[12:15]
	v_mfma_f32_16x16x32_bf16 v[208:211], v[84:87], v[180:183], v[208:211]
	v_mfma_f32_16x16x32_bf16 v[100:103], v[88:91], v[180:183], v[100:103]
	ds_read_b128 v[176:179], v75 offset:61440
	s_waitcnt lgkmcnt(4)
	v_mfma_f32_16x16x32_bf16 v[40:43], v[76:79], v[184:187], v[40:43]
	v_mfma_f32_16x16x32_bf16 v[16:19], v[80:83], v[184:187], v[16:19]
	v_mfma_f32_16x16x32_bf16 v[232:235], v[84:87], v[184:187], v[232:235]
	v_mfma_f32_16x16x32_bf16 v[104:107], v[88:91], v[184:187], v[104:107]
	ds_read_b128 v[180:183], v75 offset:63488
	s_waitcnt lgkmcnt(4)
	v_mfma_f32_16x16x32_bf16 v[44:47], v[76:79], v[192:195], v[44:47]
	v_mfma_f32_16x16x32_bf16 v[20:23], v[80:83], v[192:195], v[20:23]
	v_mfma_f32_16x16x32_bf16 v[236:239], v[84:87], v[192:195], v[236:239]
	v_mfma_f32_16x16x32_bf16 v[108:111], v[88:91], v[192:195], v[108:111]
	ds_read_b128 v[184:187], v212 offset:49152
	s_waitcnt lgkmcnt(4)
	v_mfma_f32_16x16x32_bf16 v[48:51], v[76:79], v[196:199], v[48:51]
	v_mfma_f32_16x16x32_bf16 v[0:3], v[80:83], v[196:199], v[0:3]
	v_mfma_f32_16x16x32_bf16 v[240:243], v[84:87], v[196:199], v[240:243]
	v_mfma_f32_16x16x32_bf16 v[112:115], v[88:91], v[196:199], v[112:115]
	ds_read_b128 v[192:195], v212 offset:51200
	s_waitcnt lgkmcnt(4)
	v_mfma_f32_16x16x32_bf16 v[52:55], v[76:79], v[200:203], v[52:55]
	v_mfma_f32_16x16x32_bf16 v[8:11], v[80:83], v[200:203], v[8:11]
	v_mfma_f32_16x16x32_bf16 v[248:251], v[84:87], v[200:203], v[248:251]
	v_mfma_f32_16x16x32_bf16 v[116:119], v[88:91], v[200:203], v[116:119]
	ds_read_b128 v[196:199], v212 offset:53248
	s_waitcnt lgkmcnt(4)
	v_mfma_f32_16x16x32_bf16 v[56:59], v[76:79], v[176:179], v[56:59]
	v_mfma_f32_16x16x32_bf16 v[24:27], v[80:83], v[176:179], v[24:27]
	v_mfma_f32_16x16x32_bf16 v[252:255], v[84:87], v[176:179], v[252:255]
	v_mfma_f32_16x16x32_bf16 v[120:123], v[88:91], v[176:179], v[120:123]
	ds_read_b128 v[200:203], v212 offset:55296
	s_waitcnt lgkmcnt(4)
	v_mfma_f32_16x16x32_bf16 v[60:63], v[76:79], v[180:183], v[60:63]
	v_mfma_f32_16x16x32_bf16 v[28:31], v[80:83], v[180:183], v[28:31]
	v_mfma_f32_16x16x32_bf16 v[92:95], v[84:87], v[180:183], v[92:95]
	v_mfma_f32_16x16x32_bf16 v[124:127], v[88:91], v[180:183], v[124:127]
	s_waitcnt vmcnt(0)
	ds_read_b128 v[176:179], v212 offset:57344
	s_waitcnt lgkmcnt(4)
	v_mfma_f32_16x16x32_bf16 v[32:35], v[140:143], v[184:187], v[32:35]
	v_mfma_f32_16x16x32_bf16 v[4:7], v[144:147], v[184:187], v[4:7]
	v_mfma_f32_16x16x32_bf16 v[188:191], v[148:151], v[184:187], v[188:191]
	v_mfma_f32_16x16x32_bf16 v[96:99], v[204:207], v[184:187], v[96:99]
	ds_read_b128 v[180:183], v212 offset:59392
	s_waitcnt lgkmcnt(4)
	v_mfma_f32_16x16x32_bf16 v[36:39], v[140:143], v[192:195], v[36:39]
	v_mfma_f32_16x16x32_bf16 v[12:15], v[144:147], v[192:195], v[12:15]
	v_mfma_f32_16x16x32_bf16 v[208:211], v[148:151], v[192:195], v[208:211]
	v_mfma_f32_16x16x32_bf16 v[100:103], v[204:207], v[192:195], v[100:103]
	ds_read_b128 v[184:187], v212 offset:61440
	s_waitcnt lgkmcnt(4)
	v_mfma_f32_16x16x32_bf16 v[40:43], v[140:143], v[196:199], v[40:43]
	v_mfma_f32_16x16x32_bf16 v[16:19], v[144:147], v[196:199], v[16:19]
	v_mfma_f32_16x16x32_bf16 v[232:235], v[148:151], v[196:199], v[232:235]
	v_mfma_f32_16x16x32_bf16 v[104:107], v[204:207], v[196:199], v[104:107]
	ds_read_b128 v[192:195], v212 offset:63488
	s_waitcnt lgkmcnt(4)
	v_mfma_f32_16x16x32_bf16 v[44:47], v[140:143], v[200:203], v[44:47]
	v_mfma_f32_16x16x32_bf16 v[20:23], v[144:147], v[200:203], v[20:23]
	v_mfma_f32_16x16x32_bf16 v[236:239], v[148:151], v[200:203], v[236:239]
	v_mfma_f32_16x16x32_bf16 v[108:111], v[204:207], v[200:203], v[108:111]
	s_waitcnt lgkmcnt(3)
	v_mfma_f32_16x16x32_bf16 v[48:51], v[140:143], v[176:179], v[48:51]
	v_mfma_f32_16x16x32_bf16 v[0:3], v[144:147], v[176:179], v[0:3]
	v_mfma_f32_16x16x32_bf16 v[240:243], v[148:151], v[176:179], v[240:243]
	v_mfma_f32_16x16x32_bf16 v[112:115], v[204:207], v[176:179], v[112:115]
	s_waitcnt lgkmcnt(2)
	v_mfma_f32_16x16x32_bf16 v[52:55], v[140:143], v[180:183], v[52:55]
	v_mfma_f32_16x16x32_bf16 v[8:11], v[144:147], v[180:183], v[8:11]
	v_mfma_f32_16x16x32_bf16 v[248:251], v[148:151], v[180:183], v[248:251]
	v_mfma_f32_16x16x32_bf16 v[116:119], v[204:207], v[180:183], v[116:119]
	s_waitcnt lgkmcnt(1)
	v_mfma_f32_16x16x32_bf16 v[56:59], v[140:143], v[184:187], v[56:59]
	v_mfma_f32_16x16x32_bf16 v[24:27], v[144:147], v[184:187], v[24:27]
	v_mfma_f32_16x16x32_bf16 v[252:255], v[148:151], v[184:187], v[252:255]
	v_mfma_f32_16x16x32_bf16 v[120:123], v[204:207], v[184:187], v[120:123]
	s_waitcnt lgkmcnt(0)
	v_mfma_f32_16x16x32_bf16 v[60:63], v[140:143], v[192:195], v[60:63]
	v_mfma_f32_16x16x32_bf16 v[28:31], v[144:147], v[192:195], v[28:31]
	v_mfma_f32_16x16x32_bf16 v[92:95], v[148:151], v[192:195], v[92:95]
	v_mfma_f32_16x16x32_bf16 v[124:127], v[204:207], v[192:195], v[124:127]
	s_nop 7
	s_nop 7
	s_waitcnt vmcnt(0) lgkmcnt(0)
	s_barrier
	v_mov_b32_e32 v66, v92
	v_mov_b32_e32 v67, v93
	v_mov_b32_e32 v68, v94
	v_mov_b32_e32 v69, v95
	v_mov_b32_e32 v71, v96
	v_mov_b32_e32 v74, v97
	v_mov_b32_e32 v75, v98
	v_mov_b32_e32 v160, v99
	v_mov_b32_e32 v161, v100
	v_mov_b32_e32 v162, v101
	v_mov_b32_e32 v185, v102
	v_mov_b32_e32 v186, v103
	v_mov_b32_e32 v187, v104
	v_mov_b32_e32 v207, v105
	v_mov_b32_e32 v212, v106
	v_mov_b32_e32 v213, v107
	v_mov_b32_e32 v214, v108
	v_mov_b32_e32 v216, v109
	v_mov_b32_e32 v218, v110
	v_mov_b32_e32 v220, v111
	v_mov_b32_e32 v222, v112
	v_mov_b32_e32 v224, v113
	v_mov_b32_e32 v226, v114
	v_mov_b32_e32 v228, v115
	v_mov_b32_e32 v230, v116
	v_mov_b32_e32 v231, v117
	v_mov_b32_e32 v244, v118
	v_mov_b32_e32 v245, v119
	ds_write_b128 v129, v[120:123] offset:36864
	ds_write_b128 v129, v[124:127] offset:40960
	v_lshlrev_b32_e32 v77, 13, v135
	v_lshl_add_u32 v78, v134, 3, v138
	v_lshl_or_b32 v79, v134, 11, v77
	v_lshlrev_b32_e32 v81, 5, v138
	v_or3_b32 v163, v77, v137, v81
	v_lshl_or_b32 v164, v78, 2, v79
	v_add_u32_e32 v81, 0x60, v78
	v_add_u32_e32 v78, 0x70, v78
	v_and_b32_e32 v81, 0x7f, v81
	v_and_b32_e32 v78, 0x7f, v78
	v_lshl_or_b32 v165, v81, 2, v79
	v_lshl_or_b32 v166, v78, 2, v79
	v_add_u32_e32 v79, 8, v133
	v_and_b32_e32 v79, 0x78, v79
	v_lshlrev_b32_e32 v78, 9, v136
	v_lshlrev_b32_e32 v79, 2, v79
	v_or3_b32 v168, v77, v78, v79
	v_add_u32_e32 v79, 16, v133
	v_and_b32_e32 v79, 0x78, v79
	v_lshlrev_b32_e32 v78, 9, v132
	v_lshlrev_b32_e32 v79, 2, v79
	v_or3_b32 v170, v77, v78, v79
	v_add_u32_e32 v79, 24, v133
	v_and_b32_e32 v79, 0x78, v79
	v_lshlrev_b32_e32 v80, 5, v135
	v_lshlrev_b32_e32 v78, 9, v130
	v_lshlrev_b32_e32 v79, 2, v79
	v_or3_b32 v172, v77, v78, v79
	v_or_b32_e32 v77, 16, v80
	v_add_u32_e32 v81, 0x100, v131
	v_add_u32_e32 v82, 0x200, v131
	v_add_u32_e32 v83, 0x300, v131
	v_add_u32_e32 v84, 0x500, v131
	v_add_u32_e32 v85, 0x600, v131
	v_add_u32_e32 v86, 0x700, v131
	v_or_b32_e32 v174, v77, v134
	v_or_b32_e32 v175, v136, v77
	v_or_b32_e32 v176, v132, v77
	v_or_b32_e32 v177, v130, v77
	v_and_b32_e32 v77, 24, v153
	s_movk_i32 s94, 0x3c0
	v_lshrrev_b32_e32 v178, 4, v81
	v_lshrrev_b32_e32 v179, 4, v82
	v_lshrrev_b32_e32 v180, 4, v83
	v_lshrrev_b32_e32 v182, 4, v84
	v_lshrrev_b32_e32 v183, 4, v85
	v_lshrrev_b32_e32 v184, 4, v86
	v_or_b32_e32 v167, v134, v80
	v_or_b32_e32 v169, v136, v80
	v_or_b32_e32 v171, v132, v80
	v_or_b32_e32 v173, v130, v80
	v_and_or_b32 v77, v131, s94, v77
	v_mul_u32_u24_e32 v78, 0x110, v138
	v_lshlrev_b32_e32 v79, 4, v138
	v_mul_u32_u24_e32 v80, 0x110, v128
	v_mul_u32_u24_e32 v81, 0x110, v178
	v_mul_u32_u24_e32 v82, 0x110, v179
	v_mul_u32_u24_e32 v83, 0x110, v180
	v_mul_u32_u24_e32 v84, 0x110, v182
	v_mul_u32_u24_e32 v85, 0x110, v183
	v_mul_u32_u24_e32 v86, 0x110, v184
	v_or_b32_e32 v181, 64, v128
	v_lshlrev_b32_e32 v192, 2, v138
	v_add_u32_e32 v193, v77, v78
	v_add_u32_e32 v194, v79, v80
	v_add_u32_e32 v195, v79, v81
	v_add_u32_e32 v196, v79, v82
	v_add_u32_e32 v197, v79, v83
	v_add_u32_e32 v198, v79, v84
	v_add_u32_e32 v199, v79, v85
	v_add_u32_e32 v200, v79, v86
	v_mbcnt_hi_u32_b32 v201, -1, v155
	v_mov_b32_e32 v202, 0x3db504f3
	s_waitcnt lgkmcnt(0)
	s_mov_b64 s[58:59], -1
	s_cmp_lt_i32 s65, 4
	s_branch .Lmy_ip1_epi
.Lmy_ip1_pass2:
	s_barrier
	v_mov_b32_e32 v32, v188
	v_mov_b32_e32 v33, v189
	v_mov_b32_e32 v34, v190
	v_mov_b32_e32 v35, v191
	v_mov_b32_e32 v36, v208
	v_mov_b32_e32 v37, v209
	v_mov_b32_e32 v38, v210
	v_mov_b32_e32 v39, v211
	v_mov_b32_e32 v40, v232
	v_mov_b32_e32 v41, v233
	v_mov_b32_e32 v42, v234
	v_mov_b32_e32 v43, v235
	v_mov_b32_e32 v44, v236
	v_mov_b32_e32 v45, v237
	v_mov_b32_e32 v46, v238
	v_mov_b32_e32 v47, v239
	v_mov_b32_e32 v48, v240
	v_mov_b32_e32 v49, v241
	v_mov_b32_e32 v50, v242
	v_mov_b32_e32 v51, v243
	v_mov_b32_e32 v52, v248
	v_mov_b32_e32 v53, v249
	v_mov_b32_e32 v54, v250
	v_mov_b32_e32 v55, v251
	v_mov_b32_e32 v56, v252
	v_mov_b32_e32 v57, v253
	v_mov_b32_e32 v58, v254
	v_mov_b32_e32 v59, v255
	v_mov_b32_e32 v60, v66
	v_mov_b32_e32 v61, v67
	v_mov_b32_e32 v62, v68
	v_mov_b32_e32 v63, v69
	v_mov_b32_e32 v4, v71
	v_mov_b32_e32 v5, v74
	v_mov_b32_e32 v6, v75
	v_mov_b32_e32 v7, v160
	v_mov_b32_e32 v12, v161
	v_mov_b32_e32 v13, v162
	v_mov_b32_e32 v14, v185
	v_mov_b32_e32 v15, v186
	v_mov_b32_e32 v16, v187
	v_mov_b32_e32 v17, v207
	v_mov_b32_e32 v18, v212
	v_mov_b32_e32 v19, v213
	v_mov_b32_e32 v20, v214
	v_mov_b32_e32 v21, v216
	v_mov_b32_e32 v22, v218
	v_mov_b32_e32 v23, v220
	v_mov_b32_e32 v0, v222
	v_mov_b32_e32 v1, v224
	v_mov_b32_e32 v2, v226
	v_mov_b32_e32 v3, v228
	v_mov_b32_e32 v8, v230
	v_mov_b32_e32 v9, v231
	v_mov_b32_e32 v10, v244
	v_mov_b32_e32 v11, v245
	ds_read_b128 v[24:27], v129 offset:36864
	ds_read_b128 v[28:31], v129 offset:40960
	s_waitcnt lgkmcnt(0)
	s_lshl_b64 s[54:55], s[0:1], 17
	s_mov_b64 s[58:59], -1
	s_cmp_lt_i32 s65, 4
.Lmy_ip1_epi:
	s_cbranch_scc1 .LBB0_434
	v_mul_f32_e32 v64, 0xbfb8aa3b, v32
	v_exp_f32_e32 v76, v64
	v_mul_f32_e32 v64, 0xbfb8aa3b, v33
	v_exp_f32_e32 v77, v64
	v_mul_f32_e32 v64, 0xbfb8aa3b, v34
	v_exp_f32_e32 v78, v64
	v_mul_f32_e32 v64, 0xbfb8aa3b, v35
	v_pk_add_f32 v[76:77], v[76:77], 1.0 op_sel_hi:[1,0]
	v_exp_f32_e32 v79, v64
	v_div_scale_f32 v64, s[56:57], v76, v76, v32
	v_rcp_f32_e32 v80, v64
	v_pk_add_f32 v[78:79], v[78:79], 1.0 op_sel_hi:[1,0]
	v_mul_f32_e32 v105, 0xbfb8aa3b, v59
	v_exp_f32_e32 v105, v105
	v_fma_f32 v81, -v64, v80, 1.0
	v_fmac_f32_e32 v80, v81, v80
	v_div_scale_f32 v81, vcc, v32, v76, v32
	v_mul_f32_e32 v82, v81, v80
	v_fma_f32 v83, -v64, v82, v81
	v_fmac_f32_e32 v82, v83, v80
	v_fma_f32 v64, -v64, v82, v81
	v_div_scale_f32 v81, s[56:57], v77, v77, v33
	v_rcp_f32_e32 v83, v81
	v_div_fmas_f32 v64, v64, v80, v82
	v_div_fixup_f32 v76, v64, v76, v32
	s_mov_b64 s[58:59], 0
	v_fma_f32 v64, -v81, v83, 1.0
	v_fmac_f32_e32 v83, v64, v83
	v_div_scale_f32 v64, vcc, v33, v77, v33
	v_mul_f32_e32 v80, v64, v83
	v_fma_f32 v82, -v81, v80, v64
	v_fmac_f32_e32 v80, v82, v83
	v_fma_f32 v64, -v81, v80, v64
	v_div_scale_f32 v81, s[56:57], v78, v78, v34
	v_rcp_f32_e32 v82, v81
	v_div_fmas_f32 v64, v64, v83, v80
	v_div_fixup_f32 v77, v64, v77, v33
	v_fma_f32 v64, -v81, v82, 1.0
	v_fmac_f32_e32 v82, v64, v82
	v_div_scale_f32 v64, vcc, v34, v78, v34
	v_mul_f32_e32 v80, v64, v82
	v_fma_f32 v83, -v81, v80, v64
	v_fmac_f32_e32 v80, v83, v82
	v_fma_f32 v64, -v81, v80, v64
	v_div_scale_f32 v81, s[56:57], v79, v79, v35
	v_rcp_f32_e32 v84, v81
	v_div_fmas_f32 v64, v64, v82, v80
	v_div_fixup_f32 v88, v64, v78, v34
	v_mul_f32_e32 v82, 0xbfb8aa3b, v38
	v_fma_f32 v64, -v81, v84, 1.0
	v_fmac_f32_e32 v84, v64, v84
	v_div_scale_f32 v64, vcc, v35, v79, v35
	v_mul_f32_e32 v78, v64, v84
	v_fma_f32 v80, -v81, v78, v64
	v_fmac_f32_e32 v78, v80, v84
	v_fma_f32 v64, -v81, v78, v64
	v_mul_f32_e32 v80, 0xbfb8aa3b, v36
	v_mul_f32_e32 v81, 0xbfb8aa3b, v37
	v_exp_f32_e32 v80, v80
	v_exp_f32_e32 v81, v81
	v_div_fmas_f32 v64, v64, v84, v78
	v_div_fixup_f32 v89, v64, v79, v35
	v_mul_f32_e32 v83, 0xbfb8aa3b, v39
	v_pk_add_f32 v[80:81], v[80:81], 1.0 op_sel_hi:[1,0]
	v_exp_f32_e32 v82, v82
	v_div_scale_f32 v85, s[56:57], v80, v80, v36
	v_rcp_f32_e32 v86, v85
	v_exp_f32_e32 v83, v83
	v_fma_f32 v64, -v85, v86, 1.0
	v_fmac_f32_e32 v86, v64, v86
	v_div_scale_f32 v64, vcc, v36, v80, v36
	v_mul_f32_e32 v78, v64, v86
	v_fma_f32 v79, -v85, v78, v64
	v_fmac_f32_e32 v78, v79, v86
	v_div_scale_f32 v79, s[56:57], v81, v81, v37
	v_rcp_f32_e32 v84, v79
	v_fma_f32 v64, -v85, v78, v64
	v_div_fmas_f32 v64, v64, v86, v78
	v_div_fixup_f32 v78, v64, v80, v36
	v_fma_f32 v64, -v79, v84, 1.0
	v_fmac_f32_e32 v84, v64, v84
	v_div_scale_f32 v64, vcc, v37, v81, v37
	v_mul_f32_e32 v80, v64, v84
	v_pk_add_f32 v[82:83], v[82:83], 1.0 op_sel_hi:[1,0]
	v_fma_f32 v85, -v79, v80, v64
	v_fmac_f32_e32 v80, v85, v84
	v_div_scale_f32 v85, s[56:57], v82, v82, v38
	v_rcp_f32_e32 v86, v85
	v_fma_f32 v64, -v79, v80, v64
	v_div_fmas_f32 v64, v64, v84, v80
	v_div_fixup_f32 v79, v64, v81, v37
	v_fma_f32 v64, -v85, v86, 1.0
	v_fmac_f32_e32 v86, v64, v86
	v_div_scale_f32 v64, vcc, v38, v82, v38
	v_mul_f32_e32 v80, v64, v86
	v_fma_f32 v81, -v85, v80, v64
	v_fmac_f32_e32 v80, v81, v86
	v_div_scale_f32 v81, s[56:57], v83, v83, v39
	v_rcp_f32_e32 v87, v81
	v_fma_f32 v64, -v85, v80, v64
	v_div_fmas_f32 v64, v64, v86, v80
	v_div_fixup_f32 v92, v64, v82, v38
	v_fma_f32 v64, -v81, v87, 1.0
	v_fmac_f32_e32 v87, v64, v87
	v_div_scale_f32 v64, vcc, v39, v83, v39
	v_mul_f32_e32 v82, v64, v87
	v_fma_f32 v80, -v81, v82, v64
	v_fmac_f32_e32 v82, v80, v87
	v_fma_f32 v64, -v81, v82, v64
	v_mul_f32_e32 v80, 0xbfb8aa3b, v40
	v_mul_f32_e32 v81, 0xbfb8aa3b, v41
	v_exp_f32_e32 v80, v80
	v_exp_f32_e32 v81, v81
	v_mul_f32_e32 v84, 0xbfb8aa3b, v42
	v_mul_f32_e32 v85, 0xbfb8aa3b, v43
	v_exp_f32_e32 v84, v84
	v_pk_add_f32 v[80:81], v[80:81], 1.0 op_sel_hi:[1,0]
	v_exp_f32_e32 v85, v85
	v_div_scale_f32 v86, s[56:57], v80, v80, v40
	v_rcp_f32_e32 v90, v86
	v_div_fmas_f32 v64, v64, v87, v82
	v_div_fixup_f32 v93, v64, v83, v39
	v_pk_add_f32 v[82:83], v[84:85], 1.0 op_sel_hi:[1,0]
	v_fma_f32 v64, -v86, v90, 1.0
	v_fmac_f32_e32 v90, v64, v90
	v_div_scale_f32 v64, vcc, v40, v80, v40
	v_mul_f32_e32 v84, v64, v90
	v_fma_f32 v85, -v86, v84, v64
	v_fmac_f32_e32 v84, v85, v90
	v_div_scale_f32 v85, s[56:57], v81, v81, v41
	v_fma_f32 v64, -v86, v84, v64
	v_rcp_f32_e32 v86, v85
	v_div_fmas_f32 v64, v64, v90, v84
	v_div_fixup_f32 v80, v64, v80, v40
	v_fma_f32 v64, -v85, v86, 1.0
	v_fmac_f32_e32 v86, v64, v86
	v_div_scale_f32 v64, vcc, v41, v81, v41
	v_mul_f32_e32 v84, v64, v86
	v_fma_f32 v87, -v85, v84, v64
	v_fmac_f32_e32 v84, v87, v86
	v_fma_f32 v64, -v85, v84, v64
	v_div_scale_f32 v85, s[56:57], v82, v82, v42
	v_rcp_f32_e32 v87, v85
	v_div_fmas_f32 v64, v64, v86, v84
	v_div_fixup_f32 v81, v64, v81, v41
	v_fma_f32 v64, -v85, v87, 1.0
	v_fmac_f32_e32 v87, v64, v87
	v_div_scale_f32 v64, vcc, v42, v82, v42
	v_mul_f32_e32 v84, v64, v87
	v_fma_f32 v86, -v85, v84, v64
	v_fmac_f32_e32 v84, v86, v87
	v_fma_f32 v64, -v85, v84, v64
	v_div_scale_f32 v85, s[56:57], v83, v83, v43
	v_rcp_f32_e32 v90, v85
	v_div_fmas_f32 v64, v64, v87, v84
	v_div_fixup_f32 v96, v64, v82, v42
	v_mul_f32_e32 v86, 0xbfb8aa3b, v46
	v_fma_f32 v64, -v85, v90, 1.0
	v_fmac_f32_e32 v90, v64, v90
	v_div_scale_f32 v64, vcc, v43, v83, v43
	v_mul_f32_e32 v82, v64, v90
	v_fma_f32 v84, -v85, v82, v64
	v_fmac_f32_e32 v82, v84, v90
	v_fma_f32 v64, -v85, v82, v64
	v_mul_f32_e32 v84, 0xbfb8aa3b, v44
	v_mul_f32_e32 v85, 0xbfb8aa3b, v45
	v_exp_f32_e32 v84, v84
	v_exp_f32_e32 v85, v85
	v_div_fmas_f32 v64, v64, v90, v82
	v_div_fixup_f32 v97, v64, v83, v43
	v_mul_f32_e32 v87, 0xbfb8aa3b, v47
	v_pk_add_f32 v[84:85], v[84:85], 1.0 op_sel_hi:[1,0]
	v_exp_f32_e32 v86, v86
	v_div_scale_f32 v91, s[56:57], v84, v84, v44
	v_rcp_f32_e32 v94, v91
	v_exp_f32_e32 v87, v87
	v_fma_f32 v64, -v91, v94, 1.0
	v_fmac_f32_e32 v94, v64, v94
	v_div_scale_f32 v64, vcc, v44, v84, v44
	v_mul_f32_e32 v82, v64, v94
	v_fma_f32 v83, -v91, v82, v64
	v_fmac_f32_e32 v82, v83, v94
	v_div_scale_f32 v83, s[56:57], v85, v85, v45
	v_rcp_f32_e32 v90, v83
	v_fma_f32 v64, -v91, v82, v64
	v_div_fmas_f32 v64, v64, v94, v82
	v_div_fixup_f32 v82, v64, v84, v44
	v_fma_f32 v64, -v83, v90, 1.0
	v_fmac_f32_e32 v90, v64, v90
	v_div_scale_f32 v64, vcc, v45, v85, v45
	v_mul_f32_e32 v84, v64, v90
	v_pk_add_f32 v[86:87], v[86:87], 1.0 op_sel_hi:[1,0]
	v_fma_f32 v91, -v83, v84, v64
	v_fmac_f32_e32 v84, v91, v90
	v_div_scale_f32 v91, s[56:57], v86, v86, v46
	v_rcp_f32_e32 v94, v91
	v_fma_f32 v64, -v83, v84, v64
	v_div_fmas_f32 v64, v64, v90, v84
	v_div_fixup_f32 v83, v64, v85, v45
	v_fma_f32 v64, -v91, v94, 1.0
	v_fmac_f32_e32 v94, v64, v94
	v_div_scale_f32 v64, vcc, v46, v86, v46
	v_mul_f32_e32 v84, v64, v94
	v_fma_f32 v85, -v91, v84, v64
	v_fmac_f32_e32 v84, v85, v94
	v_div_scale_f32 v85, s[56:57], v87, v87, v47
	v_rcp_f32_e32 v95, v85
	v_fma_f32 v64, -v91, v84, v64
	v_div_fmas_f32 v64, v64, v94, v84
	v_div_fixup_f32 v98, v64, v86, v46
	v_fma_f32 v64, -v85, v95, 1.0
	v_fmac_f32_e32 v95, v64, v95
	v_div_scale_f32 v64, vcc, v47, v87, v47
	v_mul_f32_e32 v86, v64, v95
	v_fma_f32 v84, -v85, v86, v64
	v_fmac_f32_e32 v86, v84, v95
	v_fma_f32 v64, -v85, v86, v64
	v_mul_f32_e32 v84, 0xbfb8aa3b, v48
	v_mul_f32_e32 v85, 0xbfb8aa3b, v49
	v_exp_f32_e32 v84, v84
	v_exp_f32_e32 v85, v85
	v_mul_f32_e32 v90, 0xbfb8aa3b, v50
	v_mul_f32_e32 v91, 0xbfb8aa3b, v51
	v_exp_f32_e32 v90, v90
	v_pk_add_f32 v[84:85], v[84:85], 1.0 op_sel_hi:[1,0]
	v_exp_f32_e32 v91, v91
	v_div_scale_f32 v94, s[56:57], v84, v84, v48
	v_rcp_f32_e32 v100, v94
	v_div_fmas_f32 v64, v64, v95, v86
	v_div_fixup_f32 v99, v64, v87, v47
	v_pk_add_f32 v[86:87], v[90:91], 1.0 op_sel_hi:[1,0]
	v_fma_f32 v64, -v94, v100, 1.0
	v_fmac_f32_e32 v100, v64, v100
	v_div_scale_f32 v64, vcc, v48, v84, v48
	v_mul_f32_e32 v90, v64, v100
	v_fma_f32 v91, -v94, v90, v64
	v_fmac_f32_e32 v90, v91, v100
	v_div_scale_f32 v91, s[56:57], v85, v85, v49
	v_fma_f32 v64, -v94, v90, v64
	v_rcp_f32_e32 v94, v91
	v_div_fmas_f32 v64, v64, v100, v90
	v_div_fixup_f32 v84, v64, v84, v48
	v_fma_f32 v64, -v91, v94, 1.0
	v_fmac_f32_e32 v94, v64, v94
	v_div_scale_f32 v64, vcc, v49, v85, v49
	v_mul_f32_e32 v90, v64, v94
	v_fma_f32 v95, -v91, v90, v64
	v_fmac_f32_e32 v90, v95, v94
	v_fma_f32 v64, -v91, v90, v64
	v_div_scale_f32 v91, s[56:57], v86, v86, v50
	v_rcp_f32_e32 v95, v91
	v_div_fmas_f32 v64, v64, v94, v90
	v_div_fixup_f32 v85, v64, v85, v49
	v_fma_f32 v64, -v91, v95, 1.0
	v_fmac_f32_e32 v95, v64, v95
	v_div_scale_f32 v64, vcc, v50, v86, v50
	v_mul_f32_e32 v90, v64, v95
	v_fma_f32 v94, -v91, v90, v64
	v_fmac_f32_e32 v90, v94, v95
	v_fma_f32 v64, -v91, v90, v64
	v_div_scale_f32 v91, s[56:57], v87, v87, v51
	v_rcp_f32_e32 v101, v91
	v_div_fmas_f32 v64, v64, v95, v90
	v_div_fixup_f32 v100, v64, v86, v50
	v_mul_f32_e32 v94, 0xbfb8aa3b, v54
	v_fma_f32 v64, -v91, v101, 1.0
	v_fmac_f32_e32 v101, v64, v101
	v_div_scale_f32 v64, vcc, v51, v87, v51
	v_mul_f32_e32 v86, v64, v101
	v_fma_f32 v90, -v91, v86, v64
	v_fmac_f32_e32 v86, v90, v101
	v_fma_f32 v64, -v91, v86, v64
	v_mul_f32_e32 v90, 0xbfb8aa3b, v52
	v_mul_f32_e32 v91, 0xbfb8aa3b, v53
	v_exp_f32_e32 v90, v90
	v_exp_f32_e32 v91, v91
	v_div_fmas_f32 v64, v64, v101, v86
	v_div_fixup_f32 v101, v64, v87, v51
	v_mul_f32_e32 v95, 0xbfb8aa3b, v55
	v_pk_add_f32 v[90:91], v[90:91], 1.0 op_sel_hi:[1,0]
	v_exp_f32_e32 v94, v94
	v_div_scale_f32 v102, s[56:57], v90, v90, v52
	v_rcp_f32_e32 v103, v102
	v_exp_f32_e32 v95, v95
	v_fma_f32 v64, -v102, v103, 1.0
	v_fmac_f32_e32 v103, v64, v103
	v_div_scale_f32 v64, vcc, v52, v90, v52
	v_mul_f32_e32 v86, v64, v103
	v_fma_f32 v87, -v102, v86, v64
	v_fmac_f32_e32 v86, v87, v103
	v_div_scale_f32 v87, s[56:57], v91, v91, v53
	v_fma_f32 v64, -v102, v86, v64
	v_rcp_f32_e32 v102, v87
	v_div_fmas_f32 v64, v64, v103, v86
	v_div_fixup_f32 v86, v64, v90, v52
	v_pk_add_f32 v[94:95], v[94:95], 1.0 op_sel_hi:[1,0]
	v_fma_f32 v64, -v87, v102, 1.0
	v_fmac_f32_e32 v102, v64, v102
	v_div_scale_f32 v64, vcc, v53, v91, v53
	v_mul_f32_e32 v90, v64, v102
	v_fma_f32 v103, -v87, v90, v64
	v_fmac_f32_e32 v90, v103, v102
	v_div_scale_f32 v103, s[56:57], v94, v94, v54
	v_rcp_f32_e32 v104, v103
	v_fma_f32 v64, -v87, v90, v64
	v_div_fmas_f32 v64, v64, v102, v90
	v_div_fixup_f32 v87, v64, v91, v53
	v_fma_f32 v64, -v103, v104, 1.0
	v_fmac_f32_e32 v104, v64, v104
	v_div_scale_f32 v64, vcc, v54, v94, v54
	v_mul_f32_e32 v90, v64, v104
	v_fma_f32 v91, -v103, v90, v64
	v_fmac_f32_e32 v90, v91, v104
	v_div_scale_f32 v91, s[56:57], v95, v95, v55
	v_fma_f32 v64, -v103, v90, v64
	v_rcp_f32_e32 v103, v91
	v_div_fmas_f32 v64, v64, v104, v90
	v_div_fixup_f32 v102, v64, v94, v54
	v_mul_f32_e32 v104, 0xbfb8aa3b, v58
	v_fma_f32 v64, -v91, v103, 1.0
	v_fmac_f32_e32 v103, v64, v103
	v_div_scale_f32 v64, vcc, v55, v95, v55
	v_mul_f32_e32 v94, v64, v103
	v_fma_f32 v90, -v91, v94, v64
	v_fmac_f32_e32 v94, v90, v103
	v_fma_f32 v64, -v91, v94, v64
	v_mul_f32_e32 v90, 0xbfb8aa3b, v56
	v_mul_f32_e32 v91, 0xbfb8aa3b, v57
	v_exp_f32_e32 v90, v90
	v_exp_f32_e32 v91, v91
	v_exp_f32_e32 v104, v104
	v_div_fmas_f32 v64, v64, v103, v94
	v_div_fixup_f32 v103, v64, v95, v55
	v_pk_add_f32 v[90:91], v[90:91], 1.0 op_sel_hi:[1,0]
	v_pk_add_f32 v[94:95], v[104:105], 1.0 op_sel_hi:[1,0]
	v_div_scale_f32 v106, s[56:57], v90, v90, v56
	v_rcp_f32_e32 v107, v106
	s_nop 0
	v_fma_f32 v64, -v106, v107, 1.0
	v_fmac_f32_e32 v107, v64, v107
	v_div_scale_f32 v64, vcc, v56, v90, v56
	v_mul_f32_e32 v104, v64, v107
	v_fma_f32 v105, -v106, v104, v64
	v_fmac_f32_e32 v104, v105, v107
	v_div_scale_f32 v105, s[56:57], v91, v91, v57
	v_fma_f32 v64, -v106, v104, v64
	v_rcp_f32_e32 v106, v105
	v_div_fmas_f32 v64, v64, v107, v104
	v_div_fixup_f32 v90, v64, v90, v56
	v_fma_f32 v64, -v105, v106, 1.0
	v_fmac_f32_e32 v106, v64, v106
	v_div_scale_f32 v64, vcc, v57, v91, v57
	v_mul_f32_e32 v104, v64, v106
	v_fma_f32 v107, -v105, v104, v64
	v_fmac_f32_e32 v104, v107, v106
	v_fma_f32 v64, -v105, v104, v64
	v_div_scale_f32 v105, s[56:57], v94, v94, v58
	v_rcp_f32_e32 v107, v105
	v_div_fmas_f32 v64, v64, v106, v104
	v_div_fixup_f32 v91, v64, v91, v57
	v_fma_f32 v64, -v105, v107, 1.0
	v_fmac_f32_e32 v107, v64, v107
	v_div_scale_f32 v64, vcc, v58, v94, v58
	v_mul_f32_e32 v104, v64, v107
	v_fma_f32 v106, -v105, v104, v64
	v_fmac_f32_e32 v104, v106, v107
	v_fma_f32 v64, -v105, v104, v64
	v_div_scale_f32 v105, s[56:57], v95, v95, v59
	v_rcp_f32_e32 v110, v105
	v_div_fmas_f32 v64, v64, v107, v104
	v_div_fixup_f32 v104, v64, v94, v58
	v_fma_f32 v64, -v105, v110, 1.0
	v_fmac_f32_e32 v110, v64, v110
	v_div_scale_f32 v64, vcc, v59, v95, v59
	v_mul_f32_e32 v94, v64, v110
	v_fma_f32 v106, -v105, v94, v64
	v_fmac_f32_e32 v94, v106, v110
	v_fma_f32 v64, -v105, v94, v64
	v_mul_f32_e32 v105, 0xbfb8aa3b, v60
	v_exp_f32_e32 v106, v105
	v_mul_f32_e32 v105, 0xbfb8aa3b, v61
	v_exp_f32_e32 v107, v105
	v_mul_f32_e32 v105, 0xbfb8aa3b, v62
	v_exp_f32_e32 v108, v105
	v_mul_f32_e32 v105, 0xbfb8aa3b, v63
	v_pk_add_f32 v[106:107], v[106:107], 1.0 op_sel_hi:[1,0]
	v_div_fmas_f32 v64, v64, v110, v94
	v_div_scale_f32 v111, s[56:57], v106, v106, v60
	v_rcp_f32_e32 v112, v111
	v_exp_f32_e32 v109, v105
	v_div_fixup_f32 v105, v64, v95, v59
	v_fma_f32 v64, -v111, v112, 1.0
	v_fmac_f32_e32 v112, v64, v112
	v_div_scale_f32 v64, vcc, v60, v106, v60
	v_mul_f32_e32 v94, v64, v112
	v_fma_f32 v95, -v111, v94, v64
	v_fmac_f32_e32 v94, v95, v112
	v_div_scale_f32 v95, s[56:57], v107, v107, v61
	v_rcp_f32_e32 v110, v95
	v_fma_f32 v64, -v111, v94, v64
	v_div_fmas_f32 v64, v64, v112, v94
	v_div_fixup_f32 v94, v64, v106, v60
	v_fma_f32 v64, -v95, v110, 1.0
	v_fmac_f32_e32 v110, v64, v110
	v_div_scale_f32 v64, vcc, v61, v107, v61
	v_mul_f32_e32 v106, v64, v110
	v_pk_add_f32 v[108:109], v[108:109], 1.0 op_sel_hi:[1,0]
	v_fma_f32 v111, -v95, v106, v64
	v_fmac_f32_e32 v106, v111, v110
	v_div_scale_f32 v111, s[56:57], v108, v108, v62
	v_rcp_f32_e32 v112, v111
	v_fma_f32 v64, -v95, v106, v64
	v_div_fmas_f32 v64, v64, v110, v106
	v_div_fixup_f32 v95, v64, v107, v61
	v_fma_f32 v64, -v111, v112, 1.0
	v_fmac_f32_e32 v112, v64, v112
	v_div_scale_f32 v64, vcc, v62, v108, v62
	v_mul_f32_e32 v106, v64, v112
	v_fma_f32 v107, -v111, v106, v64
	v_fmac_f32_e32 v106, v107, v112
	v_div_scale_f32 v107, s[56:57], v109, v109, v63
	v_rcp_f32_e32 v114, v107
	v_fma_f32 v64, -v111, v106, v64
	v_div_fmas_f32 v64, v64, v112, v106
	v_div_fixup_f32 v106, v64, v108, v62
	v_fma_f32 v64, -v107, v114, 1.0
	v_fmac_f32_e32 v114, v64, v114
	v_div_scale_f32 v64, vcc, v63, v109, v63
	v_mul_f32_e32 v108, v64, v114
	v_fma_f32 v110, -v107, v108, v64
	v_fmac_f32_e32 v108, v110, v114
	v_fma_f32 v64, -v107, v108, v64
	v_mul_f32_e32 v107, 0xbfb8aa3b, v4
	v_exp_f32_e32 v110, v107
	v_mul_f32_e32 v107, 0xbfb8aa3b, v5
	v_exp_f32_e32 v111, v107
	v_mul_f32_e32 v107, 0xbfb8aa3b, v6
	v_exp_f32_e32 v112, v107
	v_mul_f32_e32 v107, 0xbfb8aa3b, v7
	v_pk_add_f32 v[110:111], v[110:111], 1.0 op_sel_hi:[1,0]
	v_div_fmas_f32 v64, v64, v114, v108
	v_div_scale_f32 v115, s[56:57], v110, v110, v4
	v_rcp_f32_e32 v116, v115
	v_exp_f32_e32 v113, v107
	v_div_fixup_f32 v107, v64, v109, v63
	v_fma_f32 v64, -v115, v116, 1.0
	v_fmac_f32_e32 v116, v64, v116
	v_div_scale_f32 v64, vcc, v4, v110, v4
	v_mul_f32_e32 v108, v64, v116
	v_fma_f32 v109, -v115, v108, v64
	v_fmac_f32_e32 v108, v109, v116
	v_div_scale_f32 v109, s[56:57], v111, v111, v5
	v_rcp_f32_e32 v114, v109
	v_fma_f32 v64, -v115, v108, v64
	v_div_fmas_f32 v64, v64, v116, v108
	v_div_fixup_f32 v108, v64, v110, v4
	v_fma_f32 v64, -v109, v114, 1.0
	v_fmac_f32_e32 v114, v64, v114
	v_div_scale_f32 v64, vcc, v5, v111, v5
	v_mul_f32_e32 v110, v64, v114
	v_pk_add_f32 v[112:113], v[112:113], 1.0 op_sel_hi:[1,0]
	v_fma_f32 v115, -v109, v110, v64
	v_fmac_f32_e32 v110, v115, v114
	v_div_scale_f32 v115, s[56:57], v112, v112, v6
	v_rcp_f32_e32 v116, v115
	v_fma_f32 v64, -v109, v110, v64
	v_div_fmas_f32 v64, v64, v114, v110
	v_div_fixup_f32 v109, v64, v111, v5
	v_fma_f32 v64, -v115, v116, 1.0
	v_fmac_f32_e32 v116, v64, v116
	v_div_scale_f32 v64, vcc, v6, v112, v6
	v_mul_f32_e32 v110, v64, v116
	v_fma_f32 v111, -v115, v110, v64
	v_fmac_f32_e32 v110, v111, v116
	v_div_scale_f32 v111, s[56:57], v113, v113, v7
	v_rcp_f32_e32 v117, v111
	v_fma_f32 v64, -v115, v110, v64
	v_div_fmas_f32 v64, v64, v116, v110
	v_div_fixup_f32 v120, v64, v112, v6
	v_fma_f32 v64, -v111, v117, 1.0
	v_fmac_f32_e32 v117, v64, v117
	v_div_scale_f32 v64, vcc, v7, v113, v7
	v_mul_f32_e32 v112, v64, v117
	v_fma_f32 v110, -v111, v112, v64
	v_fmac_f32_e32 v112, v110, v117
	v_fma_f32 v64, -v111, v112, v64
	v_mul_f32_e32 v110, 0xbfb8aa3b, v12
	v_mul_f32_e32 v111, 0xbfb8aa3b, v13
	v_exp_f32_e32 v110, v110
	v_exp_f32_e32 v111, v111
	v_mul_f32_e32 v114, 0xbfb8aa3b, v14
	v_mul_f32_e32 v115, 0xbfb8aa3b, v15
	v_exp_f32_e32 v114, v114
	v_pk_add_f32 v[110:111], v[110:111], 1.0 op_sel_hi:[1,0]
	v_exp_f32_e32 v115, v115
	v_div_scale_f32 v116, s[56:57], v110, v110, v12
	v_rcp_f32_e32 v118, v116
	v_div_fmas_f32 v64, v64, v117, v112
	v_div_fixup_f32 v121, v64, v113, v7
	v_pk_add_f32 v[112:113], v[114:115], 1.0 op_sel_hi:[1,0]
	v_fma_f32 v64, -v116, v118, 1.0
	v_fmac_f32_e32 v118, v64, v118
	v_div_scale_f32 v64, vcc, v12, v110, v12
	v_mul_f32_e32 v114, v64, v118
	v_fma_f32 v115, -v116, v114, v64
	v_fmac_f32_e32 v114, v115, v118
	v_div_scale_f32 v115, s[56:57], v111, v111, v13
	v_fma_f32 v64, -v116, v114, v64
	v_rcp_f32_e32 v116, v115
	v_div_fmas_f32 v64, v64, v118, v114
	v_div_fixup_f32 v110, v64, v110, v12
	v_fma_f32 v64, -v115, v116, 1.0
	v_fmac_f32_e32 v116, v64, v116
	v_div_scale_f32 v64, vcc, v13, v111, v13
	v_mul_f32_e32 v114, v64, v116
	v_fma_f32 v117, -v115, v114, v64
	v_fmac_f32_e32 v114, v117, v116
	v_fma_f32 v64, -v115, v114, v64
	v_div_scale_f32 v115, s[56:57], v112, v112, v14
	v_rcp_f32_e32 v117, v115
	v_div_fmas_f32 v64, v64, v116, v114
	v_div_fixup_f32 v111, v64, v111, v13
	v_fma_f32 v64, -v115, v117, 1.0
	v_fmac_f32_e32 v117, v64, v117
	v_div_scale_f32 v64, vcc, v14, v112, v14
	v_mul_f32_e32 v114, v64, v117
	v_fma_f32 v116, -v115, v114, v64
	v_fmac_f32_e32 v114, v116, v117
	v_fma_f32 v64, -v115, v114, v64
	v_div_scale_f32 v115, s[56:57], v113, v113, v15
	v_rcp_f32_e32 v118, v115
	v_div_fmas_f32 v64, v64, v117, v114
	v_div_fixup_f32 v124, v64, v112, v14
	v_mul_f32_e32 v116, 0xbfb8aa3b, v18
	v_fma_f32 v64, -v115, v118, 1.0
	v_fmac_f32_e32 v118, v64, v118
	v_div_scale_f32 v64, vcc, v15, v113, v15
	v_mul_f32_e32 v112, v64, v118
	v_fma_f32 v114, -v115, v112, v64
	v_fmac_f32_e32 v112, v114, v118
	v_fma_f32 v64, -v115, v112, v64
	v_mul_f32_e32 v114, 0xbfb8aa3b, v16
	v_mul_f32_e32 v115, 0xbfb8aa3b, v17
	v_exp_f32_e32 v114, v114
	v_exp_f32_e32 v115, v115
	v_div_fmas_f32 v64, v64, v118, v112
	v_div_fixup_f32 v125, v64, v113, v15
	v_mul_f32_e32 v117, 0xbfb8aa3b, v19
	v_pk_add_f32 v[114:115], v[114:115], 1.0 op_sel_hi:[1,0]
	v_exp_f32_e32 v116, v116
	v_div_scale_f32 v119, s[56:57], v114, v114, v16
	v_rcp_f32_e32 v122, v119
	v_exp_f32_e32 v117, v117
	v_fma_f32 v64, -v119, v122, 1.0
	v_fmac_f32_e32 v122, v64, v122
	v_div_scale_f32 v64, vcc, v16, v114, v16
	v_mul_f32_e32 v112, v64, v122
	v_fma_f32 v113, -v119, v112, v64
	v_fmac_f32_e32 v112, v113, v122
	v_div_scale_f32 v113, s[56:57], v115, v115, v17
	v_rcp_f32_e32 v118, v113
	v_fma_f32 v64, -v119, v112, v64
	v_div_fmas_f32 v64, v64, v122, v112
	v_div_fixup_f32 v112, v64, v114, v16
	v_fma_f32 v64, -v113, v118, 1.0
	v_fmac_f32_e32 v118, v64, v118
	v_div_scale_f32 v64, vcc, v17, v115, v17
	v_mul_f32_e32 v114, v64, v118
	v_pk_add_f32 v[116:117], v[116:117], 1.0 op_sel_hi:[1,0]
	v_fma_f32 v119, -v113, v114, v64
	v_fmac_f32_e32 v114, v119, v118
	v_div_scale_f32 v119, s[56:57], v116, v116, v18
	v_rcp_f32_e32 v122, v119
	v_fma_f32 v64, -v113, v114, v64
	v_div_fmas_f32 v64, v64, v118, v114
	v_div_fixup_f32 v113, v64, v115, v17
	v_fma_f32 v64, -v119, v122, 1.0
	v_fmac_f32_e32 v122, v64, v122
	v_div_scale_f32 v64, vcc, v18, v116, v18
	v_mul_f32_e32 v114, v64, v122
	v_fma_f32 v115, -v119, v114, v64
	v_fmac_f32_e32 v114, v115, v122
	v_div_scale_f32 v115, s[56:57], v117, v117, v19
	v_rcp_f32_e32 v123, v115
	v_fma_f32 v64, -v119, v114, v64
	v_div_fmas_f32 v64, v64, v122, v114
	v_div_fixup_f32 v140, v64, v116, v18
	v_fma_f32 v64, -v115, v123, 1.0
	v_fmac_f32_e32 v123, v64, v123
	v_div_scale_f32 v64, vcc, v19, v117, v19
	v_mul_f32_e32 v116, v64, v123
	v_fma_f32 v114, -v115, v116, v64
	v_fmac_f32_e32 v116, v114, v123
	v_fma_f32 v64, -v115, v116, v64
	v_mul_f32_e32 v114, 0xbfb8aa3b, v20
	v_mul_f32_e32 v115, 0xbfb8aa3b, v21
	v_exp_f32_e32 v114, v114
	v_exp_f32_e32 v115, v115
	v_mul_f32_e32 v118, 0xbfb8aa3b, v22
	v_mul_f32_e32 v119, 0xbfb8aa3b, v23
	v_exp_f32_e32 v118, v118
	v_pk_add_f32 v[114:115], v[114:115], 1.0 op_sel_hi:[1,0]
	v_exp_f32_e32 v119, v119
	v_div_scale_f32 v122, s[56:57], v114, v114, v20
	v_rcp_f32_e32 v126, v122
	v_div_fmas_f32 v64, v64, v123, v116
	v_div_fixup_f32 v141, v64, v117, v19
	v_pk_add_f32 v[116:117], v[118:119], 1.0 op_sel_hi:[1,0]
	v_fma_f32 v64, -v122, v126, 1.0
	v_fmac_f32_e32 v126, v64, v126
	v_div_scale_f32 v64, vcc, v20, v114, v20
	v_mul_f32_e32 v118, v64, v126
	v_fma_f32 v119, -v122, v118, v64
	v_fmac_f32_e32 v118, v119, v126
	v_div_scale_f32 v119, s[56:57], v115, v115, v21
	v_fma_f32 v64, -v122, v118, v64
	v_rcp_f32_e32 v122, v119
	v_div_fmas_f32 v64, v64, v126, v118
	v_div_fixup_f32 v114, v64, v114, v20
	v_fma_f32 v64, -v119, v122, 1.0
	v_fmac_f32_e32 v122, v64, v122
	v_div_scale_f32 v64, vcc, v21, v115, v21
	v_mul_f32_e32 v118, v64, v122
	v_fma_f32 v123, -v119, v118, v64
	v_fmac_f32_e32 v118, v123, v122
	v_fma_f32 v64, -v119, v118, v64
	v_div_scale_f32 v119, s[56:57], v116, v116, v22
	v_rcp_f32_e32 v123, v119
	v_div_fmas_f32 v64, v64, v122, v118
	v_div_fixup_f32 v115, v64, v115, v21
	v_fma_f32 v64, -v119, v123, 1.0
	v_fmac_f32_e32 v123, v64, v123
	v_div_scale_f32 v64, vcc, v22, v116, v22
	v_mul_f32_e32 v118, v64, v123
	v_fma_f32 v122, -v119, v118, v64
	v_fmac_f32_e32 v118, v122, v123
	v_fma_f32 v64, -v119, v118, v64
	v_div_scale_f32 v119, s[56:57], v117, v117, v23
	v_rcp_f32_e32 v126, v119
	v_div_fmas_f32 v64, v64, v123, v118
	v_div_fixup_f32 v142, v64, v116, v22
	v_mul_f32_e32 v122, 0xbfb8aa3b, v2
	v_fma_f32 v64, -v119, v126, 1.0
	v_fmac_f32_e32 v126, v64, v126
	v_div_scale_f32 v64, vcc, v23, v117, v23
	v_mul_f32_e32 v116, v64, v126
	v_fma_f32 v118, -v119, v116, v64
	v_fmac_f32_e32 v116, v118, v126
	v_fma_f32 v64, -v119, v116, v64
	v_mul_f32_e32 v118, 0xbfb8aa3b, v0
	v_mul_f32_e32 v119, 0xbfb8aa3b, v1
	v_exp_f32_e32 v118, v118
	v_exp_f32_e32 v119, v119
	v_div_fmas_f32 v64, v64, v126, v116
	v_div_fixup_f32 v143, v64, v117, v23
	v_mul_f32_e32 v123, 0xbfb8aa3b, v3
	v_pk_add_f32 v[118:119], v[118:119], 1.0 op_sel_hi:[1,0]
	v_exp_f32_e32 v122, v122
	v_div_scale_f32 v127, s[56:57], v118, v118, v0
	v_rcp_f32_e32 v144, v127
	v_exp_f32_e32 v123, v123
	v_fma_f32 v64, -v127, v144, 1.0
	v_fmac_f32_e32 v144, v64, v144
	v_div_scale_f32 v64, vcc, v0, v118, v0
	v_mul_f32_e32 v116, v64, v144
	v_fma_f32 v117, -v127, v116, v64
	v_fmac_f32_e32 v116, v117, v144
	v_div_scale_f32 v117, s[56:57], v119, v119, v1
	v_rcp_f32_e32 v126, v117
	v_fma_f32 v64, -v127, v116, v64
	v_div_fmas_f32 v64, v64, v144, v116
	v_div_fixup_f32 v116, v64, v118, v0
	v_fma_f32 v64, -v117, v126, 1.0
	v_fmac_f32_e32 v126, v64, v126
	v_div_scale_f32 v64, vcc, v1, v119, v1
	v_mul_f32_e32 v118, v64, v126
	v_pk_add_f32 v[122:123], v[122:123], 1.0 op_sel_hi:[1,0]
	v_fma_f32 v127, -v117, v118, v64
	v_fmac_f32_e32 v118, v127, v126
	v_div_scale_f32 v127, s[56:57], v122, v122, v2
	v_rcp_f32_e32 v144, v127
	v_fma_f32 v64, -v117, v118, v64
	v_div_fmas_f32 v64, v64, v126, v118
	v_div_fixup_f32 v117, v64, v119, v1
	v_fma_f32 v64, -v127, v144, 1.0
	v_fmac_f32_e32 v144, v64, v144
	v_div_scale_f32 v64, vcc, v2, v122, v2
	v_mul_f32_e32 v118, v64, v144
	v_fma_f32 v119, -v127, v118, v64
	v_fmac_f32_e32 v118, v119, v144
	v_div_scale_f32 v119, s[56:57], v123, v123, v3
	v_rcp_f32_e32 v145, v119
	v_fma_f32 v64, -v127, v118, v64
	v_div_fmas_f32 v64, v64, v144, v118
	v_div_fixup_f32 v144, v64, v122, v2
	v_fma_f32 v64, -v119, v145, 1.0
	v_fmac_f32_e32 v145, v64, v145
	v_div_scale_f32 v64, vcc, v3, v123, v3
	v_mul_f32_e32 v122, v64, v145
	v_fma_f32 v118, -v119, v122, v64
	v_fmac_f32_e32 v122, v118, v145
	v_fma_f32 v64, -v119, v122, v64
	v_mul_f32_e32 v118, 0xbfb8aa3b, v8
	v_mul_f32_e32 v119, 0xbfb8aa3b, v9
	v_exp_f32_e32 v118, v118
	v_exp_f32_e32 v119, v119
	v_mul_f32_e32 v126, 0xbfb8aa3b, v10
	v_mul_f32_e32 v127, 0xbfb8aa3b, v11
	v_exp_f32_e32 v126, v126
	v_pk_add_f32 v[118:119], v[118:119], 1.0 op_sel_hi:[1,0]
	v_exp_f32_e32 v127, v127
	v_div_scale_f32 v146, s[56:57], v118, v118, v8
	v_rcp_f32_e32 v147, v146
	v_div_fmas_f32 v64, v64, v145, v122
	v_div_fixup_f32 v145, v64, v123, v3
	v_pk_add_f32 v[122:123], v[126:127], 1.0 op_sel_hi:[1,0]
	v_fma_f32 v64, -v146, v147, 1.0
	v_fmac_f32_e32 v147, v64, v147
	v_div_scale_f32 v64, vcc, v8, v118, v8
	v_mul_f32_e32 v126, v64, v147
	v_fma_f32 v127, -v146, v126, v64
	v_fmac_f32_e32 v126, v127, v147
	v_div_scale_f32 v127, s[56:57], v119, v119, v9
	v_fma_f32 v64, -v146, v126, v64
	v_rcp_f32_e32 v146, v127
	v_div_fmas_f32 v64, v64, v147, v126
	v_div_fixup_f32 v118, v64, v118, v8
	v_fma_f32 v64, -v127, v146, 1.0
	v_fmac_f32_e32 v146, v64, v146
	v_div_scale_f32 v64, vcc, v9, v119, v9
	v_mul_f32_e32 v126, v64, v146
	v_fma_f32 v147, -v127, v126, v64
	v_fmac_f32_e32 v126, v147, v146
	v_fma_f32 v64, -v127, v126, v64
	v_div_scale_f32 v127, s[56:57], v122, v122, v10
	v_rcp_f32_e32 v147, v127
	v_div_fmas_f32 v64, v64, v146, v126
	v_div_fixup_f32 v119, v64, v119, v9
	v_fma_f32 v64, -v127, v147, 1.0
	v_fmac_f32_e32 v147, v64, v147
	v_div_scale_f32 v64, vcc, v10, v122, v10
	v_mul_f32_e32 v126, v64, v147
	v_fma_f32 v146, -v127, v126, v64
	v_fmac_f32_e32 v126, v146, v147
	v_fma_f32 v64, -v127, v126, v64
	v_div_scale_f32 v127, s[56:57], v123, v123, v11
	v_rcp_f32_e32 v150, v127
	v_div_fmas_f32 v64, v64, v147, v126
	v_div_fixup_f32 v146, v64, v122, v10
	v_mul_f32_e32 v147, 0xbfb8aa3b, v26
	v_fma_f32 v64, -v127, v150, 1.0
	v_fmac_f32_e32 v150, v64, v150
	v_div_scale_f32 v64, vcc, v11, v123, v11
	v_mul_f32_e32 v122, v64, v150
	v_fma_f32 v126, -v127, v122, v64
	v_fmac_f32_e32 v122, v126, v150
	v_fma_f32 v64, -v127, v122, v64
	v_mul_f32_e32 v126, 0xbfb8aa3b, v24
	v_mul_f32_e32 v127, 0xbfb8aa3b, v25
	v_exp_f32_e32 v126, v126
	v_exp_f32_e32 v127, v127
	v_exp_f32_e32 v148, v147
	v_mul_f32_e32 v147, 0xbfb8aa3b, v27
	v_div_fmas_f32 v64, v64, v150, v122
	v_pk_add_f32 v[126:127], v[126:127], 1.0 op_sel_hi:[1,0]
	v_exp_f32_e32 v149, v147
	v_div_scale_f32 v151, s[56:57], v126, v126, v24
	v_rcp_f32_e32 v203, v151
	v_div_fixup_f32 v147, v64, v123, v11
	v_pk_add_f32 v[148:149], v[148:149], 1.0 op_sel_hi:[1,0]
	v_fma_f32 v64, -v151, v203, 1.0
	v_fmac_f32_e32 v203, v64, v203
	v_div_scale_f32 v64, vcc, v24, v126, v24
	v_mul_f32_e32 v122, v64, v203
	v_fma_f32 v123, -v151, v122, v64
	v_fmac_f32_e32 v122, v123, v203
	v_div_scale_f32 v123, s[56:57], v127, v127, v25
	v_rcp_f32_e32 v150, v123
	v_fma_f32 v64, -v151, v122, v64
	v_div_fmas_f32 v64, v64, v203, v122
	v_div_fixup_f32 v122, v64, v126, v24
	v_fma_f32 v64, -v123, v150, 1.0
	v_fmac_f32_e32 v150, v64, v150
	v_div_scale_f32 v64, vcc, v25, v127, v25
	v_mul_f32_e32 v126, v64, v150
	v_fma_f32 v151, -v123, v126, v64
	v_fmac_f32_e32 v126, v151, v150
	v_div_scale_f32 v151, s[56:57], v148, v148, v26
	v_rcp_f32_e32 v203, v151
	v_fma_f32 v64, -v123, v126, v64
	v_div_fmas_f32 v64, v64, v150, v126
	v_div_fixup_f32 v123, v64, v127, v25
	v_fma_f32 v64, -v151, v203, 1.0
	v_fmac_f32_e32 v203, v64, v203
	v_div_scale_f32 v64, vcc, v26, v148, v26
	v_mul_f32_e32 v126, v64, v203
	v_fma_f32 v127, -v151, v126, v64
	v_fmac_f32_e32 v126, v127, v203
	v_div_scale_f32 v127, s[56:57], v149, v149, v27
	v_rcp_f32_e32 v204, v127
	v_fma_f32 v64, -v151, v126, v64
	v_div_fmas_f32 v64, v64, v203, v126
	v_div_fixup_f32 v148, v64, v148, v26
	v_fma_f32 v64, -v127, v204, 1.0
	v_fmac_f32_e32 v204, v64, v204
	v_div_scale_f32 v64, vcc, v27, v149, v27
	v_mul_f32_e32 v203, v64, v204
	v_fma_f32 v126, -v127, v203, v64
	v_fmac_f32_e32 v203, v126, v204
	v_fma_f32 v64, -v127, v203, v64
	v_mul_f32_e32 v126, 0xbfb8aa3b, v28
	v_mul_f32_e32 v127, 0xbfb8aa3b, v29
	v_exp_f32_e32 v126, v126
	v_exp_f32_e32 v127, v127
	v_div_fmas_f32 v64, v64, v204, v203
	v_div_fixup_f32 v149, v64, v149, v27
	v_mul_f32_e32 v150, 0xbfb8aa3b, v30
	v_pk_add_f32 v[126:127], v[126:127], 1.0 op_sel_hi:[1,0]
	v_mul_f32_e32 v151, 0xbfb8aa3b, v31
	v_div_scale_f32 v205, s[56:57], v126, v126, v28
	v_rcp_f32_e32 v206, v205
	v_exp_f32_e32 v150, v150
	v_exp_f32_e32 v151, v151
	v_fma_f32 v64, -v205, v206, 1.0
	v_fmac_f32_e32 v206, v64, v206
	v_div_scale_f32 v64, vcc, v28, v126, v28
	v_mul_f32_e32 v203, v64, v206
	v_fma_f32 v204, -v205, v203, v64
	v_fmac_f32_e32 v203, v204, v206
	v_div_scale_f32 v204, s[56:57], v127, v127, v29
	v_fma_f32 v64, -v205, v203, v64
	v_rcp_f32_e32 v205, v204
	v_div_fmas_f32 v64, v64, v206, v203
	v_div_fixup_f32 v126, v64, v126, v28
	v_pk_add_f32 v[150:151], v[150:151], 1.0 op_sel_hi:[1,0]
	v_fma_f32 v64, -v204, v205, 1.0
	v_fmac_f32_e32 v205, v64, v205
	v_div_scale_f32 v64, vcc, v29, v127, v29
	v_mul_f32_e32 v203, v64, v205
	v_fma_f32 v206, -v204, v203, v64
	v_fmac_f32_e32 v203, v206, v205
	v_fma_f32 v64, -v204, v203, v64
	v_div_scale_f32 v204, s[56:57], v150, v150, v30
	v_rcp_f32_e32 v206, v204
	v_div_fmas_f32 v64, v64, v205, v203
	v_div_fixup_f32 v127, v64, v127, v29
	v_fma_f32 v64, -v204, v206, 1.0
	v_fmac_f32_e32 v206, v64, v206
	v_div_scale_f32 v64, vcc, v30, v150, v30
	v_mul_f32_e32 v203, v64, v206
	v_fma_f32 v205, -v204, v203, v64
	v_fmac_f32_e32 v203, v205, v206
	v_fma_f32 v64, -v204, v203, v64
	v_div_scale_f32 v204, s[56:57], v151, v151, v31
	v_rcp_f32_e32 v205, v204
	v_div_fmas_f32 v64, v64, v206, v203
	v_div_fixup_f32 v150, v64, v150, v30
	s_lshl_b64 s[56:57], s[0:1], 19
	v_fma_f32 v64, -v204, v205, 1.0
	v_fmac_f32_e32 v205, v64, v205
	v_div_scale_f32 v64, vcc, v31, v151, v31
	s_add_u32 s56, s36, s56
	v_mul_f32_e32 v203, v64, v205
	s_addc_u32 s57, s37, s57
	s_lshl_b32 s38, s4, 7
	v_fma_f32 v206, -v204, v203, v64
	s_lshl_b64 s[4:5], s[38:39], 1
	v_fmac_f32_e32 v203, v206, v205
	s_add_u32 s4, s56, s4
	v_fma_f32 v64, -v204, v203, v64
	s_addc_u32 s5, s57, s5
	v_div_fmas_f32 v64, v64, v205, v203
	s_add_u32 s56, s4, 0xffffe000
	v_div_fixup_f32 v151, v64, v151, v31
	s_addc_u32 s57, s5, -1
